# GEMM K-loops: mid-segment s_setprio 0/1 flip pair deleted (A/B of the template's per-group flips)
# speedup vs baseline: 1.0093x; 1.0093x over previous
; #define PG8_STAGE(bufoff, gbase, voff) do { _Pragma("unroll") for (int _i = 0; _i < 2; ++_i) \
;         __builtin_amdgcn_global_load_lds((const unsigned*)((const char*)(gbase) + (voff)[_i]), (LAS unsigned*)(lds + (bufoff) + ldsw + _i * 8192), 16, 0, 0); } while (0)
; #define PG8_LDA(dst, b, h) do { _Pragma("unroll") for (int m = 0; m < 4; ++m) _Pragma("unroll") for (int k = 0; k < 2; ++k) dst[m][k] = *(const LAS bf16x8*)(lds + PG8_SA(b, h) + aoff + m * 2048 + k * 1024); } while (0)
; #define PG8_LDB(dst, b, h) do { _Pragma("unroll") for (int n = 0; n < 2; ++n) _Pragma("unroll") for (int k = 0; k < 2; ++k) dst[n][k] = *(const LAS bf16x8*)(lds + PG8_SB(b, h) + boff + n * 2048 + k * 1024); } while (0)
; #define PG8_MMA(ai, bj, At, Bt) do { __builtin_amdgcn_s_setprio(1); _Pragma("unroll") for (int m = 0; m < 4; ++m) _Pragma("unroll") for (int n = 0; n < 2; ++n) _Pragma("unroll") for (int k = 0; k < 2; ++k) \
;         acc[ai][bj][m][n] = __builtin_amdgcn_mfma_f32_16x16x32_bf16(Bt[n][k], At[m][k], acc[ai][bj][m][n], 0, 0, 0); __builtin_amdgcn_s_setprio(0); } while (0)
; #define PG8_WAIT_V(n) asm volatile("s_waitcnt vmcnt(" #n ")" ::: "memory")
; #define PG8_WAIT_L(n) asm volatile("s_waitcnt lgkmcnt(" #n ")" ::: "memory")
; #define PG8_BAR __builtin_amdgcn_s_barrier()
; #define PG8_SCHED __builtin_amdgcn_sched_barrier(0)
; template <class Epi, bool ALIGN_EPI>
; __device__ __forceinline__ void gemm_phase(LAS unsigned char* lds, const Gemm g, const StaticOrder& S, const Epi& E) {
;     ...
;         for (int t = 0; t < nt; t += 2) {
;             const bool last = (t == nt - 2);
;             const char* a1 = cA + (size_t)(t + 1) * kstep;
;             const char* a2 = last ? nA : cA + (size_t)(t + 2) * kstep; const char* b2 = last ? nB : cB + (size_t)(t + 2) * kstep;
;             const char* a3 = a2 + kstep; const char* b3 = b2 + kstep;
;             PG8_LDB(B0, 0, 0); PG8_LDB(B1, 0, 1); PG8_SCHED; PG8_LDA(At, 0, 0); PG8_STAGE(PG8_SA(1, 1), a1 + hA, voffA);
;             PG8_WAIT_V(8); PG8_WAIT_L(0); PG8_BAR; PG8_MMA(0, 0, At, B0); PG8_MMA(0, 1, At, B1); PG8_BAR; PG8_SCHED;
;             PG8_LDA(At, 0, 1); PG8_STAGE(PG8_SB(0, 0), b2, voffB); PG8_STAGE(PG8_SB(0, 1), b2 + hB, voffB); PG8_STAGE(PG8_SA(0, 0), a2, voffA);
;             PG8_WAIT_V(8); PG8_WAIT_L(0); PG8_BAR; PG8_MMA(1, 0, At, B0); PG8_MMA(1, 1, At, B1); PG8_BAR; PG8_SCHED;
.LBB0_252:
	ds_read_b128 v[168:171], v153
	ds_read_b128 v[172:175], v153 offset:1024
	ds_read_b128 v[176:179], v153 offset:2048
	ds_read_b128 v[180:183], v153 offset:3072
	ds_read_b128 v[184:187], v154
	ds_read_b128 v[188:191], v154 offset:1024
	ds_read_b128 v[194:197], v154 offset:2048
	ds_read_b128 v[198:201], v154 offset:3072
	s_add_u32 s8, s6, 0xfff80080
	s_addc_u32 s9, s7, -1
	s_cmp_eq_u32 s71, 28
	s_cselect_b32 s55, s47, s9
	s_cselect_b32 s54, s67, s8
	s_cselect_b32 s9, s45, s70
	s_cselect_b32 s8, s68, s69
	v_lshl_add_u64 v[234:235], s[6:7], 0, v[136:137]
	s_add_i32 m0, s39, 0xc000
	ds_read_b128 v[202:205], v155
	ds_read_b128 v[206:209], v155 offset:1024
	ds_read_b128 v[210:213], v155 offset:2048
	ds_read_b128 v[214:217], v155 offset:3072
	ds_read_b128 v[218:221], v155 offset:4096
	ds_read_b128 v[222:225], v155 offset:5120
	ds_read_b128 v[226:229], v155 offset:6144
	ds_read_b128 v[230:233], v155 offset:7168
	global_load_lds_dwordx4 v[234:235], off
	v_lshl_add_u64 v[234:235], s[6:7], 0, v[138:139]
	s_add_i32 m0, s39, 0xe000
	s_nop 0
	global_load_lds_dwordx4 v[234:235], off
	s_waitcnt vmcnt(8)
	s_waitcnt lgkmcnt(0)
	s_barrier
	s_setprio 1
	s_waitcnt lgkmcnt(0)
	v_mfma_f32_16x16x32_bf16 v[124:127], v[168:171], v[202:205], v[124:127]
	v_mfma_f32_16x16x32_bf16 v[124:127], v[172:175], v[206:209], v[124:127]
	v_mfma_f32_16x16x32_bf16 v[120:123], v[176:179], v[202:205], v[120:123]
	v_mfma_f32_16x16x32_bf16 v[120:123], v[180:183], v[206:209], v[120:123]
	v_mfma_f32_16x16x32_bf16 v[108:111], v[168:171], v[210:213], v[108:111]
	v_mfma_f32_16x16x32_bf16 v[108:111], v[172:175], v[214:217], v[108:111]
	v_mfma_f32_16x16x32_bf16 v[104:107], v[176:179], v[210:213], v[104:107]
	v_mfma_f32_16x16x32_bf16 v[104:107], v[180:183], v[214:217], v[104:107]
	v_mfma_f32_16x16x32_bf16 v[92:95], v[168:171], v[218:221], v[92:95]
	v_mfma_f32_16x16x32_bf16 v[92:95], v[172:175], v[222:225], v[92:95]
	v_mfma_f32_16x16x32_bf16 v[88:91], v[176:179], v[218:221], v[88:91]
	v_mfma_f32_16x16x32_bf16 v[88:91], v[180:183], v[222:225], v[88:91]
	v_mfma_f32_16x16x32_bf16 v[76:79], v[168:171], v[226:229], v[76:79]
	v_mfma_f32_16x16x32_bf16 v[76:79], v[172:175], v[230:233], v[76:79]
	v_mfma_f32_16x16x32_bf16 v[72:75], v[176:179], v[226:229], v[72:75]
	v_mfma_f32_16x16x32_bf16 v[72:75], v[180:183], v[230:233], v[72:75]
	v_mfma_f32_16x16x32_bf16 v[116:119], v[184:187], v[202:205], v[116:119]
	v_mfma_f32_16x16x32_bf16 v[116:119], v[188:191], v[206:209], v[116:119]
	v_mfma_f32_16x16x32_bf16 v[112:115], v[194:197], v[202:205], v[112:115]
	v_mfma_f32_16x16x32_bf16 v[112:115], v[198:201], v[206:209], v[112:115]
	v_mfma_f32_16x16x32_bf16 v[100:103], v[184:187], v[210:213], v[100:103]
	v_mfma_f32_16x16x32_bf16 v[100:103], v[188:191], v[214:217], v[100:103]
	v_mfma_f32_16x16x32_bf16 v[96:99], v[194:197], v[210:213], v[96:99]
	v_mfma_f32_16x16x32_bf16 v[96:99], v[198:201], v[214:217], v[96:99]
	v_mfma_f32_16x16x32_bf16 v[84:87], v[184:187], v[218:221], v[84:87]
	v_mfma_f32_16x16x32_bf16 v[84:87], v[188:191], v[222:225], v[84:87]
	v_mfma_f32_16x16x32_bf16 v[80:83], v[194:197], v[218:221], v[80:83]
	v_mfma_f32_16x16x32_bf16 v[80:83], v[198:201], v[222:225], v[80:83]
	v_mfma_f32_16x16x32_bf16 v[68:71], v[184:187], v[226:229], v[68:71]
	v_mfma_f32_16x16x32_bf16 v[68:71], v[188:191], v[230:233], v[68:71]
	v_mfma_f32_16x16x32_bf16 v[64:67], v[194:197], v[226:229], v[64:67]
	v_mfma_f32_16x16x32_bf16 v[64:67], v[198:201], v[230:233], v[64:67]
	s_setprio 0
	s_barrier
	s_add_i32 s72, s63, s33
	v_lshl_add_u64 v[234:235], s[8:9], 0, v[132:133]
	s_mov_b32 m0, s72
	ds_read_b128 v[202:205], v155 offset:16384
	ds_read_b128 v[206:209], v155 offset:17408
	ds_read_b128 v[210:213], v155 offset:18432
	ds_read_b128 v[214:217], v155 offset:19456
	ds_read_b128 v[218:221], v155 offset:20480
	ds_read_b128 v[222:225], v155 offset:21504
	ds_read_b128 v[226:229], v155 offset:22528
	ds_read_b128 v[230:233], v155 offset:23552
	global_load_lds_dwordx4 v[234:235], off
	s_add_i32 m0, s72, 0x2000
	s_add_u32 s72, s8, 0x80000
	v_lshl_add_u64 v[236:237], s[8:9], 0, v[128:129]
	s_addc_u32 s73, s9, 0
	s_add_i32 s74, s64, s33
	global_load_lds_dwordx4 v[236:237], off
	v_lshl_add_u64 v[238:239], s[72:73], 0, v[132:133]
	s_mov_b32 m0, s74
	v_lshl_add_u64 v[240:241], s[54:55], 0, v[130:131]
	global_load_lds_dwordx4 v[238:239], off
	v_lshl_add_u64 v[238:239], s[72:73], 0, v[128:129]
	s_add_i32 m0, s74, 0x2000
	s_nop 0
	global_load_lds_dwordx4 v[238:239], off
	v_lshl_add_u64 v[238:239], s[54:55], 0, v[134:135]
	s_mov_b32 m0, s39
	s_nop 0
	global_load_lds_dwordx4 v[238:239], off
	s_mov_b32 m0, s53
	s_nop 0
	global_load_lds_dwordx4 v[240:241], off
	s_waitcnt vmcnt(8)
	s_waitcnt lgkmcnt(0)
	s_barrier
; #define PG8_STAGE(bufoff, gbase, voff) do { _Pragma("unroll") for (int _i = 0; _i < 2; ++_i) \
;         __builtin_amdgcn_global_load_lds((const unsigned*)((const char*)(gbase) + (voff)[_i]), (LAS unsigned*)(lds + (bufoff) + ldsw + _i * 8192), 16, 0, 0); } while (0)
; #define PG8_LDA(dst, b, h) do { _Pragma("unroll") for (int m = 0; m < 4; ++m) _Pragma("unroll") for (int k = 0; k < 2; ++k) dst[m][k] = *(const LAS bf16x8*)(lds + PG8_SA(b, h) + aoff + m * 2048 + k * 1024); } while (0)
; #define PG8_LDB(dst, b, h) do { _Pragma("unroll") for (int n = 0; n < 2; ++n) _Pragma("unroll") for (int k = 0; k < 2; ++k) dst[n][k] = *(const LAS bf16x8*)(lds + PG8_SB(b, h) + boff + n * 2048 + k * 1024); } while (0)
; #define PG8_MMA(ai, bj, At, Bt) do { __builtin_amdgcn_s_setprio(1); _Pragma("unroll") for (int m = 0; m < 4; ++m) _Pragma("unroll") for (int n = 0; n < 2; ++n) _Pragma("unroll") for (int k = 0; k < 2; ++k) \
;         acc[ai][bj][m][n] = __builtin_amdgcn_mfma_f32_16x16x32_bf16(Bt[n][k], At[m][k], acc[ai][bj][m][n], 0, 0, 0); __builtin_amdgcn_s_setprio(0); } while (0)
; #define PG8_WAIT_V(n) asm volatile("s_waitcnt vmcnt(" #n ")" ::: "memory")
; #define PG8_WAIT_L(n) asm volatile("s_waitcnt lgkmcnt(" #n ")" ::: "memory")
; #define PG8_BAR __builtin_amdgcn_s_barrier()
; #define PG8_SCHED __builtin_amdgcn_sched_barrier(0)
; template <class Epi, bool ALIGN_EPI>
; __device__ __forceinline__ void gemm_phase(LAS unsigned char* lds, const Gemm g, const StaticOrder& S, const Epi& E) {
;     ...
;             PG8_WAIT_V(8); PG8_WAIT_L(0); PG8_BAR; PG8_MMA(1, 0, At, B0); PG8_MMA(1, 1, At, B1); PG8_BAR; PG8_SCHED;
;             PG8_LDB(B0, 1, 0); PG8_LDB(B1, 1, 1); PG8_SCHED; PG8_LDA(At, 1, 0); PG8_STAGE(PG8_SA(0, 1), a2 + hA, voffA);
;             PG8_WAIT_V(8); PG8_WAIT_L(0); PG8_BAR; PG8_MMA(0, 0, At, B0); PG8_MMA(0, 1, At, B1); PG8_BAR; PG8_SCHED;
	s_setprio 1
	s_waitcnt lgkmcnt(0)
	v_mfma_f32_16x16x32_bf16 v[60:63], v[168:171], v[202:205], v[60:63]
	v_mfma_f32_16x16x32_bf16 v[60:63], v[172:175], v[206:209], v[60:63]
	v_mfma_f32_16x16x32_bf16 v[56:59], v[176:179], v[202:205], v[56:59]
	v_mfma_f32_16x16x32_bf16 v[56:59], v[180:183], v[206:209], v[56:59]
	v_mfma_f32_16x16x32_bf16 v[48:51], v[168:171], v[210:213], v[48:51]
	v_mfma_f32_16x16x32_bf16 v[48:51], v[172:175], v[214:217], v[48:51]
	v_mfma_f32_16x16x32_bf16 v[40:43], v[176:179], v[210:213], v[40:43]
	v_mfma_f32_16x16x32_bf16 v[40:43], v[180:183], v[214:217], v[40:43]
	v_mfma_f32_16x16x32_bf16 v[32:35], v[168:171], v[218:221], v[32:35]
	v_mfma_f32_16x16x32_bf16 v[32:35], v[172:175], v[222:225], v[32:35]
	v_mfma_f32_16x16x32_bf16 v[24:27], v[176:179], v[218:221], v[24:27]
	v_mfma_f32_16x16x32_bf16 v[24:27], v[180:183], v[222:225], v[24:27]
	v_mfma_f32_16x16x32_bf16 v[16:19], v[168:171], v[226:229], v[16:19]
	v_mfma_f32_16x16x32_bf16 v[16:19], v[172:175], v[230:233], v[16:19]
	v_mfma_f32_16x16x32_bf16 v[8:11], v[176:179], v[226:229], v[8:11]
	v_mfma_f32_16x16x32_bf16 v[8:11], v[180:183], v[230:233], v[8:11]
	v_mfma_f32_16x16x32_bf16 v[52:55], v[184:187], v[202:205], v[52:55]
	v_mfma_f32_16x16x32_bf16 v[52:55], v[188:191], v[206:209], v[52:55]
	v_mfma_f32_16x16x32_bf16 v[44:47], v[194:197], v[202:205], v[44:47]
	v_mfma_f32_16x16x32_bf16 v[44:47], v[198:201], v[206:209], v[44:47]
	v_mfma_f32_16x16x32_bf16 v[36:39], v[184:187], v[210:213], v[36:39]
	v_mfma_f32_16x16x32_bf16 v[36:39], v[188:191], v[214:217], v[36:39]
	v_mfma_f32_16x16x32_bf16 v[28:31], v[194:197], v[210:213], v[28:31]
	v_mfma_f32_16x16x32_bf16 v[28:31], v[198:201], v[214:217], v[28:31]
	v_mfma_f32_16x16x32_bf16 v[20:23], v[184:187], v[218:221], v[20:23]
	v_mfma_f32_16x16x32_bf16 v[20:23], v[188:191], v[222:225], v[20:23]
	v_mfma_f32_16x16x32_bf16 v[12:15], v[194:197], v[218:221], v[12:15]
	v_mfma_f32_16x16x32_bf16 v[12:15], v[198:201], v[222:225], v[12:15]
	v_mfma_f32_16x16x32_bf16 v[4:7], v[184:187], v[226:229], v[4:7]
	v_mfma_f32_16x16x32_bf16 v[4:7], v[188:191], v[230:233], v[4:7]
	v_mfma_f32_16x16x32_bf16 v[0:3], v[194:197], v[226:229], v[0:3]
	v_mfma_f32_16x16x32_bf16 v[0:3], v[198:201], v[230:233], v[0:3]
	s_setprio 0
	s_barrier
	s_add_i32 s72, 0, 0x18000
	v_add_u32_e32 v167, s72, v149
	s_add_i32 s73, 0, 0x1c000
	ds_read_b128 v[168:171], v167
	ds_read_b128 v[172:175], v167 offset:1024
	ds_read_b128 v[176:179], v167 offset:2048
	ds_read_b128 v[180:183], v167 offset:3072
	v_add_u32_e32 v167, s73, v149
	ds_read_b128 v[184:187], v167
	ds_read_b128 v[188:191], v167 offset:1024
	ds_read_b128 v[194:197], v167 offset:2048
	ds_read_b128 v[198:201], v167 offset:3072
	s_add_u32 s54, s54, 0x80000
	s_addc_u32 s55, s55, 0
	s_mov_b32 m0, s56
	v_lshl_add_u64 v[242:243], s[54:55], 0, v[134:135]
	ds_read_b128 v[202:205], v155 offset:32768
	ds_read_b128 v[206:209], v155 offset:33792
	ds_read_b128 v[210:213], v155 offset:34816
	ds_read_b128 v[214:217], v155 offset:35840
	ds_read_b128 v[218:221], v155 offset:36864
	ds_read_b128 v[222:225], v155 offset:37888
	ds_read_b128 v[226:229], v155 offset:38912
	ds_read_b128 v[230:233], v155 offset:39936
	global_load_lds_dwordx4 v[242:243], off
	v_lshl_add_u64 v[242:243], s[54:55], 0, v[130:131]
	s_mov_b32 m0, s57
	s_nop 0
	global_load_lds_dwordx4 v[242:243], off
	s_waitcnt vmcnt(8)
	s_waitcnt lgkmcnt(0)
	s_barrier
	s_setprio 1
	s_waitcnt lgkmcnt(0)
	v_mfma_f32_16x16x32_bf16 v[124:127], v[168:171], v[202:205], v[124:127]
	v_mfma_f32_16x16x32_bf16 v[124:127], v[172:175], v[206:209], v[124:127]
	v_mfma_f32_16x16x32_bf16 v[120:123], v[176:179], v[202:205], v[120:123]
	v_mfma_f32_16x16x32_bf16 v[120:123], v[180:183], v[206:209], v[120:123]
	v_mfma_f32_16x16x32_bf16 v[108:111], v[168:171], v[210:213], v[108:111]
	v_mfma_f32_16x16x32_bf16 v[108:111], v[172:175], v[214:217], v[108:111]
	v_mfma_f32_16x16x32_bf16 v[104:107], v[176:179], v[210:213], v[104:107]
	v_mfma_f32_16x16x32_bf16 v[104:107], v[180:183], v[214:217], v[104:107]
	v_mfma_f32_16x16x32_bf16 v[92:95], v[168:171], v[218:221], v[92:95]
	v_mfma_f32_16x16x32_bf16 v[92:95], v[172:175], v[222:225], v[92:95]
	v_mfma_f32_16x16x32_bf16 v[88:91], v[176:179], v[218:221], v[88:91]
	v_mfma_f32_16x16x32_bf16 v[88:91], v[180:183], v[222:225], v[88:91]
	v_mfma_f32_16x16x32_bf16 v[76:79], v[168:171], v[226:229], v[76:79]
	v_mfma_f32_16x16x32_bf16 v[76:79], v[172:175], v[230:233], v[76:79]
	v_mfma_f32_16x16x32_bf16 v[72:75], v[176:179], v[226:229], v[72:75]
	v_mfma_f32_16x16x32_bf16 v[72:75], v[180:183], v[230:233], v[72:75]
	v_mfma_f32_16x16x32_bf16 v[116:119], v[184:187], v[202:205], v[116:119]
	v_mfma_f32_16x16x32_bf16 v[116:119], v[188:191], v[206:209], v[116:119]
	v_mfma_f32_16x16x32_bf16 v[112:115], v[194:197], v[202:205], v[112:115]
	v_mfma_f32_16x16x32_bf16 v[112:115], v[198:201], v[206:209], v[112:115]
	v_mfma_f32_16x16x32_bf16 v[100:103], v[184:187], v[210:213], v[100:103]
	v_mfma_f32_16x16x32_bf16 v[100:103], v[188:191], v[214:217], v[100:103]
	v_mfma_f32_16x16x32_bf16 v[96:99], v[194:197], v[210:213], v[96:99]
	v_mfma_f32_16x16x32_bf16 v[96:99], v[198:201], v[214:217], v[96:99]
	v_mfma_f32_16x16x32_bf16 v[84:87], v[184:187], v[218:221], v[84:87]
	v_mfma_f32_16x16x32_bf16 v[84:87], v[188:191], v[222:225], v[84:87]
	v_mfma_f32_16x16x32_bf16 v[80:83], v[194:197], v[218:221], v[80:83]
	v_mfma_f32_16x16x32_bf16 v[80:83], v[198:201], v[222:225], v[80:83]
	v_mfma_f32_16x16x32_bf16 v[68:71], v[184:187], v[226:229], v[68:71]
	v_mfma_f32_16x16x32_bf16 v[68:71], v[188:191], v[230:233], v[68:71]
	v_mfma_f32_16x16x32_bf16 v[64:67], v[194:197], v[226:229], v[64:67]
	v_mfma_f32_16x16x32_bf16 v[64:67], v[198:201], v[230:233], v[64:67]
	s_setprio 0
	s_barrier
; #define PG8_STAGE(bufoff, gbase, voff) do { _Pragma("unroll") for (int _i = 0; _i < 2; ++_i) \
;         __builtin_amdgcn_global_load_lds((const unsigned*)((const char*)(gbase) + (voff)[_i]), (LAS unsigned*)(lds + (bufoff) + ldsw + _i * 8192), 16, 0, 0); } while (0)
; #define PG8_LDA(dst, b, h) do { _Pragma("unroll") for (int m = 0; m < 4; ++m) _Pragma("unroll") for (int k = 0; k < 2; ++k) dst[m][k] = *(const LAS bf16x8*)(lds + PG8_SA(b, h) + aoff + m * 2048 + k * 1024); } while (0)
; #define PG8_MMA(ai, bj, At, Bt) do { __builtin_amdgcn_s_setprio(1); _Pragma("unroll") for (int m = 0; m < 4; ++m) _Pragma("unroll") for (int n = 0; n < 2; ++n) _Pragma("unroll") for (int k = 0; k < 2; ++k) \
;         acc[ai][bj][m][n] = __builtin_amdgcn_mfma_f32_16x16x32_bf16(Bt[n][k], At[m][k], acc[ai][bj][m][n], 0, 0, 0); __builtin_amdgcn_s_setprio(0); } while (0)
; #define PG8_WAIT_V(n) asm volatile("s_waitcnt vmcnt(" #n ")" ::: "memory")
; #define PG8_WAIT_L(n) asm volatile("s_waitcnt lgkmcnt(" #n ")" ::: "memory")
; #define PG8_BAR __builtin_amdgcn_s_barrier()
; #define PG8_SCHED __builtin_amdgcn_sched_barrier(0)
; template <class Epi, bool ALIGN_EPI>
; __device__ __forceinline__ void gemm_phase(LAS unsigned char* lds, const Gemm g, const StaticOrder& S, const Epi& E) {
;     ...
;             PG8_WAIT_V(8); PG8_WAIT_L(0); PG8_BAR; PG8_MMA(0, 0, At, B0); PG8_MMA(0, 1, At, B1); PG8_BAR; PG8_SCHED;
;             PG8_LDA(At, 1, 1); PG8_STAGE(PG8_SB(1, 0), b3, voffB); PG8_STAGE(PG8_SB(1, 1), b3 + hB, voffB); PG8_STAGE(PG8_SA(1, 0), a3, voffA);
;             PG8_WAIT_V(8); PG8_WAIT_L(0); PG8_BAR; PG8_MMA(1, 0, At, B0); PG8_MMA(1, 1, At, B1); PG8_BAR; PG8_SCHED;
;         }
;         if constexpr (ALIGN_EPI) { if (wr == 0) PG8_BAR; }
	s_add_i32 s54, s72, s33
	v_lshl_add_u64 v[234:235], v[234:235], 0, s[20:21]
	s_mov_b32 m0, s54
	ds_read_b128 v[202:205], v155 offset:49152
	ds_read_b128 v[206:209], v155 offset:50176
	ds_read_b128 v[210:213], v155 offset:51200
	ds_read_b128 v[214:217], v155 offset:52224
	ds_read_b128 v[218:221], v155 offset:53248
	ds_read_b128 v[222:225], v155 offset:54272
	ds_read_b128 v[226:229], v155 offset:55296
	ds_read_b128 v[230:233], v155 offset:56320
	global_load_lds_dwordx4 v[234:235], off
	s_add_i32 m0, s54, 0x2000
	s_add_u32 s8, s8, 0x80080
	v_lshl_add_u64 v[234:235], v[236:237], 0, s[20:21]
	s_addc_u32 s9, s9, 0
	s_add_i32 s54, s73, s33
	global_load_lds_dwordx4 v[234:235], off
	v_lshl_add_u64 v[234:235], s[8:9], 0, v[132:133]
	s_mov_b32 m0, s54
	s_nop 0
	global_load_lds_dwordx4 v[234:235], off
	v_lshl_add_u64 v[234:235], s[8:9], 0, v[128:129]
	s_add_i32 m0, s54, 0x2000
	s_nop 0
	global_load_lds_dwordx4 v[234:235], off
	v_lshl_add_u64 v[234:235], v[238:239], 0, s[20:21]
	s_mov_b32 m0, s60
	s_nop 0
	global_load_lds_dwordx4 v[234:235], off
	v_lshl_add_u64 v[234:235], v[240:241], 0, s[20:21]
	s_mov_b32 m0, s61
	s_nop 0
	global_load_lds_dwordx4 v[234:235], off
	s_waitcnt vmcnt(8)
	s_waitcnt lgkmcnt(0)
	s_barrier
	s_setprio 1
	s_waitcnt lgkmcnt(0)
	v_mfma_f32_16x16x32_bf16 v[60:63], v[168:171], v[202:205], v[60:63]
	v_mfma_f32_16x16x32_bf16 v[60:63], v[172:175], v[206:209], v[60:63]
	v_mfma_f32_16x16x32_bf16 v[56:59], v[176:179], v[202:205], v[56:59]
	v_mfma_f32_16x16x32_bf16 v[56:59], v[180:183], v[206:209], v[56:59]
	v_mfma_f32_16x16x32_bf16 v[48:51], v[168:171], v[210:213], v[48:51]
	v_mfma_f32_16x16x32_bf16 v[48:51], v[172:175], v[214:217], v[48:51]
	v_mfma_f32_16x16x32_bf16 v[40:43], v[176:179], v[210:213], v[40:43]
	v_mfma_f32_16x16x32_bf16 v[40:43], v[180:183], v[214:217], v[40:43]
	v_mfma_f32_16x16x32_bf16 v[32:35], v[168:171], v[218:221], v[32:35]
	v_mfma_f32_16x16x32_bf16 v[32:35], v[172:175], v[222:225], v[32:35]
	v_mfma_f32_16x16x32_bf16 v[24:27], v[176:179], v[218:221], v[24:27]
	v_mfma_f32_16x16x32_bf16 v[24:27], v[180:183], v[222:225], v[24:27]
	v_mfma_f32_16x16x32_bf16 v[16:19], v[168:171], v[226:229], v[16:19]
	v_mfma_f32_16x16x32_bf16 v[16:19], v[172:175], v[230:233], v[16:19]
	v_mfma_f32_16x16x32_bf16 v[8:11], v[176:179], v[226:229], v[8:11]
	v_mfma_f32_16x16x32_bf16 v[8:11], v[180:183], v[230:233], v[8:11]
	v_mfma_f32_16x16x32_bf16 v[52:55], v[184:187], v[202:205], v[52:55]
	v_mfma_f32_16x16x32_bf16 v[52:55], v[188:191], v[206:209], v[52:55]
	v_mfma_f32_16x16x32_bf16 v[44:47], v[194:197], v[202:205], v[44:47]
	v_mfma_f32_16x16x32_bf16 v[44:47], v[198:201], v[206:209], v[44:47]
	v_mfma_f32_16x16x32_bf16 v[36:39], v[184:187], v[210:213], v[36:39]
	v_mfma_f32_16x16x32_bf16 v[36:39], v[188:191], v[214:217], v[36:39]
	v_mfma_f32_16x16x32_bf16 v[28:31], v[194:197], v[210:213], v[28:31]
	v_mfma_f32_16x16x32_bf16 v[28:31], v[198:201], v[214:217], v[28:31]
	v_mfma_f32_16x16x32_bf16 v[20:23], v[184:187], v[218:221], v[20:23]
	v_mfma_f32_16x16x32_bf16 v[20:23], v[188:191], v[222:225], v[20:23]
	v_mfma_f32_16x16x32_bf16 v[12:15], v[194:197], v[218:221], v[12:15]
	v_mfma_f32_16x16x32_bf16 v[12:15], v[198:201], v[222:225], v[12:15]
	v_mfma_f32_16x16x32_bf16 v[4:7], v[184:187], v[226:229], v[4:7]
	v_mfma_f32_16x16x32_bf16 v[4:7], v[188:191], v[230:233], v[4:7]
	v_mfma_f32_16x16x32_bf16 v[0:3], v[194:197], v[226:229], v[0:3]
	v_mfma_f32_16x16x32_bf16 v[0:3], v[198:201], v[230:233], v[0:3]
	s_setprio 0
	s_barrier
	s_add_i32 s71, s71, 2
	s_add_u32 s6, s6, 0x100
	s_addc_u32 s7, s7, 0
	s_add_u32 s69, s69, 0x100
	s_addc_u32 s70, s70, 0
	s_cmp_gt_u32 s71, 29
	s_cbranch_scc0 .LBB0_252
	s_and_b64 vcc, exec, s[22:23]
	s_cbranch_vccz .LBB0_255
	s_barrier

; #define PG8_STAGE(bufoff, gbase, voff) do { _Pragma("unroll") for (int _i = 0; _i < 2; ++_i) \
;         __builtin_amdgcn_global_load_lds((const unsigned*)((const char*)(gbase) + (voff)[_i]), (LAS unsigned*)(lds + (bufoff) + ldsw + _i * 8192), 16, 0, 0); } while (0)
; #define PG8_LDA(dst, b, h) do { _Pragma("unroll") for (int m = 0; m < 4; ++m) _Pragma("unroll") for (int k = 0; k < 2; ++k) dst[m][k] = *(const LAS bf16x8*)(lds + PG8_SA(b, h) + aoff + m * 2048 + k * 1024); } while (0)
; #define PG8_LDB(dst, b, h) do { _Pragma("unroll") for (int n = 0; n < 2; ++n) _Pragma("unroll") for (int k = 0; k < 2; ++k) dst[n][k] = *(const LAS bf16x8*)(lds + PG8_SB(b, h) + boff + n * 2048 + k * 1024); } while (0)
; #define PG8_MMA(ai, bj, At, Bt) do { __builtin_amdgcn_s_setprio(1); _Pragma("unroll") for (int m = 0; m < 4; ++m) _Pragma("unroll") for (int n = 0; n < 2; ++n) _Pragma("unroll") for (int k = 0; k < 2; ++k) \
;         acc[ai][bj][m][n] = __builtin_amdgcn_mfma_f32_16x16x32_bf16(Bt[n][k], At[m][k], acc[ai][bj][m][n], 0, 0, 0); __builtin_amdgcn_s_setprio(0); } while (0)
; #define PG8_WAIT_V(n) asm volatile("s_waitcnt vmcnt(" #n ")" ::: "memory")
; #define PG8_WAIT_L(n) asm volatile("s_waitcnt lgkmcnt(" #n ")" ::: "memory")
; #define PG8_BAR __builtin_amdgcn_s_barrier()
; #define PG8_SCHED __builtin_amdgcn_sched_barrier(0)
; template <class Epi, bool ALIGN_EPI>
; __device__ __forceinline__ void gemm_phase(LAS unsigned char* lds, const Gemm g, const StaticOrder& S, const Epi& E) {
;     ...
;             const bool last = (t == nt - 2);
;             const char* a1 = cA + (size_t)(t + 1) * kstep;
;             const char* a2 = last ? nA : cA + (size_t)(t + 2) * kstep; const char* b2 = last ? nB : cB + (size_t)(t + 2) * kstep;
;             const char* a3 = a2 + kstep; const char* b3 = b2 + kstep;
;             PG8_LDB(B0, 0, 0); PG8_LDB(B1, 0, 1); PG8_SCHED; PG8_LDA(At, 0, 0); PG8_STAGE(PG8_SA(1, 1), a1 + hA, voffA);
;             PG8_WAIT_V(8); PG8_WAIT_L(0); PG8_BAR; PG8_MMA(0, 0, At, B0); PG8_MMA(0, 1, At, B1); PG8_BAR; PG8_SCHED;
;             PG8_LDA(At, 0, 1); PG8_STAGE(PG8_SB(0, 0), b2, voffB); PG8_STAGE(PG8_SB(0, 1), b2 + hB, voffB); PG8_STAGE(PG8_SA(0, 0), a2, voffA);
;             PG8_WAIT_V(8); PG8_WAIT_L(0); PG8_BAR; PG8_MMA(1, 0, At, B0); PG8_MMA(1, 1, At, B1); PG8_BAR; PG8_SCHED;
.LBB0_385:
	ds_read_b128 v[152:155], v149
	ds_read_b128 v[156:159], v149 offset:1024
	ds_read_b128 v[160:163], v149 offset:2048
	ds_read_b128 v[164:167], v149 offset:3072
	ds_read_b128 v[168:171], v150
	ds_read_b128 v[172:175], v150 offset:1024
	ds_read_b128 v[176:179], v150 offset:2048
	ds_read_b128 v[180:183], v150 offset:3072
	s_add_u32 s40, s36, 0xfff80080
	s_addc_u32 s41, s37, -1
	s_cmp_eq_u32 s61, 4
	s_cselect_b32 s43, s27, s41
	s_cselect_b32 s42, s57, s40
	s_cselect_b32 s41, s25, s60
	s_cselect_b32 s40, s58, s59
	v_lshl_add_u64 v[144:145], s[36:37], 0, v[136:137]
	s_add_i32 m0, s35, 0xc000
	ds_read_b128 v[184:187], v151
	ds_read_b128 v[188:191], v151 offset:1024
	ds_read_b128 v[194:197], v151 offset:2048
	ds_read_b128 v[198:201], v151 offset:3072
	ds_read_b128 v[202:205], v151 offset:4096
	ds_read_b128 v[206:209], v151 offset:5120
	ds_read_b128 v[210:213], v151 offset:6144
	ds_read_b128 v[214:217], v151 offset:7168
	global_load_lds_dwordx4 v[144:145], off
	v_lshl_add_u64 v[144:145], s[36:37], 0, v[138:139]
	s_add_i32 m0, s35, 0xe000
	s_nop 0
	global_load_lds_dwordx4 v[144:145], off
	s_waitcnt vmcnt(8)
	s_waitcnt lgkmcnt(0)
	s_barrier
	s_setprio 1
	s_waitcnt lgkmcnt(0)
	v_mfma_f32_16x16x32_bf16 v[124:127], v[152:155], v[184:187], v[124:127]
	v_mfma_f32_16x16x32_bf16 v[124:127], v[156:159], v[188:191], v[124:127]
	v_mfma_f32_16x16x32_bf16 v[120:123], v[160:163], v[184:187], v[120:123]
	v_mfma_f32_16x16x32_bf16 v[120:123], v[164:167], v[188:191], v[120:123]
	v_mfma_f32_16x16x32_bf16 v[116:119], v[152:155], v[194:197], v[116:119]
	v_mfma_f32_16x16x32_bf16 v[116:119], v[156:159], v[198:201], v[116:119]
	v_mfma_f32_16x16x32_bf16 v[108:111], v[160:163], v[194:197], v[108:111]
	v_mfma_f32_16x16x32_bf16 v[108:111], v[164:167], v[198:201], v[108:111]
	v_mfma_f32_16x16x32_bf16 v[100:103], v[152:155], v[202:205], v[100:103]
	v_mfma_f32_16x16x32_bf16 v[100:103], v[156:159], v[206:209], v[100:103]
	v_mfma_f32_16x16x32_bf16 v[92:95], v[160:163], v[202:205], v[92:95]
	v_mfma_f32_16x16x32_bf16 v[92:95], v[164:167], v[206:209], v[92:95]
	v_mfma_f32_16x16x32_bf16 v[84:87], v[152:155], v[210:213], v[84:87]
	v_mfma_f32_16x16x32_bf16 v[84:87], v[156:159], v[214:217], v[84:87]
	v_mfma_f32_16x16x32_bf16 v[76:79], v[160:163], v[210:213], v[76:79]
	v_mfma_f32_16x16x32_bf16 v[76:79], v[164:167], v[214:217], v[76:79]
	v_mfma_f32_16x16x32_bf16 v[112:115], v[168:171], v[184:187], v[112:115]
	v_mfma_f32_16x16x32_bf16 v[112:115], v[172:175], v[188:191], v[112:115]
	v_mfma_f32_16x16x32_bf16 v[104:107], v[176:179], v[184:187], v[104:107]
	v_mfma_f32_16x16x32_bf16 v[104:107], v[180:183], v[188:191], v[104:107]
	v_mfma_f32_16x16x32_bf16 v[96:99], v[168:171], v[194:197], v[96:99]
	v_mfma_f32_16x16x32_bf16 v[96:99], v[172:175], v[198:201], v[96:99]
	v_mfma_f32_16x16x32_bf16 v[88:91], v[176:179], v[194:197], v[88:91]
	v_mfma_f32_16x16x32_bf16 v[88:91], v[180:183], v[198:201], v[88:91]
	v_mfma_f32_16x16x32_bf16 v[80:83], v[168:171], v[202:205], v[80:83]
	v_mfma_f32_16x16x32_bf16 v[80:83], v[172:175], v[206:209], v[80:83]
	v_mfma_f32_16x16x32_bf16 v[72:75], v[176:179], v[202:205], v[72:75]
	v_mfma_f32_16x16x32_bf16 v[72:75], v[180:183], v[206:209], v[72:75]
	v_mfma_f32_16x16x32_bf16 v[68:71], v[168:171], v[210:213], v[68:71]
	v_mfma_f32_16x16x32_bf16 v[68:71], v[172:175], v[214:217], v[68:71]
	v_mfma_f32_16x16x32_bf16 v[64:67], v[176:179], v[210:213], v[64:67]
	v_mfma_f32_16x16x32_bf16 v[64:67], v[180:183], v[214:217], v[64:67]
	s_setprio 0
	s_barrier
	s_add_i32 s62, s53, s45
	v_lshl_add_u64 v[144:145], s[40:41], 0, v[132:133]
	s_mov_b32 m0, s62
	ds_read_b128 v[184:187], v151 offset:16384
	ds_read_b128 v[188:191], v151 offset:17408
	ds_read_b128 v[194:197], v151 offset:18432
	ds_read_b128 v[198:201], v151 offset:19456
	ds_read_b128 v[202:205], v151 offset:20480
	ds_read_b128 v[206:209], v151 offset:21504
	ds_read_b128 v[210:213], v151 offset:22528
	ds_read_b128 v[214:217], v151 offset:23552
	global_load_lds_dwordx4 v[144:145], off
	s_add_i32 m0, s62, 0x2000
	s_add_u32 s62, s40, 0x20000
	v_lshl_add_u64 v[218:219], s[40:41], 0, v[128:129]
	s_addc_u32 s63, s41, 0
	s_add_i32 s64, s54, s45
	global_load_lds_dwordx4 v[218:219], off
	v_lshl_add_u64 v[220:221], s[62:63], 0, v[132:133]
	s_mov_b32 m0, s64
	v_lshl_add_u64 v[222:223], s[42:43], 0, v[130:131]
	global_load_lds_dwordx4 v[220:221], off
	v_lshl_add_u64 v[220:221], s[62:63], 0, v[128:129]
	s_add_i32 m0, s64, 0x2000
	s_nop 0
	global_load_lds_dwordx4 v[220:221], off
	v_lshl_add_u64 v[220:221], s[42:43], 0, v[134:135]
	s_mov_b32 m0, s35
	s_nop 0
	global_load_lds_dwordx4 v[220:221], off
	s_mov_b32 m0, s47
	s_nop 0
	global_load_lds_dwordx4 v[222:223], off
	s_waitcnt vmcnt(8)
	s_waitcnt lgkmcnt(0)
	s_barrier
; #define PG8_STAGE(bufoff, gbase, voff) do { _Pragma("unroll") for (int _i = 0; _i < 2; ++_i) \
;         __builtin_amdgcn_global_load_lds((const unsigned*)((const char*)(gbase) + (voff)[_i]), (LAS unsigned*)(lds + (bufoff) + ldsw + _i * 8192), 16, 0, 0); } while (0)
; #define PG8_LDA(dst, b, h) do { _Pragma("unroll") for (int m = 0; m < 4; ++m) _Pragma("unroll") for (int k = 0; k < 2; ++k) dst[m][k] = *(const LAS bf16x8*)(lds + PG8_SA(b, h) + aoff + m * 2048 + k * 1024); } while (0)
; #define PG8_LDB(dst, b, h) do { _Pragma("unroll") for (int n = 0; n < 2; ++n) _Pragma("unroll") for (int k = 0; k < 2; ++k) dst[n][k] = *(const LAS bf16x8*)(lds + PG8_SB(b, h) + boff + n * 2048 + k * 1024); } while (0)
; #define PG8_MMA(ai, bj, At, Bt) do { __builtin_amdgcn_s_setprio(1); _Pragma("unroll") for (int m = 0; m < 4; ++m) _Pragma("unroll") for (int n = 0; n < 2; ++n) _Pragma("unroll") for (int k = 0; k < 2; ++k) \
;         acc[ai][bj][m][n] = __builtin_amdgcn_mfma_f32_16x16x32_bf16(Bt[n][k], At[m][k], acc[ai][bj][m][n], 0, 0, 0); __builtin_amdgcn_s_setprio(0); } while (0)
; #define PG8_WAIT_V(n) asm volatile("s_waitcnt vmcnt(" #n ")" ::: "memory")
; #define PG8_WAIT_L(n) asm volatile("s_waitcnt lgkmcnt(" #n ")" ::: "memory")
; #define PG8_BAR __builtin_amdgcn_s_barrier()
; #define PG8_SCHED __builtin_amdgcn_sched_barrier(0)
; template <class Epi, bool ALIGN_EPI>
; __device__ __forceinline__ void gemm_phase(LAS unsigned char* lds, const Gemm g, const StaticOrder& S, const Epi& E) {
;     ...
;             PG8_WAIT_V(8); PG8_WAIT_L(0); PG8_BAR; PG8_MMA(1, 0, At, B0); PG8_MMA(1, 1, At, B1); PG8_BAR; PG8_SCHED;
;             PG8_LDB(B0, 1, 0); PG8_LDB(B1, 1, 1); PG8_SCHED; PG8_LDA(At, 1, 0); PG8_STAGE(PG8_SA(0, 1), a2 + hA, voffA);
;             PG8_WAIT_V(8); PG8_WAIT_L(0); PG8_BAR; PG8_MMA(0, 0, At, B0); PG8_MMA(0, 1, At, B1); PG8_BAR; PG8_SCHED;
	s_setprio 1
	s_waitcnt lgkmcnt(0)
	v_mfma_f32_16x16x32_bf16 v[60:63], v[152:155], v[184:187], v[60:63]
	v_mfma_f32_16x16x32_bf16 v[60:63], v[156:159], v[188:191], v[60:63]
	v_mfma_f32_16x16x32_bf16 v[56:59], v[160:163], v[184:187], v[56:59]
	v_mfma_f32_16x16x32_bf16 v[56:59], v[164:167], v[188:191], v[56:59]
	v_mfma_f32_16x16x32_bf16 v[52:55], v[152:155], v[194:197], v[52:55]
	v_mfma_f32_16x16x32_bf16 v[52:55], v[156:159], v[198:201], v[52:55]
	v_mfma_f32_16x16x32_bf16 v[44:47], v[160:163], v[194:197], v[44:47]
	v_mfma_f32_16x16x32_bf16 v[44:47], v[164:167], v[198:201], v[44:47]
	v_mfma_f32_16x16x32_bf16 v[36:39], v[152:155], v[202:205], v[36:39]
	v_mfma_f32_16x16x32_bf16 v[36:39], v[156:159], v[206:209], v[36:39]
	v_mfma_f32_16x16x32_bf16 v[28:31], v[160:163], v[202:205], v[28:31]
	v_mfma_f32_16x16x32_bf16 v[28:31], v[164:167], v[206:209], v[28:31]
	v_mfma_f32_16x16x32_bf16 v[20:23], v[152:155], v[210:213], v[20:23]
	v_mfma_f32_16x16x32_bf16 v[20:23], v[156:159], v[214:217], v[20:23]
	v_mfma_f32_16x16x32_bf16 v[12:15], v[160:163], v[210:213], v[12:15]
	v_mfma_f32_16x16x32_bf16 v[12:15], v[164:167], v[214:217], v[12:15]
	v_mfma_f32_16x16x32_bf16 v[48:51], v[168:171], v[184:187], v[48:51]
	v_mfma_f32_16x16x32_bf16 v[48:51], v[172:175], v[188:191], v[48:51]
	v_mfma_f32_16x16x32_bf16 v[40:43], v[176:179], v[184:187], v[40:43]
	v_mfma_f32_16x16x32_bf16 v[40:43], v[180:183], v[188:191], v[40:43]
	v_mfma_f32_16x16x32_bf16 v[32:35], v[168:171], v[194:197], v[32:35]
	v_mfma_f32_16x16x32_bf16 v[32:35], v[172:175], v[198:201], v[32:35]
	v_mfma_f32_16x16x32_bf16 v[24:27], v[176:179], v[194:197], v[24:27]
	v_mfma_f32_16x16x32_bf16 v[24:27], v[180:183], v[198:201], v[24:27]
	v_mfma_f32_16x16x32_bf16 v[16:19], v[168:171], v[202:205], v[16:19]
	v_mfma_f32_16x16x32_bf16 v[16:19], v[172:175], v[206:209], v[16:19]
	v_mfma_f32_16x16x32_bf16 v[8:11], v[176:179], v[202:205], v[8:11]
	v_mfma_f32_16x16x32_bf16 v[8:11], v[180:183], v[206:209], v[8:11]
	v_mfma_f32_16x16x32_bf16 v[4:7], v[168:171], v[210:213], v[4:7]
	v_mfma_f32_16x16x32_bf16 v[4:7], v[172:175], v[214:217], v[4:7]
	v_mfma_f32_16x16x32_bf16 v[0:3], v[176:179], v[210:213], v[0:3]
	v_mfma_f32_16x16x32_bf16 v[0:3], v[180:183], v[214:217], v[0:3]
	s_setprio 0
	s_barrier
	s_add_i32 s62, 0, 0x18000
	s_add_i32 s63, 0, 0x1c000
	v_add_u32_e32 v164, s62, v147
	v_add_u32_e32 v180, s63, v147
	ds_read_b128 v[152:155], v164
	ds_read_b128 v[156:159], v164 offset:1024
	ds_read_b128 v[160:163], v164 offset:2048
	ds_read_b128 v[164:167], v164 offset:3072
	ds_read_b128 v[168:171], v180
	ds_read_b128 v[172:175], v180 offset:1024
	ds_read_b128 v[176:179], v180 offset:2048
	ds_read_b128 v[180:183], v180 offset:3072
	s_add_u32 s42, s42, 0x80000
	s_addc_u32 s43, s43, 0
	s_mov_b32 m0, s48
	v_lshl_add_u64 v[224:225], s[42:43], 0, v[134:135]
	ds_read_b128 v[184:187], v151 offset:32768
	ds_read_b128 v[188:191], v151 offset:33792
	ds_read_b128 v[194:197], v151 offset:34816
	ds_read_b128 v[198:201], v151 offset:35840
	ds_read_b128 v[202:205], v151 offset:36864
	ds_read_b128 v[206:209], v151 offset:37888
	ds_read_b128 v[210:213], v151 offset:38912
	ds_read_b128 v[214:217], v151 offset:39936
	global_load_lds_dwordx4 v[224:225], off
	v_lshl_add_u64 v[224:225], s[42:43], 0, v[130:131]
	s_mov_b32 m0, s49
	s_nop 0
	global_load_lds_dwordx4 v[224:225], off
	s_waitcnt vmcnt(8)
	s_waitcnt lgkmcnt(0)
	s_barrier
	s_setprio 1
	s_waitcnt lgkmcnt(0)
	v_mfma_f32_16x16x32_bf16 v[124:127], v[152:155], v[184:187], v[124:127]
	v_mfma_f32_16x16x32_bf16 v[124:127], v[156:159], v[188:191], v[124:127]
	v_mfma_f32_16x16x32_bf16 v[120:123], v[160:163], v[184:187], v[120:123]
	v_mfma_f32_16x16x32_bf16 v[120:123], v[164:167], v[188:191], v[120:123]
	v_mfma_f32_16x16x32_bf16 v[116:119], v[152:155], v[194:197], v[116:119]
	v_mfma_f32_16x16x32_bf16 v[116:119], v[156:159], v[198:201], v[116:119]
	v_mfma_f32_16x16x32_bf16 v[108:111], v[160:163], v[194:197], v[108:111]
	v_mfma_f32_16x16x32_bf16 v[108:111], v[164:167], v[198:201], v[108:111]
	v_mfma_f32_16x16x32_bf16 v[100:103], v[152:155], v[202:205], v[100:103]
	v_mfma_f32_16x16x32_bf16 v[100:103], v[156:159], v[206:209], v[100:103]
	v_mfma_f32_16x16x32_bf16 v[92:95], v[160:163], v[202:205], v[92:95]
	v_mfma_f32_16x16x32_bf16 v[92:95], v[164:167], v[206:209], v[92:95]
	v_mfma_f32_16x16x32_bf16 v[84:87], v[152:155], v[210:213], v[84:87]
	v_mfma_f32_16x16x32_bf16 v[84:87], v[156:159], v[214:217], v[84:87]
	v_mfma_f32_16x16x32_bf16 v[76:79], v[160:163], v[210:213], v[76:79]
	v_mfma_f32_16x16x32_bf16 v[76:79], v[164:167], v[214:217], v[76:79]
	v_mfma_f32_16x16x32_bf16 v[112:115], v[168:171], v[184:187], v[112:115]
	v_mfma_f32_16x16x32_bf16 v[112:115], v[172:175], v[188:191], v[112:115]
	v_mfma_f32_16x16x32_bf16 v[104:107], v[176:179], v[184:187], v[104:107]
	v_mfma_f32_16x16x32_bf16 v[104:107], v[180:183], v[188:191], v[104:107]
	v_mfma_f32_16x16x32_bf16 v[96:99], v[168:171], v[194:197], v[96:99]
	v_mfma_f32_16x16x32_bf16 v[96:99], v[172:175], v[198:201], v[96:99]
	v_mfma_f32_16x16x32_bf16 v[88:91], v[176:179], v[194:197], v[88:91]
	v_mfma_f32_16x16x32_bf16 v[88:91], v[180:183], v[198:201], v[88:91]
	v_mfma_f32_16x16x32_bf16 v[80:83], v[168:171], v[202:205], v[80:83]
	v_mfma_f32_16x16x32_bf16 v[80:83], v[172:175], v[206:209], v[80:83]
	v_mfma_f32_16x16x32_bf16 v[72:75], v[176:179], v[202:205], v[72:75]
	v_mfma_f32_16x16x32_bf16 v[72:75], v[180:183], v[206:209], v[72:75]
	v_mfma_f32_16x16x32_bf16 v[68:71], v[168:171], v[210:213], v[68:71]
	v_mfma_f32_16x16x32_bf16 v[68:71], v[172:175], v[214:217], v[68:71]
	v_mfma_f32_16x16x32_bf16 v[64:67], v[176:179], v[210:213], v[64:67]
	v_mfma_f32_16x16x32_bf16 v[64:67], v[180:183], v[214:217], v[64:67]
	s_setprio 0
	s_barrier
; #define PG8_STAGE(bufoff, gbase, voff) do { _Pragma("unroll") for (int _i = 0; _i < 2; ++_i) \
;         __builtin_amdgcn_global_load_lds((const unsigned*)((const char*)(gbase) + (voff)[_i]), (LAS unsigned*)(lds + (bufoff) + ldsw + _i * 8192), 16, 0, 0); } while (0)
; #define PG8_LDA(dst, b, h) do { _Pragma("unroll") for (int m = 0; m < 4; ++m) _Pragma("unroll") for (int k = 0; k < 2; ++k) dst[m][k] = *(const LAS bf16x8*)(lds + PG8_SA(b, h) + aoff + m * 2048 + k * 1024); } while (0)
; #define PG8_MMA(ai, bj, At, Bt) do { __builtin_amdgcn_s_setprio(1); _Pragma("unroll") for (int m = 0; m < 4; ++m) _Pragma("unroll") for (int n = 0; n < 2; ++n) _Pragma("unroll") for (int k = 0; k < 2; ++k) \
;         acc[ai][bj][m][n] = __builtin_amdgcn_mfma_f32_16x16x32_bf16(Bt[n][k], At[m][k], acc[ai][bj][m][n], 0, 0, 0); __builtin_amdgcn_s_setprio(0); } while (0)
; #define PG8_WAIT_V(n) asm volatile("s_waitcnt vmcnt(" #n ")" ::: "memory")
; #define PG8_WAIT_L(n) asm volatile("s_waitcnt lgkmcnt(" #n ")" ::: "memory")
; #define PG8_BAR __builtin_amdgcn_s_barrier()
; #define PG8_SCHED __builtin_amdgcn_sched_barrier(0)
; template <class Epi, bool ALIGN_EPI>
; __device__ __forceinline__ void gemm_phase(LAS unsigned char* lds, const Gemm g, const StaticOrder& S, const Epi& E) {
;     ...
;             PG8_LDA(At, 1, 1); PG8_STAGE(PG8_SB(1, 0), b3, voffB); PG8_STAGE(PG8_SB(1, 1), b3 + hB, voffB); PG8_STAGE(PG8_SA(1, 0), a3, voffA);
;             PG8_WAIT_V(8); PG8_WAIT_L(0); PG8_BAR; PG8_MMA(1, 0, At, B0); PG8_MMA(1, 1, At, B1); PG8_BAR; PG8_SCHED;
;         }
	s_add_i32 s42, s62, s45
	v_lshl_add_u64 v[144:145], v[144:145], 0, s[18:19]
	s_mov_b32 m0, s42
	ds_read_b128 v[184:187], v151 offset:49152
	ds_read_b128 v[188:191], v151 offset:50176
	ds_read_b128 v[194:197], v151 offset:51200
	ds_read_b128 v[198:201], v151 offset:52224
	ds_read_b128 v[202:205], v151 offset:53248
	ds_read_b128 v[206:209], v151 offset:54272
	ds_read_b128 v[210:213], v151 offset:55296
	ds_read_b128 v[214:217], v151 offset:56320
	global_load_lds_dwordx4 v[144:145], off
	s_add_i32 m0, s42, 0x2000
	s_add_u32 s40, s40, 0x20080
	v_lshl_add_u64 v[144:145], v[218:219], 0, s[18:19]
	s_addc_u32 s41, s41, 0
	s_add_i32 s42, s63, s45
	global_load_lds_dwordx4 v[144:145], off
	v_lshl_add_u64 v[144:145], s[40:41], 0, v[132:133]
	s_mov_b32 m0, s42
	s_nop 0
	global_load_lds_dwordx4 v[144:145], off
	v_lshl_add_u64 v[144:145], s[40:41], 0, v[128:129]
	s_add_i32 m0, s42, 0x2000
	s_nop 0
	global_load_lds_dwordx4 v[144:145], off
	v_lshl_add_u64 v[144:145], v[220:221], 0, s[18:19]
	s_mov_b32 m0, s50
	s_nop 0
	global_load_lds_dwordx4 v[144:145], off
	v_lshl_add_u64 v[144:145], v[222:223], 0, s[18:19]
	s_mov_b32 m0, s51
	s_nop 0
	global_load_lds_dwordx4 v[144:145], off
	s_waitcnt vmcnt(8)
	s_waitcnt lgkmcnt(0)
	s_barrier
	s_setprio 1
	s_waitcnt lgkmcnt(0)
	v_mfma_f32_16x16x32_bf16 v[60:63], v[152:155], v[184:187], v[60:63]
	v_mfma_f32_16x16x32_bf16 v[60:63], v[156:159], v[188:191], v[60:63]
	v_mfma_f32_16x16x32_bf16 v[56:59], v[160:163], v[184:187], v[56:59]
	v_mfma_f32_16x16x32_bf16 v[56:59], v[164:167], v[188:191], v[56:59]
	v_mfma_f32_16x16x32_bf16 v[52:55], v[152:155], v[194:197], v[52:55]
	v_mfma_f32_16x16x32_bf16 v[52:55], v[156:159], v[198:201], v[52:55]
	v_mfma_f32_16x16x32_bf16 v[44:47], v[160:163], v[194:197], v[44:47]
	v_mfma_f32_16x16x32_bf16 v[44:47], v[164:167], v[198:201], v[44:47]
	v_mfma_f32_16x16x32_bf16 v[36:39], v[152:155], v[202:205], v[36:39]
	v_mfma_f32_16x16x32_bf16 v[36:39], v[156:159], v[206:209], v[36:39]
	v_mfma_f32_16x16x32_bf16 v[28:31], v[160:163], v[202:205], v[28:31]
	v_mfma_f32_16x16x32_bf16 v[28:31], v[164:167], v[206:209], v[28:31]
	v_mfma_f32_16x16x32_bf16 v[20:23], v[152:155], v[210:213], v[20:23]
	v_mfma_f32_16x16x32_bf16 v[20:23], v[156:159], v[214:217], v[20:23]
	v_mfma_f32_16x16x32_bf16 v[12:15], v[160:163], v[210:213], v[12:15]
	v_mfma_f32_16x16x32_bf16 v[12:15], v[164:167], v[214:217], v[12:15]
	v_mfma_f32_16x16x32_bf16 v[48:51], v[168:171], v[184:187], v[48:51]
	v_mfma_f32_16x16x32_bf16 v[48:51], v[172:175], v[188:191], v[48:51]
	v_mfma_f32_16x16x32_bf16 v[40:43], v[176:179], v[184:187], v[40:43]
	v_mfma_f32_16x16x32_bf16 v[40:43], v[180:183], v[188:191], v[40:43]
	v_mfma_f32_16x16x32_bf16 v[32:35], v[168:171], v[194:197], v[32:35]
	v_mfma_f32_16x16x32_bf16 v[32:35], v[172:175], v[198:201], v[32:35]
	v_mfma_f32_16x16x32_bf16 v[24:27], v[176:179], v[194:197], v[24:27]
	v_mfma_f32_16x16x32_bf16 v[24:27], v[180:183], v[198:201], v[24:27]
	v_mfma_f32_16x16x32_bf16 v[16:19], v[168:171], v[202:205], v[16:19]
	v_mfma_f32_16x16x32_bf16 v[16:19], v[172:175], v[206:209], v[16:19]
	v_mfma_f32_16x16x32_bf16 v[8:11], v[176:179], v[202:205], v[8:11]
	v_mfma_f32_16x16x32_bf16 v[8:11], v[180:183], v[206:209], v[8:11]
	v_mfma_f32_16x16x32_bf16 v[4:7], v[168:171], v[210:213], v[4:7]
	v_mfma_f32_16x16x32_bf16 v[4:7], v[172:175], v[214:217], v[4:7]
	v_mfma_f32_16x16x32_bf16 v[0:3], v[176:179], v[210:213], v[0:3]
	v_mfma_f32_16x16x32_bf16 v[0:3], v[180:183], v[214:217], v[0:3]
	s_setprio 0
	s_barrier
	s_add_i32 s61, s61, 2
	s_add_u32 s36, s36, 0x100
	s_addc_u32 s37, s37, 0
	s_add_u32 s59, s59, 0x100
	s_addc_u32 s60, s60, 0
	s_cmp_gt_u32 s61, 5
	s_cbranch_scc0 .LBB0_385
	s_and_b64 vcc, exec, s[20:21]
	s_cbranch_vccz .LBB0_388
	s_barrier

; #define PG8_STAGE(bufoff, gbase, voff) do { _Pragma("unroll") for (int _i = 0; _i < 2; ++_i) \
;         __builtin_amdgcn_global_load_lds((const unsigned*)((const char*)(gbase) + (voff)[_i]), (LAS unsigned*)(lds + (bufoff) + ldsw + _i * 8192), 16, 0, 0); } while (0)
; #define PG8_LDA(dst, b, h) do { _Pragma("unroll") for (int m = 0; m < 4; ++m) _Pragma("unroll") for (int k = 0; k < 2; ++k) dst[m][k] = *(const LAS bf16x8*)(lds + PG8_SA(b, h) + aoff + m * 2048 + k * 1024); } while (0)
; #define PG8_LDB(dst, b, h) do { _Pragma("unroll") for (int n = 0; n < 2; ++n) _Pragma("unroll") for (int k = 0; k < 2; ++k) dst[n][k] = *(const LAS bf16x8*)(lds + PG8_SB(b, h) + boff + n * 2048 + k * 1024); } while (0)
; #define PG8_MMA(ai, bj, At, Bt) do { __builtin_amdgcn_s_setprio(1); _Pragma("unroll") for (int m = 0; m < 4; ++m) _Pragma("unroll") for (int n = 0; n < 2; ++n) _Pragma("unroll") for (int k = 0; k < 2; ++k) \
;         acc[ai][bj][m][n] = __builtin_amdgcn_mfma_f32_16x16x32_bf16(Bt[n][k], At[m][k], acc[ai][bj][m][n], 0, 0, 0); __builtin_amdgcn_s_setprio(0); } while (0)
; #define PG8_WAIT_V(n) asm volatile("s_waitcnt vmcnt(" #n ")" ::: "memory")
; #define PG8_WAIT_L(n) asm volatile("s_waitcnt lgkmcnt(" #n ")" ::: "memory")
; #define PG8_BAR __builtin_amdgcn_s_barrier()
; #define PG8_SCHED __builtin_amdgcn_sched_barrier(0)
; template <class Epi, bool ALIGN_EPI>
; __device__ __forceinline__ void gemm_phase(LAS unsigned char* lds, const Gemm g, const StaticOrder& S, const Epi& E) {
;     ...
;             const bool last = (t == nt - 2);
;             const char* a1 = cA + (size_t)(t + 1) * kstep;
;             const char* a2 = last ? nA : cA + (size_t)(t + 2) * kstep; const char* b2 = last ? nB : cB + (size_t)(t + 2) * kstep;
;             const char* a3 = a2 + kstep; const char* b3 = b2 + kstep;
;             PG8_LDB(B0, 0, 0); PG8_LDB(B1, 0, 1); PG8_SCHED; PG8_LDA(At, 0, 0); PG8_STAGE(PG8_SA(1, 1), a1 + hA, voffA);
;             PG8_WAIT_V(8); PG8_WAIT_L(0); PG8_BAR; PG8_MMA(0, 0, At, B0); PG8_MMA(0, 1, At, B1); PG8_BAR; PG8_SCHED;
;             PG8_LDA(At, 0, 1); PG8_STAGE(PG8_SB(0, 0), b2, voffB); PG8_STAGE(PG8_SB(0, 1), b2 + hB, voffB); PG8_STAGE(PG8_SA(0, 0), a2, voffA);
;             PG8_WAIT_V(8); PG8_WAIT_L(0); PG8_BAR; PG8_MMA(1, 0, At, B0); PG8_MMA(1, 1, At, B1); PG8_BAR; PG8_SCHED;
.LBB0_403:
	ds_read_b128 v[152:155], v149
	ds_read_b128 v[156:159], v149 offset:1024
	ds_read_b128 v[160:163], v149 offset:2048
	ds_read_b128 v[164:167], v149 offset:3072
	ds_read_b128 v[168:171], v150
	ds_read_b128 v[172:175], v150 offset:1024
	ds_read_b128 v[176:179], v150 offset:2048
	ds_read_b128 v[180:183], v150 offset:3072
	s_add_u32 s30, s6, 0xfff80080
	s_addc_u32 s31, s7, -1
	s_cmp_eq_u32 s53, 8
	s_cselect_b32 s35, s23, s31
	s_cselect_b32 s34, s50, s30
	s_cselect_b32 s31, s25, s52
	s_cselect_b32 s30, s24, s51
	v_lshl_add_u64 v[144:145], s[6:7], 0, v[136:137]
	s_add_i32 m0, s0, 0xc000
	ds_read_b128 v[184:187], v151
	ds_read_b128 v[188:191], v151 offset:1024
	ds_read_b128 v[194:197], v151 offset:2048
	ds_read_b128 v[198:201], v151 offset:3072
	ds_read_b128 v[202:205], v151 offset:4096
	ds_read_b128 v[206:209], v151 offset:5120
	ds_read_b128 v[210:213], v151 offset:6144
	ds_read_b128 v[214:217], v151 offset:7168
	global_load_lds_dwordx4 v[144:145], off
	v_lshl_add_u64 v[144:145], s[6:7], 0, v[138:139]
	s_add_i32 m0, s0, 0xe000
	s_nop 0
	global_load_lds_dwordx4 v[144:145], off
	s_waitcnt vmcnt(8)
	s_waitcnt lgkmcnt(0)
	s_barrier
	s_setprio 1
	s_waitcnt lgkmcnt(0)
	v_mfma_f32_16x16x32_bf16 v[124:127], v[152:155], v[184:187], v[124:127]
	v_mfma_f32_16x16x32_bf16 v[124:127], v[156:159], v[188:191], v[124:127]
	v_mfma_f32_16x16x32_bf16 v[120:123], v[160:163], v[184:187], v[120:123]
	v_mfma_f32_16x16x32_bf16 v[120:123], v[164:167], v[188:191], v[120:123]
	v_mfma_f32_16x16x32_bf16 v[116:119], v[152:155], v[194:197], v[116:119]
	v_mfma_f32_16x16x32_bf16 v[116:119], v[156:159], v[198:201], v[116:119]
	v_mfma_f32_16x16x32_bf16 v[108:111], v[160:163], v[194:197], v[108:111]
	v_mfma_f32_16x16x32_bf16 v[108:111], v[164:167], v[198:201], v[108:111]
	v_mfma_f32_16x16x32_bf16 v[100:103], v[152:155], v[202:205], v[100:103]
	v_mfma_f32_16x16x32_bf16 v[100:103], v[156:159], v[206:209], v[100:103]
	v_mfma_f32_16x16x32_bf16 v[92:95], v[160:163], v[202:205], v[92:95]
	v_mfma_f32_16x16x32_bf16 v[92:95], v[164:167], v[206:209], v[92:95]
	v_mfma_f32_16x16x32_bf16 v[84:87], v[152:155], v[210:213], v[84:87]
	v_mfma_f32_16x16x32_bf16 v[84:87], v[156:159], v[214:217], v[84:87]
	v_mfma_f32_16x16x32_bf16 v[76:79], v[160:163], v[210:213], v[76:79]
	v_mfma_f32_16x16x32_bf16 v[76:79], v[164:167], v[214:217], v[76:79]
	v_mfma_f32_16x16x32_bf16 v[112:115], v[168:171], v[184:187], v[112:115]
	v_mfma_f32_16x16x32_bf16 v[112:115], v[172:175], v[188:191], v[112:115]
	v_mfma_f32_16x16x32_bf16 v[104:107], v[176:179], v[184:187], v[104:107]
	v_mfma_f32_16x16x32_bf16 v[104:107], v[180:183], v[188:191], v[104:107]
	v_mfma_f32_16x16x32_bf16 v[96:99], v[168:171], v[194:197], v[96:99]
	v_mfma_f32_16x16x32_bf16 v[96:99], v[172:175], v[198:201], v[96:99]
	v_mfma_f32_16x16x32_bf16 v[88:91], v[176:179], v[194:197], v[88:91]
	v_mfma_f32_16x16x32_bf16 v[88:91], v[180:183], v[198:201], v[88:91]
	v_mfma_f32_16x16x32_bf16 v[80:83], v[168:171], v[202:205], v[80:83]
	v_mfma_f32_16x16x32_bf16 v[80:83], v[172:175], v[206:209], v[80:83]
	v_mfma_f32_16x16x32_bf16 v[72:75], v[176:179], v[202:205], v[72:75]
	v_mfma_f32_16x16x32_bf16 v[72:75], v[180:183], v[206:209], v[72:75]
	v_mfma_f32_16x16x32_bf16 v[68:71], v[168:171], v[210:213], v[68:71]
	v_mfma_f32_16x16x32_bf16 v[68:71], v[172:175], v[214:217], v[68:71]
	v_mfma_f32_16x16x32_bf16 v[64:67], v[176:179], v[210:213], v[64:67]
	v_mfma_f32_16x16x32_bf16 v[64:67], v[180:183], v[214:217], v[64:67]
	s_setprio 0
	s_barrier
	s_add_i32 s54, s45, s2
	v_lshl_add_u64 v[144:145], s[30:31], 0, v[132:133]
	s_mov_b32 m0, s54
	ds_read_b128 v[184:187], v151 offset:16384
	ds_read_b128 v[188:191], v151 offset:17408
	ds_read_b128 v[194:197], v151 offset:18432
	ds_read_b128 v[198:201], v151 offset:19456
	ds_read_b128 v[202:205], v151 offset:20480
	ds_read_b128 v[206:209], v151 offset:21504
	ds_read_b128 v[210:213], v151 offset:22528
	ds_read_b128 v[214:217], v151 offset:23552
	global_load_lds_dwordx4 v[144:145], off
	s_add_i32 m0, s54, 0x2000
	s_add_u32 s54, s30, 0x30000
	v_lshl_add_u64 v[218:219], s[30:31], 0, v[128:129]
	s_addc_u32 s55, s31, 0
	s_add_i32 s56, s46, s2
	global_load_lds_dwordx4 v[218:219], off
	v_lshl_add_u64 v[220:221], s[54:55], 0, v[132:133]
	s_mov_b32 m0, s56
	v_lshl_add_u64 v[222:223], s[34:35], 0, v[130:131]
	global_load_lds_dwordx4 v[220:221], off
	v_lshl_add_u64 v[220:221], s[54:55], 0, v[128:129]
	s_add_i32 m0, s56, 0x2000
	s_nop 0
	global_load_lds_dwordx4 v[220:221], off
	v_lshl_add_u64 v[220:221], s[34:35], 0, v[134:135]
	s_mov_b32 m0, s0
	s_nop 0
	global_load_lds_dwordx4 v[220:221], off
	s_mov_b32 m0, s1
	s_nop 0
	global_load_lds_dwordx4 v[222:223], off
	s_waitcnt vmcnt(8)
	s_waitcnt lgkmcnt(0)
	s_barrier
; #define PG8_STAGE(bufoff, gbase, voff) do { _Pragma("unroll") for (int _i = 0; _i < 2; ++_i) \
;         __builtin_amdgcn_global_load_lds((const unsigned*)((const char*)(gbase) + (voff)[_i]), (LAS unsigned*)(lds + (bufoff) + ldsw + _i * 8192), 16, 0, 0); } while (0)
; #define PG8_LDA(dst, b, h) do { _Pragma("unroll") for (int m = 0; m < 4; ++m) _Pragma("unroll") for (int k = 0; k < 2; ++k) dst[m][k] = *(const LAS bf16x8*)(lds + PG8_SA(b, h) + aoff + m * 2048 + k * 1024); } while (0)
; #define PG8_LDB(dst, b, h) do { _Pragma("unroll") for (int n = 0; n < 2; ++n) _Pragma("unroll") for (int k = 0; k < 2; ++k) dst[n][k] = *(const LAS bf16x8*)(lds + PG8_SB(b, h) + boff + n * 2048 + k * 1024); } while (0)
; #define PG8_MMA(ai, bj, At, Bt) do { __builtin_amdgcn_s_setprio(1); _Pragma("unroll") for (int m = 0; m < 4; ++m) _Pragma("unroll") for (int n = 0; n < 2; ++n) _Pragma("unroll") for (int k = 0; k < 2; ++k) \
;         acc[ai][bj][m][n] = __builtin_amdgcn_mfma_f32_16x16x32_bf16(Bt[n][k], At[m][k], acc[ai][bj][m][n], 0, 0, 0); __builtin_amdgcn_s_setprio(0); } while (0)
; #define PG8_WAIT_V(n) asm volatile("s_waitcnt vmcnt(" #n ")" ::: "memory")
; #define PG8_WAIT_L(n) asm volatile("s_waitcnt lgkmcnt(" #n ")" ::: "memory")
; #define PG8_BAR __builtin_amdgcn_s_barrier()
; #define PG8_SCHED __builtin_amdgcn_sched_barrier(0)
; template <class Epi, bool ALIGN_EPI>
; __device__ __forceinline__ void gemm_phase(LAS unsigned char* lds, const Gemm g, const StaticOrder& S, const Epi& E) {
;     ...
;             PG8_WAIT_V(8); PG8_WAIT_L(0); PG8_BAR; PG8_MMA(1, 0, At, B0); PG8_MMA(1, 1, At, B1); PG8_BAR; PG8_SCHED;
;             PG8_LDB(B0, 1, 0); PG8_LDB(B1, 1, 1); PG8_SCHED; PG8_LDA(At, 1, 0); PG8_STAGE(PG8_SA(0, 1), a2 + hA, voffA);
;             PG8_WAIT_V(8); PG8_WAIT_L(0); PG8_BAR; PG8_MMA(0, 0, At, B0); PG8_MMA(0, 1, At, B1); PG8_BAR; PG8_SCHED;
	s_setprio 1
	s_waitcnt lgkmcnt(0)
	v_mfma_f32_16x16x32_bf16 v[60:63], v[152:155], v[184:187], v[60:63]
	v_mfma_f32_16x16x32_bf16 v[60:63], v[156:159], v[188:191], v[60:63]
	v_mfma_f32_16x16x32_bf16 v[56:59], v[160:163], v[184:187], v[56:59]
	v_mfma_f32_16x16x32_bf16 v[56:59], v[164:167], v[188:191], v[56:59]
	v_mfma_f32_16x16x32_bf16 v[52:55], v[152:155], v[194:197], v[52:55]
	v_mfma_f32_16x16x32_bf16 v[52:55], v[156:159], v[198:201], v[52:55]
	v_mfma_f32_16x16x32_bf16 v[44:47], v[160:163], v[194:197], v[44:47]
	v_mfma_f32_16x16x32_bf16 v[44:47], v[164:167], v[198:201], v[44:47]
	v_mfma_f32_16x16x32_bf16 v[36:39], v[152:155], v[202:205], v[36:39]
	v_mfma_f32_16x16x32_bf16 v[36:39], v[156:159], v[206:209], v[36:39]
	v_mfma_f32_16x16x32_bf16 v[28:31], v[160:163], v[202:205], v[28:31]
	v_mfma_f32_16x16x32_bf16 v[28:31], v[164:167], v[206:209], v[28:31]
	v_mfma_f32_16x16x32_bf16 v[20:23], v[152:155], v[210:213], v[20:23]
	v_mfma_f32_16x16x32_bf16 v[20:23], v[156:159], v[214:217], v[20:23]
	v_mfma_f32_16x16x32_bf16 v[12:15], v[160:163], v[210:213], v[12:15]
	v_mfma_f32_16x16x32_bf16 v[12:15], v[164:167], v[214:217], v[12:15]
	v_mfma_f32_16x16x32_bf16 v[48:51], v[168:171], v[184:187], v[48:51]
	v_mfma_f32_16x16x32_bf16 v[48:51], v[172:175], v[188:191], v[48:51]
	v_mfma_f32_16x16x32_bf16 v[40:43], v[176:179], v[184:187], v[40:43]
	v_mfma_f32_16x16x32_bf16 v[40:43], v[180:183], v[188:191], v[40:43]
	v_mfma_f32_16x16x32_bf16 v[32:35], v[168:171], v[194:197], v[32:35]
	v_mfma_f32_16x16x32_bf16 v[32:35], v[172:175], v[198:201], v[32:35]
	v_mfma_f32_16x16x32_bf16 v[24:27], v[176:179], v[194:197], v[24:27]
	v_mfma_f32_16x16x32_bf16 v[24:27], v[180:183], v[198:201], v[24:27]
	v_mfma_f32_16x16x32_bf16 v[16:19], v[168:171], v[202:205], v[16:19]
	v_mfma_f32_16x16x32_bf16 v[16:19], v[172:175], v[206:209], v[16:19]
	v_mfma_f32_16x16x32_bf16 v[8:11], v[176:179], v[202:205], v[8:11]
	v_mfma_f32_16x16x32_bf16 v[8:11], v[180:183], v[206:209], v[8:11]
	v_mfma_f32_16x16x32_bf16 v[4:7], v[168:171], v[210:213], v[4:7]
	v_mfma_f32_16x16x32_bf16 v[4:7], v[172:175], v[214:217], v[4:7]
	v_mfma_f32_16x16x32_bf16 v[0:3], v[176:179], v[210:213], v[0:3]
	v_mfma_f32_16x16x32_bf16 v[0:3], v[180:183], v[214:217], v[0:3]
	s_setprio 0
	s_barrier
	s_add_i32 s54, 0, 0x18000
	s_add_i32 s55, 0, 0x1c000
	v_add_u32_e32 v164, s54, v147
	v_add_u32_e32 v180, s55, v147
	ds_read_b128 v[152:155], v164
	ds_read_b128 v[156:159], v164 offset:1024
	ds_read_b128 v[160:163], v164 offset:2048
	ds_read_b128 v[164:167], v164 offset:3072
	ds_read_b128 v[168:171], v180
	ds_read_b128 v[172:175], v180 offset:1024
	ds_read_b128 v[176:179], v180 offset:2048
	ds_read_b128 v[180:183], v180 offset:3072
	s_add_u32 s34, s34, 0x80000
	s_addc_u32 s35, s35, 0
	s_mov_b32 m0, s29
	v_lshl_add_u64 v[224:225], s[34:35], 0, v[134:135]
	ds_read_b128 v[184:187], v151 offset:32768
	ds_read_b128 v[188:191], v151 offset:33792
	ds_read_b128 v[194:197], v151 offset:34816
	ds_read_b128 v[198:201], v151 offset:35840
	ds_read_b128 v[202:205], v151 offset:36864
	ds_read_b128 v[206:209], v151 offset:37888
	ds_read_b128 v[210:213], v151 offset:38912
	ds_read_b128 v[214:217], v151 offset:39936
	global_load_lds_dwordx4 v[224:225], off
	v_lshl_add_u64 v[224:225], s[34:35], 0, v[130:131]
	s_mov_b32 m0, s40
	s_nop 0
	global_load_lds_dwordx4 v[224:225], off
	s_waitcnt vmcnt(8)
	s_waitcnt lgkmcnt(0)
	s_barrier
	s_setprio 1
	s_waitcnt lgkmcnt(0)
	v_mfma_f32_16x16x32_bf16 v[124:127], v[152:155], v[184:187], v[124:127]
	v_mfma_f32_16x16x32_bf16 v[124:127], v[156:159], v[188:191], v[124:127]
	v_mfma_f32_16x16x32_bf16 v[120:123], v[160:163], v[184:187], v[120:123]
	v_mfma_f32_16x16x32_bf16 v[120:123], v[164:167], v[188:191], v[120:123]
	v_mfma_f32_16x16x32_bf16 v[116:119], v[152:155], v[194:197], v[116:119]
	v_mfma_f32_16x16x32_bf16 v[116:119], v[156:159], v[198:201], v[116:119]
	v_mfma_f32_16x16x32_bf16 v[108:111], v[160:163], v[194:197], v[108:111]
	v_mfma_f32_16x16x32_bf16 v[108:111], v[164:167], v[198:201], v[108:111]
	v_mfma_f32_16x16x32_bf16 v[100:103], v[152:155], v[202:205], v[100:103]
	v_mfma_f32_16x16x32_bf16 v[100:103], v[156:159], v[206:209], v[100:103]
	v_mfma_f32_16x16x32_bf16 v[92:95], v[160:163], v[202:205], v[92:95]
	v_mfma_f32_16x16x32_bf16 v[92:95], v[164:167], v[206:209], v[92:95]
	v_mfma_f32_16x16x32_bf16 v[84:87], v[152:155], v[210:213], v[84:87]
	v_mfma_f32_16x16x32_bf16 v[84:87], v[156:159], v[214:217], v[84:87]
	v_mfma_f32_16x16x32_bf16 v[76:79], v[160:163], v[210:213], v[76:79]
	v_mfma_f32_16x16x32_bf16 v[76:79], v[164:167], v[214:217], v[76:79]
	v_mfma_f32_16x16x32_bf16 v[112:115], v[168:171], v[184:187], v[112:115]
	v_mfma_f32_16x16x32_bf16 v[112:115], v[172:175], v[188:191], v[112:115]
	v_mfma_f32_16x16x32_bf16 v[104:107], v[176:179], v[184:187], v[104:107]
	v_mfma_f32_16x16x32_bf16 v[104:107], v[180:183], v[188:191], v[104:107]
	v_mfma_f32_16x16x32_bf16 v[96:99], v[168:171], v[194:197], v[96:99]
	v_mfma_f32_16x16x32_bf16 v[96:99], v[172:175], v[198:201], v[96:99]
	v_mfma_f32_16x16x32_bf16 v[88:91], v[176:179], v[194:197], v[88:91]
	v_mfma_f32_16x16x32_bf16 v[88:91], v[180:183], v[198:201], v[88:91]
	v_mfma_f32_16x16x32_bf16 v[80:83], v[168:171], v[202:205], v[80:83]
	v_mfma_f32_16x16x32_bf16 v[80:83], v[172:175], v[206:209], v[80:83]
	v_mfma_f32_16x16x32_bf16 v[72:75], v[176:179], v[202:205], v[72:75]
	v_mfma_f32_16x16x32_bf16 v[72:75], v[180:183], v[206:209], v[72:75]
	v_mfma_f32_16x16x32_bf16 v[68:71], v[168:171], v[210:213], v[68:71]
	v_mfma_f32_16x16x32_bf16 v[68:71], v[172:175], v[214:217], v[68:71]
	v_mfma_f32_16x16x32_bf16 v[64:67], v[176:179], v[210:213], v[64:67]
	v_mfma_f32_16x16x32_bf16 v[64:67], v[180:183], v[214:217], v[64:67]
	s_setprio 0
	s_barrier
; #define PG8_STAGE(bufoff, gbase, voff) do { _Pragma("unroll") for (int _i = 0; _i < 2; ++_i) \
;         __builtin_amdgcn_global_load_lds((const unsigned*)((const char*)(gbase) + (voff)[_i]), (LAS unsigned*)(lds + (bufoff) + ldsw + _i * 8192), 16, 0, 0); } while (0)
; #define PG8_LDA(dst, b, h) do { _Pragma("unroll") for (int m = 0; m < 4; ++m) _Pragma("unroll") for (int k = 0; k < 2; ++k) dst[m][k] = *(const LAS bf16x8*)(lds + PG8_SA(b, h) + aoff + m * 2048 + k * 1024); } while (0)
; #define PG8_MMA(ai, bj, At, Bt) do { __builtin_amdgcn_s_setprio(1); _Pragma("unroll") for (int m = 0; m < 4; ++m) _Pragma("unroll") for (int n = 0; n < 2; ++n) _Pragma("unroll") for (int k = 0; k < 2; ++k) \
;         acc[ai][bj][m][n] = __builtin_amdgcn_mfma_f32_16x16x32_bf16(Bt[n][k], At[m][k], acc[ai][bj][m][n], 0, 0, 0); __builtin_amdgcn_s_setprio(0); } while (0)
; #define PG8_WAIT_V(n) asm volatile("s_waitcnt vmcnt(" #n ")" ::: "memory")
; #define PG8_WAIT_L(n) asm volatile("s_waitcnt lgkmcnt(" #n ")" ::: "memory")
; #define PG8_BAR __builtin_amdgcn_s_barrier()
; #define PG8_SCHED __builtin_amdgcn_sched_barrier(0)
; template <class Epi, bool ALIGN_EPI>
; __device__ __forceinline__ void gemm_phase(LAS unsigned char* lds, const Gemm g, const StaticOrder& S, const Epi& E) {
;     ...
;             PG8_LDA(At, 1, 1); PG8_STAGE(PG8_SB(1, 0), b3, voffB); PG8_STAGE(PG8_SB(1, 1), b3 + hB, voffB); PG8_STAGE(PG8_SA(1, 0), a3, voffA);
;             PG8_WAIT_V(8); PG8_WAIT_L(0); PG8_BAR; PG8_MMA(1, 0, At, B0); PG8_MMA(1, 1, At, B1); PG8_BAR; PG8_SCHED;
;         }
	s_add_i32 s34, s54, s2
	v_lshl_add_u64 v[144:145], v[144:145], 0, s[16:17]
	s_mov_b32 m0, s34
	ds_read_b128 v[184:187], v151 offset:49152
	ds_read_b128 v[188:191], v151 offset:50176
	ds_read_b128 v[194:197], v151 offset:51200
	ds_read_b128 v[198:201], v151 offset:52224
	ds_read_b128 v[202:205], v151 offset:53248
	ds_read_b128 v[206:209], v151 offset:54272
	ds_read_b128 v[210:213], v151 offset:55296
	ds_read_b128 v[214:217], v151 offset:56320
	global_load_lds_dwordx4 v[144:145], off
	s_add_i32 m0, s34, 0x2000
	s_add_u32 s30, s30, 0x30080
	v_lshl_add_u64 v[144:145], v[218:219], 0, s[16:17]
	s_addc_u32 s31, s31, 0
	s_add_i32 s34, s55, s2
	global_load_lds_dwordx4 v[144:145], off
	v_lshl_add_u64 v[144:145], s[30:31], 0, v[132:133]
	s_mov_b32 m0, s34
	s_nop 0
	global_load_lds_dwordx4 v[144:145], off
	v_lshl_add_u64 v[144:145], s[30:31], 0, v[128:129]
	s_add_i32 m0, s34, 0x2000
	s_nop 0
	global_load_lds_dwordx4 v[144:145], off
	v_lshl_add_u64 v[144:145], v[220:221], 0, s[16:17]
	s_mov_b32 m0, s42
	s_nop 0
	global_load_lds_dwordx4 v[144:145], off
	v_lshl_add_u64 v[144:145], v[222:223], 0, s[16:17]
	s_mov_b32 m0, s43
	s_nop 0
	global_load_lds_dwordx4 v[144:145], off
	s_waitcnt vmcnt(8)
	s_waitcnt lgkmcnt(0)
	s_barrier
	s_setprio 1
	s_waitcnt lgkmcnt(0)
	v_mfma_f32_16x16x32_bf16 v[60:63], v[152:155], v[184:187], v[60:63]
	v_mfma_f32_16x16x32_bf16 v[60:63], v[156:159], v[188:191], v[60:63]
	v_mfma_f32_16x16x32_bf16 v[56:59], v[160:163], v[184:187], v[56:59]
	v_mfma_f32_16x16x32_bf16 v[56:59], v[164:167], v[188:191], v[56:59]
	v_mfma_f32_16x16x32_bf16 v[52:55], v[152:155], v[194:197], v[52:55]
	v_mfma_f32_16x16x32_bf16 v[52:55], v[156:159], v[198:201], v[52:55]
	v_mfma_f32_16x16x32_bf16 v[44:47], v[160:163], v[194:197], v[44:47]
	v_mfma_f32_16x16x32_bf16 v[44:47], v[164:167], v[198:201], v[44:47]
	v_mfma_f32_16x16x32_bf16 v[36:39], v[152:155], v[202:205], v[36:39]
	v_mfma_f32_16x16x32_bf16 v[36:39], v[156:159], v[206:209], v[36:39]
	v_mfma_f32_16x16x32_bf16 v[28:31], v[160:163], v[202:205], v[28:31]
	v_mfma_f32_16x16x32_bf16 v[28:31], v[164:167], v[206:209], v[28:31]
	v_mfma_f32_16x16x32_bf16 v[20:23], v[152:155], v[210:213], v[20:23]
	v_mfma_f32_16x16x32_bf16 v[20:23], v[156:159], v[214:217], v[20:23]
	v_mfma_f32_16x16x32_bf16 v[12:15], v[160:163], v[210:213], v[12:15]
	v_mfma_f32_16x16x32_bf16 v[12:15], v[164:167], v[214:217], v[12:15]
	v_mfma_f32_16x16x32_bf16 v[48:51], v[168:171], v[184:187], v[48:51]
	v_mfma_f32_16x16x32_bf16 v[48:51], v[172:175], v[188:191], v[48:51]
	v_mfma_f32_16x16x32_bf16 v[40:43], v[176:179], v[184:187], v[40:43]
	v_mfma_f32_16x16x32_bf16 v[40:43], v[180:183], v[188:191], v[40:43]
	v_mfma_f32_16x16x32_bf16 v[32:35], v[168:171], v[194:197], v[32:35]
	v_mfma_f32_16x16x32_bf16 v[32:35], v[172:175], v[198:201], v[32:35]
	v_mfma_f32_16x16x32_bf16 v[24:27], v[176:179], v[194:197], v[24:27]
	v_mfma_f32_16x16x32_bf16 v[24:27], v[180:183], v[198:201], v[24:27]
	v_mfma_f32_16x16x32_bf16 v[16:19], v[168:171], v[202:205], v[16:19]
	v_mfma_f32_16x16x32_bf16 v[16:19], v[172:175], v[206:209], v[16:19]
	v_mfma_f32_16x16x32_bf16 v[8:11], v[176:179], v[202:205], v[8:11]
	v_mfma_f32_16x16x32_bf16 v[8:11], v[180:183], v[206:209], v[8:11]
	v_mfma_f32_16x16x32_bf16 v[4:7], v[168:171], v[210:213], v[4:7]
	v_mfma_f32_16x16x32_bf16 v[4:7], v[172:175], v[214:217], v[4:7]
	v_mfma_f32_16x16x32_bf16 v[0:3], v[176:179], v[210:213], v[0:3]
	v_mfma_f32_16x16x32_bf16 v[0:3], v[180:183], v[214:217], v[0:3]
	s_setprio 0
	s_barrier
	s_add_i32 s53, s53, 2
	s_add_u32 s6, s6, 0x100
	s_addc_u32 s7, s7, 0
	s_add_u32 s51, s51, 0x100
	s_addc_u32 s52, s52, 0
	s_cmp_gt_u32 s53, 9
	s_cbranch_scc0 .LBB0_403
	s_and_b64 vcc, exec, s[18:19]
	s_cbranch_vccz .LBB0_406
	s_barrier

; #define PG8_STAGE(bufoff, gbase, voff) do { _Pragma("unroll") for (int _i = 0; _i < 2; ++_i) \
;         __builtin_amdgcn_global_load_lds((const unsigned*)((const char*)(gbase) + (voff)[_i]), (LAS unsigned*)(lds + (bufoff) + ldsw + _i * 8192), 16, 0, 0); } while (0)
; #define PG8_LDA(dst, b, h) do { _Pragma("unroll") for (int m = 0; m < 4; ++m) _Pragma("unroll") for (int k = 0; k < 2; ++k) dst[m][k] = *(const LAS bf16x8*)(lds + PG8_SA(b, h) + aoff + m * 2048 + k * 1024); } while (0)
; #define PG8_LDB(dst, b, h) do { _Pragma("unroll") for (int n = 0; n < 2; ++n) _Pragma("unroll") for (int k = 0; k < 2; ++k) dst[n][k] = *(const LAS bf16x8*)(lds + PG8_SB(b, h) + boff + n * 2048 + k * 1024); } while (0)
; #define PG8_MMA(ai, bj, At, Bt) do { __builtin_amdgcn_s_setprio(1); _Pragma("unroll") for (int m = 0; m < 4; ++m) _Pragma("unroll") for (int n = 0; n < 2; ++n) _Pragma("unroll") for (int k = 0; k < 2; ++k) \
;         acc[ai][bj][m][n] = __builtin_amdgcn_mfma_f32_16x16x32_bf16(Bt[n][k], At[m][k], acc[ai][bj][m][n], 0, 0, 0); __builtin_amdgcn_s_setprio(0); } while (0)
; #define PG8_WAIT_V(n) asm volatile("s_waitcnt vmcnt(" #n ")" ::: "memory")
; #define PG8_WAIT_L(n) asm volatile("s_waitcnt lgkmcnt(" #n ")" ::: "memory")
; #define PG8_BAR __builtin_amdgcn_s_barrier()
; #define PG8_SCHED __builtin_amdgcn_sched_barrier(0)
; template <class Epi, bool ALIGN_EPI>
; __device__ __forceinline__ void gemm_phase(LAS unsigned char* lds, const Gemm g, const StaticOrder& S, const Epi& E) {
;     ...
;             const bool last = (t == nt - 2);
;             const char* a1 = cA + (size_t)(t + 1) * kstep;
;             const char* a2 = last ? nA : cA + (size_t)(t + 2) * kstep; const char* b2 = last ? nB : cB + (size_t)(t + 2) * kstep;
;             const char* a3 = a2 + kstep; const char* b3 = b2 + kstep;
;             PG8_LDB(B0, 0, 0); PG8_LDB(B1, 0, 1); PG8_SCHED; PG8_LDA(At, 0, 0); PG8_STAGE(PG8_SA(1, 1), a1 + hA, voffA);
;             PG8_WAIT_V(8); PG8_WAIT_L(0); PG8_BAR; PG8_MMA(0, 0, At, B0); PG8_MMA(0, 1, At, B1); PG8_BAR; PG8_SCHED;
;             PG8_LDA(At, 0, 1); PG8_STAGE(PG8_SB(0, 0), b2, voffB); PG8_STAGE(PG8_SB(0, 1), b2 + hB, voffB); PG8_STAGE(PG8_SA(0, 0), a2, voffA);
;             PG8_WAIT_V(8); PG8_WAIT_L(0); PG8_BAR; PG8_MMA(1, 0, At, B0); PG8_MMA(1, 1, At, B1); PG8_BAR; PG8_SCHED;
.LBB0_419:
	ds_read_b128 v[148:151], v145
	ds_read_b128 v[152:155], v145 offset:1024
	ds_read_b128 v[156:159], v145 offset:2048
	ds_read_b128 v[160:163], v145 offset:3072
	ds_read_b128 v[164:167], v146
	ds_read_b128 v[168:171], v146 offset:1024
	ds_read_b128 v[172:175], v146 offset:2048
	ds_read_b128 v[176:179], v146 offset:3072
	s_add_u32 s30, s28, 0xfff80080
	s_addc_u32 s31, s29, -1
	s_cmp_eq_u32 s53, 28
	s_cselect_b32 s35, s19, s31
	s_cselect_b32 s34, s49, s30
	s_cselect_b32 s31, s17, s52
	s_cselect_b32 s30, s50, s51
	v_lshl_add_u64 v[140:141], s[28:29], 0, v[136:137]
	s_add_i32 m0, s27, 0xc000
	ds_read_b128 v[180:183], v147
	ds_read_b128 v[184:187], v147 offset:1024
	ds_read_b128 v[188:191], v147 offset:2048
	ds_read_b128 v[194:197], v147 offset:3072
	ds_read_b128 v[198:201], v147 offset:4096
	ds_read_b128 v[202:205], v147 offset:5120
	ds_read_b128 v[206:209], v147 offset:6144
	ds_read_b128 v[210:213], v147 offset:7168
	global_load_lds_dwordx4 v[140:141], off
	v_lshl_add_u64 v[140:141], s[28:29], 0, v[138:139]
	s_add_i32 m0, s27, 0xe000
	s_nop 0
	global_load_lds_dwordx4 v[140:141], off
	s_waitcnt vmcnt(8)
	s_waitcnt lgkmcnt(0)
	s_barrier
	s_setprio 1
	s_waitcnt lgkmcnt(0)
	v_mfma_f32_16x16x32_bf16 v[124:127], v[148:151], v[180:183], v[124:127]
	v_mfma_f32_16x16x32_bf16 v[124:127], v[152:155], v[184:187], v[124:127]
	v_mfma_f32_16x16x32_bf16 v[120:123], v[156:159], v[180:183], v[120:123]
	v_mfma_f32_16x16x32_bf16 v[120:123], v[160:163], v[184:187], v[120:123]
	v_mfma_f32_16x16x32_bf16 v[116:119], v[148:151], v[188:191], v[116:119]
	v_mfma_f32_16x16x32_bf16 v[116:119], v[152:155], v[194:197], v[116:119]
	v_mfma_f32_16x16x32_bf16 v[108:111], v[156:159], v[188:191], v[108:111]
	v_mfma_f32_16x16x32_bf16 v[108:111], v[160:163], v[194:197], v[108:111]
	v_mfma_f32_16x16x32_bf16 v[100:103], v[148:151], v[198:201], v[100:103]
	v_mfma_f32_16x16x32_bf16 v[100:103], v[152:155], v[202:205], v[100:103]
	v_mfma_f32_16x16x32_bf16 v[92:95], v[156:159], v[198:201], v[92:95]
	v_mfma_f32_16x16x32_bf16 v[92:95], v[160:163], v[202:205], v[92:95]
	v_mfma_f32_16x16x32_bf16 v[84:87], v[148:151], v[206:209], v[84:87]
	v_mfma_f32_16x16x32_bf16 v[84:87], v[152:155], v[210:213], v[84:87]
	v_mfma_f32_16x16x32_bf16 v[76:79], v[156:159], v[206:209], v[76:79]
	v_mfma_f32_16x16x32_bf16 v[76:79], v[160:163], v[210:213], v[76:79]
	v_mfma_f32_16x16x32_bf16 v[112:115], v[164:167], v[180:183], v[112:115]
	v_mfma_f32_16x16x32_bf16 v[112:115], v[168:171], v[184:187], v[112:115]
	v_mfma_f32_16x16x32_bf16 v[104:107], v[172:175], v[180:183], v[104:107]
	v_mfma_f32_16x16x32_bf16 v[104:107], v[176:179], v[184:187], v[104:107]
	v_mfma_f32_16x16x32_bf16 v[96:99], v[164:167], v[188:191], v[96:99]
	v_mfma_f32_16x16x32_bf16 v[96:99], v[168:171], v[194:197], v[96:99]
	v_mfma_f32_16x16x32_bf16 v[88:91], v[172:175], v[188:191], v[88:91]
	v_mfma_f32_16x16x32_bf16 v[88:91], v[176:179], v[194:197], v[88:91]
	v_mfma_f32_16x16x32_bf16 v[80:83], v[164:167], v[198:201], v[80:83]
	v_mfma_f32_16x16x32_bf16 v[80:83], v[168:171], v[202:205], v[80:83]
	v_mfma_f32_16x16x32_bf16 v[72:75], v[172:175], v[198:201], v[72:75]
	v_mfma_f32_16x16x32_bf16 v[72:75], v[176:179], v[202:205], v[72:75]
	v_mfma_f32_16x16x32_bf16 v[68:71], v[164:167], v[206:209], v[68:71]
	v_mfma_f32_16x16x32_bf16 v[68:71], v[168:171], v[210:213], v[68:71]
	v_mfma_f32_16x16x32_bf16 v[64:67], v[172:175], v[206:209], v[64:67]
	v_mfma_f32_16x16x32_bf16 v[64:67], v[176:179], v[210:213], v[64:67]
	s_setprio 0
	s_barrier
	s_add_i32 s54, s45, s1
	v_lshl_add_u64 v[140:141], s[30:31], 0, v[132:133]
	s_mov_b32 m0, s54
	ds_read_b128 v[180:183], v147 offset:16384
	ds_read_b128 v[184:187], v147 offset:17408
	ds_read_b128 v[188:191], v147 offset:18432
	ds_read_b128 v[194:197], v147 offset:19456
	ds_read_b128 v[198:201], v147 offset:20480
	ds_read_b128 v[202:205], v147 offset:21504
	ds_read_b128 v[206:209], v147 offset:22528
	ds_read_b128 v[210:213], v147 offset:23552
	global_load_lds_dwordx4 v[140:141], off
	s_add_i32 m0, s54, 0x2000
	s_add_u32 s54, s30, 0x80000
	v_lshl_add_u64 v[214:215], s[30:31], 0, v[128:129]
	s_addc_u32 s55, s31, 0
	s_add_i32 s56, s46, s1
	global_load_lds_dwordx4 v[214:215], off
	v_lshl_add_u64 v[216:217], s[54:55], 0, v[132:133]
	s_mov_b32 m0, s56
	v_lshl_add_u64 v[218:219], s[34:35], 0, v[130:131]
	global_load_lds_dwordx4 v[216:217], off
	v_lshl_add_u64 v[216:217], s[54:55], 0, v[128:129]
	s_add_i32 m0, s56, 0x2000
	s_nop 0
	global_load_lds_dwordx4 v[216:217], off
	v_lshl_add_u64 v[216:217], s[34:35], 0, v[134:135]
	s_mov_b32 m0, s27
	s_nop 0
	global_load_lds_dwordx4 v[216:217], off
	s_mov_b32 m0, s39
	s_nop 0
	global_load_lds_dwordx4 v[218:219], off
	s_waitcnt vmcnt(8)
	s_waitcnt lgkmcnt(0)
	s_barrier
; #define PG8_STAGE(bufoff, gbase, voff) do { _Pragma("unroll") for (int _i = 0; _i < 2; ++_i) \
;         __builtin_amdgcn_global_load_lds((const unsigned*)((const char*)(gbase) + (voff)[_i]), (LAS unsigned*)(lds + (bufoff) + ldsw + _i * 8192), 16, 0, 0); } while (0)
; #define PG8_LDA(dst, b, h) do { _Pragma("unroll") for (int m = 0; m < 4; ++m) _Pragma("unroll") for (int k = 0; k < 2; ++k) dst[m][k] = *(const LAS bf16x8*)(lds + PG8_SA(b, h) + aoff + m * 2048 + k * 1024); } while (0)
; #define PG8_LDB(dst, b, h) do { _Pragma("unroll") for (int n = 0; n < 2; ++n) _Pragma("unroll") for (int k = 0; k < 2; ++k) dst[n][k] = *(const LAS bf16x8*)(lds + PG8_SB(b, h) + boff + n * 2048 + k * 1024); } while (0)
; #define PG8_MMA(ai, bj, At, Bt) do { __builtin_amdgcn_s_setprio(1); _Pragma("unroll") for (int m = 0; m < 4; ++m) _Pragma("unroll") for (int n = 0; n < 2; ++n) _Pragma("unroll") for (int k = 0; k < 2; ++k) \
;         acc[ai][bj][m][n] = __builtin_amdgcn_mfma_f32_16x16x32_bf16(Bt[n][k], At[m][k], acc[ai][bj][m][n], 0, 0, 0); __builtin_amdgcn_s_setprio(0); } while (0)
; #define PG8_WAIT_V(n) asm volatile("s_waitcnt vmcnt(" #n ")" ::: "memory")
; #define PG8_WAIT_L(n) asm volatile("s_waitcnt lgkmcnt(" #n ")" ::: "memory")
; #define PG8_BAR __builtin_amdgcn_s_barrier()
; #define PG8_SCHED __builtin_amdgcn_sched_barrier(0)
; template <class Epi, bool ALIGN_EPI>
; __device__ __forceinline__ void gemm_phase(LAS unsigned char* lds, const Gemm g, const StaticOrder& S, const Epi& E) {
;     ...
;             PG8_WAIT_V(8); PG8_WAIT_L(0); PG8_BAR; PG8_MMA(1, 0, At, B0); PG8_MMA(1, 1, At, B1); PG8_BAR; PG8_SCHED;
;             PG8_LDB(B0, 1, 0); PG8_LDB(B1, 1, 1); PG8_SCHED; PG8_LDA(At, 1, 0); PG8_STAGE(PG8_SA(0, 1), a2 + hA, voffA);
;             PG8_WAIT_V(8); PG8_WAIT_L(0); PG8_BAR; PG8_MMA(0, 0, At, B0); PG8_MMA(0, 1, At, B1); PG8_BAR; PG8_SCHED;
	s_setprio 1
	s_waitcnt lgkmcnt(0)
	v_mfma_f32_16x16x32_bf16 v[60:63], v[148:151], v[180:183], v[60:63]
	v_mfma_f32_16x16x32_bf16 v[60:63], v[152:155], v[184:187], v[60:63]
	v_mfma_f32_16x16x32_bf16 v[56:59], v[156:159], v[180:183], v[56:59]
	v_mfma_f32_16x16x32_bf16 v[56:59], v[160:163], v[184:187], v[56:59]
	v_mfma_f32_16x16x32_bf16 v[52:55], v[148:151], v[188:191], v[52:55]
	v_mfma_f32_16x16x32_bf16 v[52:55], v[152:155], v[194:197], v[52:55]
	v_mfma_f32_16x16x32_bf16 v[44:47], v[156:159], v[188:191], v[44:47]
	v_mfma_f32_16x16x32_bf16 v[44:47], v[160:163], v[194:197], v[44:47]
	v_mfma_f32_16x16x32_bf16 v[36:39], v[148:151], v[198:201], v[36:39]
	v_mfma_f32_16x16x32_bf16 v[36:39], v[152:155], v[202:205], v[36:39]
	v_mfma_f32_16x16x32_bf16 v[28:31], v[156:159], v[198:201], v[28:31]
	v_mfma_f32_16x16x32_bf16 v[28:31], v[160:163], v[202:205], v[28:31]
	v_mfma_f32_16x16x32_bf16 v[20:23], v[148:151], v[206:209], v[20:23]
	v_mfma_f32_16x16x32_bf16 v[20:23], v[152:155], v[210:213], v[20:23]
	v_mfma_f32_16x16x32_bf16 v[12:15], v[156:159], v[206:209], v[12:15]
	v_mfma_f32_16x16x32_bf16 v[12:15], v[160:163], v[210:213], v[12:15]
	v_mfma_f32_16x16x32_bf16 v[48:51], v[164:167], v[180:183], v[48:51]
	v_mfma_f32_16x16x32_bf16 v[48:51], v[168:171], v[184:187], v[48:51]
	v_mfma_f32_16x16x32_bf16 v[40:43], v[172:175], v[180:183], v[40:43]
	v_mfma_f32_16x16x32_bf16 v[40:43], v[176:179], v[184:187], v[40:43]
	v_mfma_f32_16x16x32_bf16 v[32:35], v[164:167], v[188:191], v[32:35]
	v_mfma_f32_16x16x32_bf16 v[32:35], v[168:171], v[194:197], v[32:35]
	v_mfma_f32_16x16x32_bf16 v[24:27], v[172:175], v[188:191], v[24:27]
	v_mfma_f32_16x16x32_bf16 v[24:27], v[176:179], v[194:197], v[24:27]
	v_mfma_f32_16x16x32_bf16 v[16:19], v[164:167], v[198:201], v[16:19]
	v_mfma_f32_16x16x32_bf16 v[16:19], v[168:171], v[202:205], v[16:19]
	v_mfma_f32_16x16x32_bf16 v[8:11], v[172:175], v[198:201], v[8:11]
	v_mfma_f32_16x16x32_bf16 v[8:11], v[176:179], v[202:205], v[8:11]
	v_mfma_f32_16x16x32_bf16 v[4:7], v[164:167], v[206:209], v[4:7]
	v_mfma_f32_16x16x32_bf16 v[4:7], v[168:171], v[210:213], v[4:7]
	v_mfma_f32_16x16x32_bf16 v[0:3], v[172:175], v[206:209], v[0:3]
	v_mfma_f32_16x16x32_bf16 v[0:3], v[176:179], v[210:213], v[0:3]
	s_setprio 0
	s_barrier
	s_add_i32 s54, 0, 0x18000
	s_add_i32 s55, 0, 0x1c000
	v_add_u32_e32 v160, s54, v143
	v_add_u32_e32 v176, s55, v143
	ds_read_b128 v[148:151], v160
	ds_read_b128 v[152:155], v160 offset:1024
	ds_read_b128 v[156:159], v160 offset:2048
	ds_read_b128 v[160:163], v160 offset:3072
	ds_read_b128 v[164:167], v176
	ds_read_b128 v[168:171], v176 offset:1024
	ds_read_b128 v[172:175], v176 offset:2048
	ds_read_b128 v[176:179], v176 offset:3072
	s_add_u32 s34, s34, 0x80000
	s_addc_u32 s35, s35, 0
	s_mov_b32 m0, s40
	v_lshl_add_u64 v[220:221], s[34:35], 0, v[134:135]
	ds_read_b128 v[180:183], v147 offset:32768
	ds_read_b128 v[184:187], v147 offset:33792
	ds_read_b128 v[188:191], v147 offset:34816
	ds_read_b128 v[194:197], v147 offset:35840
	ds_read_b128 v[198:201], v147 offset:36864
	ds_read_b128 v[202:205], v147 offset:37888
	ds_read_b128 v[206:209], v147 offset:38912
	ds_read_b128 v[210:213], v147 offset:39936
	global_load_lds_dwordx4 v[220:221], off
	v_lshl_add_u64 v[220:221], s[34:35], 0, v[130:131]
	s_mov_b32 m0, s41
	s_nop 0
	global_load_lds_dwordx4 v[220:221], off
	s_waitcnt vmcnt(8)
	s_waitcnt lgkmcnt(0)
	s_barrier
	s_setprio 1
	s_waitcnt lgkmcnt(0)
	v_mfma_f32_16x16x32_bf16 v[124:127], v[148:151], v[180:183], v[124:127]
	v_mfma_f32_16x16x32_bf16 v[124:127], v[152:155], v[184:187], v[124:127]
	v_mfma_f32_16x16x32_bf16 v[120:123], v[156:159], v[180:183], v[120:123]
	v_mfma_f32_16x16x32_bf16 v[120:123], v[160:163], v[184:187], v[120:123]
	v_mfma_f32_16x16x32_bf16 v[116:119], v[148:151], v[188:191], v[116:119]
	v_mfma_f32_16x16x32_bf16 v[116:119], v[152:155], v[194:197], v[116:119]
	v_mfma_f32_16x16x32_bf16 v[108:111], v[156:159], v[188:191], v[108:111]
	v_mfma_f32_16x16x32_bf16 v[108:111], v[160:163], v[194:197], v[108:111]
	v_mfma_f32_16x16x32_bf16 v[100:103], v[148:151], v[198:201], v[100:103]
	v_mfma_f32_16x16x32_bf16 v[100:103], v[152:155], v[202:205], v[100:103]
	v_mfma_f32_16x16x32_bf16 v[92:95], v[156:159], v[198:201], v[92:95]
	v_mfma_f32_16x16x32_bf16 v[92:95], v[160:163], v[202:205], v[92:95]
	v_mfma_f32_16x16x32_bf16 v[84:87], v[148:151], v[206:209], v[84:87]
	v_mfma_f32_16x16x32_bf16 v[84:87], v[152:155], v[210:213], v[84:87]
	v_mfma_f32_16x16x32_bf16 v[76:79], v[156:159], v[206:209], v[76:79]
	v_mfma_f32_16x16x32_bf16 v[76:79], v[160:163], v[210:213], v[76:79]
	v_mfma_f32_16x16x32_bf16 v[112:115], v[164:167], v[180:183], v[112:115]
	v_mfma_f32_16x16x32_bf16 v[112:115], v[168:171], v[184:187], v[112:115]
	v_mfma_f32_16x16x32_bf16 v[104:107], v[172:175], v[180:183], v[104:107]
	v_mfma_f32_16x16x32_bf16 v[104:107], v[176:179], v[184:187], v[104:107]
	v_mfma_f32_16x16x32_bf16 v[96:99], v[164:167], v[188:191], v[96:99]
	v_mfma_f32_16x16x32_bf16 v[96:99], v[168:171], v[194:197], v[96:99]
	v_mfma_f32_16x16x32_bf16 v[88:91], v[172:175], v[188:191], v[88:91]
	v_mfma_f32_16x16x32_bf16 v[88:91], v[176:179], v[194:197], v[88:91]
	v_mfma_f32_16x16x32_bf16 v[80:83], v[164:167], v[198:201], v[80:83]
	v_mfma_f32_16x16x32_bf16 v[80:83], v[168:171], v[202:205], v[80:83]
	v_mfma_f32_16x16x32_bf16 v[72:75], v[172:175], v[198:201], v[72:75]
	v_mfma_f32_16x16x32_bf16 v[72:75], v[176:179], v[202:205], v[72:75]
	v_mfma_f32_16x16x32_bf16 v[68:71], v[164:167], v[206:209], v[68:71]
	v_mfma_f32_16x16x32_bf16 v[68:71], v[168:171], v[210:213], v[68:71]
	v_mfma_f32_16x16x32_bf16 v[64:67], v[172:175], v[206:209], v[64:67]
	v_mfma_f32_16x16x32_bf16 v[64:67], v[176:179], v[210:213], v[64:67]
	s_setprio 0
	s_barrier
; #define PG8_STAGE(bufoff, gbase, voff) do { _Pragma("unroll") for (int _i = 0; _i < 2; ++_i) \
;         __builtin_amdgcn_global_load_lds((const unsigned*)((const char*)(gbase) + (voff)[_i]), (LAS unsigned*)(lds + (bufoff) + ldsw + _i * 8192), 16, 0, 0); } while (0)
; #define PG8_LDA(dst, b, h) do { _Pragma("unroll") for (int m = 0; m < 4; ++m) _Pragma("unroll") for (int k = 0; k < 2; ++k) dst[m][k] = *(const LAS bf16x8*)(lds + PG8_SA(b, h) + aoff + m * 2048 + k * 1024); } while (0)
; #define PG8_MMA(ai, bj, At, Bt) do { __builtin_amdgcn_s_setprio(1); _Pragma("unroll") for (int m = 0; m < 4; ++m) _Pragma("unroll") for (int n = 0; n < 2; ++n) _Pragma("unroll") for (int k = 0; k < 2; ++k) \
;         acc[ai][bj][m][n] = __builtin_amdgcn_mfma_f32_16x16x32_bf16(Bt[n][k], At[m][k], acc[ai][bj][m][n], 0, 0, 0); __builtin_amdgcn_s_setprio(0); } while (0)
; #define PG8_WAIT_V(n) asm volatile("s_waitcnt vmcnt(" #n ")" ::: "memory")
; #define PG8_WAIT_L(n) asm volatile("s_waitcnt lgkmcnt(" #n ")" ::: "memory")
; #define PG8_BAR __builtin_amdgcn_s_barrier()
; #define PG8_SCHED __builtin_amdgcn_sched_barrier(0)
; template <class Epi, bool ALIGN_EPI>
; __device__ __forceinline__ void gemm_phase(LAS unsigned char* lds, const Gemm g, const StaticOrder& S, const Epi& E) {
;     ...
;             PG8_LDA(At, 1, 1); PG8_STAGE(PG8_SB(1, 0), b3, voffB); PG8_STAGE(PG8_SB(1, 1), b3 + hB, voffB); PG8_STAGE(PG8_SA(1, 0), a3, voffA);
;             PG8_WAIT_V(8); PG8_WAIT_L(0); PG8_BAR; PG8_MMA(1, 0, At, B0); PG8_MMA(1, 1, At, B1); PG8_BAR; PG8_SCHED;
;         }
	s_add_i32 s34, s54, s1
	v_lshl_add_u64 v[140:141], v[140:141], 0, s[10:11]
	s_mov_b32 m0, s34
	ds_read_b128 v[180:183], v147 offset:49152
	ds_read_b128 v[184:187], v147 offset:50176
	ds_read_b128 v[188:191], v147 offset:51200
	ds_read_b128 v[194:197], v147 offset:52224
	ds_read_b128 v[198:201], v147 offset:53248
	ds_read_b128 v[202:205], v147 offset:54272
	ds_read_b128 v[206:209], v147 offset:55296
	ds_read_b128 v[210:213], v147 offset:56320
	global_load_lds_dwordx4 v[140:141], off
	s_add_i32 m0, s34, 0x2000
	s_add_u32 s30, s30, 0x80080
	v_lshl_add_u64 v[140:141], v[214:215], 0, s[10:11]
	s_addc_u32 s31, s31, 0
	s_add_i32 s34, s55, s1
	global_load_lds_dwordx4 v[140:141], off
	v_lshl_add_u64 v[140:141], s[30:31], 0, v[132:133]
	s_mov_b32 m0, s34
	s_nop 0
	global_load_lds_dwordx4 v[140:141], off
	v_lshl_add_u64 v[140:141], s[30:31], 0, v[128:129]
	s_add_i32 m0, s34, 0x2000
	s_nop 0
	global_load_lds_dwordx4 v[140:141], off
	v_lshl_add_u64 v[140:141], v[216:217], 0, s[10:11]
	s_mov_b32 m0, s42
	s_nop 0
	global_load_lds_dwordx4 v[140:141], off
	v_lshl_add_u64 v[140:141], v[218:219], 0, s[10:11]
	s_mov_b32 m0, s43
	s_nop 0
	global_load_lds_dwordx4 v[140:141], off
	s_waitcnt vmcnt(8)
	s_waitcnt lgkmcnt(0)
	s_barrier
	s_setprio 1
	s_waitcnt lgkmcnt(0)
	v_mfma_f32_16x16x32_bf16 v[60:63], v[148:151], v[180:183], v[60:63]
	v_mfma_f32_16x16x32_bf16 v[60:63], v[152:155], v[184:187], v[60:63]
	v_mfma_f32_16x16x32_bf16 v[56:59], v[156:159], v[180:183], v[56:59]
	v_mfma_f32_16x16x32_bf16 v[56:59], v[160:163], v[184:187], v[56:59]
	v_mfma_f32_16x16x32_bf16 v[52:55], v[148:151], v[188:191], v[52:55]
	v_mfma_f32_16x16x32_bf16 v[52:55], v[152:155], v[194:197], v[52:55]
	v_mfma_f32_16x16x32_bf16 v[44:47], v[156:159], v[188:191], v[44:47]
	v_mfma_f32_16x16x32_bf16 v[44:47], v[160:163], v[194:197], v[44:47]
	v_mfma_f32_16x16x32_bf16 v[36:39], v[148:151], v[198:201], v[36:39]
	v_mfma_f32_16x16x32_bf16 v[36:39], v[152:155], v[202:205], v[36:39]
	v_mfma_f32_16x16x32_bf16 v[28:31], v[156:159], v[198:201], v[28:31]
	v_mfma_f32_16x16x32_bf16 v[28:31], v[160:163], v[202:205], v[28:31]
	v_mfma_f32_16x16x32_bf16 v[20:23], v[148:151], v[206:209], v[20:23]
	v_mfma_f32_16x16x32_bf16 v[20:23], v[152:155], v[210:213], v[20:23]
	v_mfma_f32_16x16x32_bf16 v[12:15], v[156:159], v[206:209], v[12:15]
	v_mfma_f32_16x16x32_bf16 v[12:15], v[160:163], v[210:213], v[12:15]
	v_mfma_f32_16x16x32_bf16 v[48:51], v[164:167], v[180:183], v[48:51]
	v_mfma_f32_16x16x32_bf16 v[48:51], v[168:171], v[184:187], v[48:51]
	v_mfma_f32_16x16x32_bf16 v[40:43], v[172:175], v[180:183], v[40:43]
	v_mfma_f32_16x16x32_bf16 v[40:43], v[176:179], v[184:187], v[40:43]
	v_mfma_f32_16x16x32_bf16 v[32:35], v[164:167], v[188:191], v[32:35]
	v_mfma_f32_16x16x32_bf16 v[32:35], v[168:171], v[194:197], v[32:35]
	v_mfma_f32_16x16x32_bf16 v[24:27], v[172:175], v[188:191], v[24:27]
	v_mfma_f32_16x16x32_bf16 v[24:27], v[176:179], v[194:197], v[24:27]
	v_mfma_f32_16x16x32_bf16 v[16:19], v[164:167], v[198:201], v[16:19]
	v_mfma_f32_16x16x32_bf16 v[16:19], v[168:171], v[202:205], v[16:19]
	v_mfma_f32_16x16x32_bf16 v[8:11], v[172:175], v[198:201], v[8:11]
	v_mfma_f32_16x16x32_bf16 v[8:11], v[176:179], v[202:205], v[8:11]
	v_mfma_f32_16x16x32_bf16 v[4:7], v[164:167], v[206:209], v[4:7]
	v_mfma_f32_16x16x32_bf16 v[4:7], v[168:171], v[210:213], v[4:7]
	v_mfma_f32_16x16x32_bf16 v[0:3], v[172:175], v[206:209], v[0:3]
	v_mfma_f32_16x16x32_bf16 v[0:3], v[176:179], v[210:213], v[0:3]
	s_setprio 0
	s_barrier
	s_add_i32 s53, s53, 2
	s_add_u32 s28, s28, 0x100
	s_addc_u32 s29, s29, 0
	s_add_u32 s51, s51, 0x100
	s_addc_u32 s52, s52, 0
	s_cmp_gt_u32 s53, 29
	s_cbranch_scc0 .LBB0_419
	s_and_b64 vcc, exec, s[14:15]
	s_cbranch_vccz .LBB0_422
	s_barrier

; #define PG8_STAGE(bufoff, gbase, voff) do { _Pragma("unroll") for (int _i = 0; _i < 2; ++_i) \
;         __builtin_amdgcn_global_load_lds((const unsigned*)((const char*)(gbase) + (voff)[_i]), (LAS unsigned*)(lds + (bufoff) + ldsw + _i * 8192), 16, 0, 0); } while (0)
; #define PG8_LDA(dst, b, h) do { _Pragma("unroll") for (int m = 0; m < 4; ++m) _Pragma("unroll") for (int k = 0; k < 2; ++k) dst[m][k] = *(const LAS bf16x8*)(lds + PG8_SA(b, h) + aoff + m * 2048 + k * 1024); } while (0)
; #define PG8_LDB(dst, b, h) do { _Pragma("unroll") for (int n = 0; n < 2; ++n) _Pragma("unroll") for (int k = 0; k < 2; ++k) dst[n][k] = *(const LAS bf16x8*)(lds + PG8_SB(b, h) + boff + n * 2048 + k * 1024); } while (0)
; #define PG8_MMA(ai, bj, At, Bt) do { __builtin_amdgcn_s_setprio(1); _Pragma("unroll") for (int m = 0; m < 4; ++m) _Pragma("unroll") for (int n = 0; n < 2; ++n) _Pragma("unroll") for (int k = 0; k < 2; ++k) \
;         acc[ai][bj][m][n] = __builtin_amdgcn_mfma_f32_16x16x32_bf16(Bt[n][k], At[m][k], acc[ai][bj][m][n], 0, 0, 0); __builtin_amdgcn_s_setprio(0); } while (0)
; #define PG8_WAIT_V(n) asm volatile("s_waitcnt vmcnt(" #n ")" ::: "memory")
; #define PG8_WAIT_L(n) asm volatile("s_waitcnt lgkmcnt(" #n ")" ::: "memory")
; #define PG8_BAR __builtin_amdgcn_s_barrier()
; #define PG8_SCHED __builtin_amdgcn_sched_barrier(0)
; template <class Epi, bool ALIGN_EPI>
; __device__ __forceinline__ void gemm_phase(LAS unsigned char* lds, const Gemm g, const StaticOrder& S, const Epi& E) {
;     ...
;             const bool last = (t == nt - 2);
;             const char* a1 = cA + (size_t)(t + 1) * kstep;
;             const char* a2 = last ? nA : cA + (size_t)(t + 2) * kstep; const char* b2 = last ? nB : cB + (size_t)(t + 2) * kstep;
;             const char* a3 = a2 + kstep; const char* b3 = b2 + kstep;
;             PG8_LDB(B0, 0, 0); PG8_LDB(B1, 0, 1); PG8_SCHED; PG8_LDA(At, 0, 0); PG8_STAGE(PG8_SA(1, 1), a1 + hA, voffA);
;             PG8_WAIT_V(8); PG8_WAIT_L(0); PG8_BAR; PG8_MMA(0, 0, At, B0); PG8_MMA(0, 1, At, B1); PG8_BAR; PG8_SCHED;
;             PG8_LDA(At, 0, 1); PG8_STAGE(PG8_SB(0, 0), b2, voffB); PG8_STAGE(PG8_SB(0, 1), b2 + hB, voffB); PG8_STAGE(PG8_SA(0, 0), a2, voffA);
;             PG8_WAIT_V(8); PG8_WAIT_L(0); PG8_BAR; PG8_MMA(1, 0, At, B0); PG8_MMA(1, 1, At, B1); PG8_BAR; PG8_SCHED;
.LBB0_775:
	ds_read_b128 v[128:131], v196
	ds_read_b128 v[132:135], v196 offset:1024
	ds_read_b128 v[136:139], v196 offset:2048
	ds_read_b128 v[140:143], v196 offset:3072
	ds_read_b128 v[144:147], v197
	ds_read_b128 v[148:151], v197 offset:1024
	ds_read_b128 v[152:155], v197 offset:2048
	ds_read_b128 v[156:159], v197 offset:3072
	s_add_u32 s37, s40, 0xfff80080
	s_addc_u32 s38, s41, -1
	s_cmp_eq_u32 s29, 28
	s_cselect_b32 s45, s0, s38
	s_cselect_b32 s44, s1, s37
	s_cselect_b32 s43, s2, s27
	s_cselect_b32 s42, s3, s9
	v_lshl_add_u64 v[216:217], s[40:41], 0, v[168:169]
	s_add_i32 m0, s50, 0xc000
	ds_read_b128 v[176:179], v198
	ds_read_b128 v[180:183], v198 offset:1024
	ds_read_b128 v[184:187], v198 offset:2048
	ds_read_b128 v[188:191], v198 offset:3072
	ds_read_b128 v[200:203], v198 offset:4096
	ds_read_b128 v[204:207], v198 offset:5120
	ds_read_b128 v[208:211], v198 offset:6144
	ds_read_b128 v[212:215], v198 offset:7168
	global_load_lds_dwordx4 v[216:217], off
	v_lshl_add_u64 v[216:217], s[40:41], 0, v[170:171]
	s_add_i32 m0, s50, 0xe000
	s_nop 0
	global_load_lds_dwordx4 v[216:217], off
	s_waitcnt vmcnt(8)
	s_waitcnt lgkmcnt(0)
	s_barrier
	s_setprio 1
	s_waitcnt lgkmcnt(0)
	v_mfma_f32_16x16x32_bf16 v[124:127], v[128:131], v[176:179], v[124:127]
	v_mfma_f32_16x16x32_bf16 v[124:127], v[132:135], v[180:183], v[124:127]
	v_mfma_f32_16x16x32_bf16 v[120:123], v[136:139], v[176:179], v[120:123]
	v_mfma_f32_16x16x32_bf16 v[120:123], v[140:143], v[180:183], v[120:123]
	v_mfma_f32_16x16x32_bf16 v[108:111], v[128:131], v[184:187], v[108:111]
	v_mfma_f32_16x16x32_bf16 v[108:111], v[132:135], v[188:191], v[108:111]
	v_mfma_f32_16x16x32_bf16 v[104:107], v[136:139], v[184:187], v[104:107]
	v_mfma_f32_16x16x32_bf16 v[104:107], v[140:143], v[188:191], v[104:107]
	v_mfma_f32_16x16x32_bf16 v[92:95], v[128:131], v[200:203], v[92:95]
	v_mfma_f32_16x16x32_bf16 v[92:95], v[132:135], v[204:207], v[92:95]
	v_mfma_f32_16x16x32_bf16 v[88:91], v[136:139], v[200:203], v[88:91]
	v_mfma_f32_16x16x32_bf16 v[88:91], v[140:143], v[204:207], v[88:91]
	v_mfma_f32_16x16x32_bf16 v[76:79], v[128:131], v[208:211], v[76:79]
	v_mfma_f32_16x16x32_bf16 v[76:79], v[132:135], v[212:215], v[76:79]
	v_mfma_f32_16x16x32_bf16 v[72:75], v[136:139], v[208:211], v[72:75]
	v_mfma_f32_16x16x32_bf16 v[72:75], v[140:143], v[212:215], v[72:75]
	v_mfma_f32_16x16x32_bf16 v[116:119], v[144:147], v[176:179], v[116:119]
	v_mfma_f32_16x16x32_bf16 v[116:119], v[148:151], v[180:183], v[116:119]
	v_mfma_f32_16x16x32_bf16 v[112:115], v[152:155], v[176:179], v[112:115]
	v_mfma_f32_16x16x32_bf16 v[112:115], v[156:159], v[180:183], v[112:115]
	v_mfma_f32_16x16x32_bf16 v[100:103], v[144:147], v[184:187], v[100:103]
	v_mfma_f32_16x16x32_bf16 v[100:103], v[148:151], v[188:191], v[100:103]
	v_mfma_f32_16x16x32_bf16 v[96:99], v[152:155], v[184:187], v[96:99]
	v_mfma_f32_16x16x32_bf16 v[96:99], v[156:159], v[188:191], v[96:99]
	v_mfma_f32_16x16x32_bf16 v[84:87], v[144:147], v[200:203], v[84:87]
	v_mfma_f32_16x16x32_bf16 v[84:87], v[148:151], v[204:207], v[84:87]
	v_mfma_f32_16x16x32_bf16 v[80:83], v[152:155], v[200:203], v[80:83]
	v_mfma_f32_16x16x32_bf16 v[80:83], v[156:159], v[204:207], v[80:83]
	v_mfma_f32_16x16x32_bf16 v[68:71], v[144:147], v[208:211], v[68:71]
	v_mfma_f32_16x16x32_bf16 v[68:71], v[148:151], v[212:215], v[68:71]
	v_mfma_f32_16x16x32_bf16 v[64:67], v[152:155], v[208:211], v[64:67]
	v_mfma_f32_16x16x32_bf16 v[64:67], v[156:159], v[212:215], v[64:67]
	s_setprio 0
	s_barrier
	s_add_i32 s37, s60, s49
	v_lshl_add_u64 v[216:217], s[42:43], 0, v[162:163]
	s_mov_b32 m0, s37
	ds_read_b128 v[176:179], v198 offset:16384
	ds_read_b128 v[180:183], v198 offset:17408
	ds_read_b128 v[184:187], v198 offset:18432
	ds_read_b128 v[188:191], v198 offset:19456
	ds_read_b128 v[200:203], v198 offset:20480
	ds_read_b128 v[204:207], v198 offset:21504
	ds_read_b128 v[208:211], v198 offset:22528
	ds_read_b128 v[212:215], v198 offset:23552
	global_load_lds_dwordx4 v[216:217], off
	s_add_i32 m0, s37, 0x2000
	s_add_u32 s38, s42, 0x80000
	v_lshl_add_u64 v[218:219], s[42:43], 0, v[166:167]
	s_addc_u32 s39, s43, 0
	s_add_i32 s37, s61, s49
	global_load_lds_dwordx4 v[218:219], off
	v_lshl_add_u64 v[220:221], s[38:39], 0, v[162:163]
	s_mov_b32 m0, s37
	v_lshl_add_u64 v[222:223], s[44:45], 0, v[164:165]
	global_load_lds_dwordx4 v[220:221], off
	v_lshl_add_u64 v[220:221], s[38:39], 0, v[166:167]
	s_add_i32 m0, s37, 0x2000
	s_nop 0
	global_load_lds_dwordx4 v[220:221], off
	v_lshl_add_u64 v[220:221], s[44:45], 0, v[160:161]
	s_mov_b32 m0, s50
	s_nop 0
	global_load_lds_dwordx4 v[220:221], off
	s_mov_b32 m0, s51
	s_nop 0
	global_load_lds_dwordx4 v[222:223], off
	s_waitcnt vmcnt(8)
	s_waitcnt lgkmcnt(0)
	s_barrier
; #define PG8_STAGE(bufoff, gbase, voff) do { _Pragma("unroll") for (int _i = 0; _i < 2; ++_i) \
;         __builtin_amdgcn_global_load_lds((const unsigned*)((const char*)(gbase) + (voff)[_i]), (LAS unsigned*)(lds + (bufoff) + ldsw + _i * 8192), 16, 0, 0); } while (0)
; #define PG8_LDA(dst, b, h) do { _Pragma("unroll") for (int m = 0; m < 4; ++m) _Pragma("unroll") for (int k = 0; k < 2; ++k) dst[m][k] = *(const LAS bf16x8*)(lds + PG8_SA(b, h) + aoff + m * 2048 + k * 1024); } while (0)
; #define PG8_LDB(dst, b, h) do { _Pragma("unroll") for (int n = 0; n < 2; ++n) _Pragma("unroll") for (int k = 0; k < 2; ++k) dst[n][k] = *(const LAS bf16x8*)(lds + PG8_SB(b, h) + boff + n * 2048 + k * 1024); } while (0)
; #define PG8_MMA(ai, bj, At, Bt) do { __builtin_amdgcn_s_setprio(1); _Pragma("unroll") for (int m = 0; m < 4; ++m) _Pragma("unroll") for (int n = 0; n < 2; ++n) _Pragma("unroll") for (int k = 0; k < 2; ++k) \
;         acc[ai][bj][m][n] = __builtin_amdgcn_mfma_f32_16x16x32_bf16(Bt[n][k], At[m][k], acc[ai][bj][m][n], 0, 0, 0); __builtin_amdgcn_s_setprio(0); } while (0)
; #define PG8_WAIT_V(n) asm volatile("s_waitcnt vmcnt(" #n ")" ::: "memory")
; #define PG8_WAIT_L(n) asm volatile("s_waitcnt lgkmcnt(" #n ")" ::: "memory")
; #define PG8_BAR __builtin_amdgcn_s_barrier()
; #define PG8_SCHED __builtin_amdgcn_sched_barrier(0)
; template <class Epi, bool ALIGN_EPI>
; __device__ __forceinline__ void gemm_phase(LAS unsigned char* lds, const Gemm g, const StaticOrder& S, const Epi& E) {
;     ...
;             PG8_WAIT_V(8); PG8_WAIT_L(0); PG8_BAR; PG8_MMA(1, 0, At, B0); PG8_MMA(1, 1, At, B1); PG8_BAR; PG8_SCHED;
;             PG8_LDB(B0, 1, 0); PG8_LDB(B1, 1, 1); PG8_SCHED; PG8_LDA(At, 1, 0); PG8_STAGE(PG8_SA(0, 1), a2 + hA, voffA);
;             PG8_WAIT_V(8); PG8_WAIT_L(0); PG8_BAR; PG8_MMA(0, 0, At, B0); PG8_MMA(0, 1, At, B1); PG8_BAR; PG8_SCHED;
	s_setprio 1
	s_waitcnt lgkmcnt(0)
	v_mfma_f32_16x16x32_bf16 v[60:63], v[128:131], v[176:179], v[60:63]
	v_mfma_f32_16x16x32_bf16 v[60:63], v[132:135], v[180:183], v[60:63]
	v_mfma_f32_16x16x32_bf16 v[56:59], v[136:139], v[176:179], v[56:59]
	v_mfma_f32_16x16x32_bf16 v[56:59], v[140:143], v[180:183], v[56:59]
	v_mfma_f32_16x16x32_bf16 v[44:47], v[128:131], v[184:187], v[44:47]
	v_mfma_f32_16x16x32_bf16 v[44:47], v[132:135], v[188:191], v[44:47]
	v_mfma_f32_16x16x32_bf16 v[40:43], v[136:139], v[184:187], v[40:43]
	v_mfma_f32_16x16x32_bf16 v[40:43], v[140:143], v[188:191], v[40:43]
	v_mfma_f32_16x16x32_bf16 v[28:31], v[128:131], v[200:203], v[28:31]
	v_mfma_f32_16x16x32_bf16 v[28:31], v[132:135], v[204:207], v[28:31]
	v_mfma_f32_16x16x32_bf16 v[24:27], v[136:139], v[200:203], v[24:27]
	v_mfma_f32_16x16x32_bf16 v[24:27], v[140:143], v[204:207], v[24:27]
	v_mfma_f32_16x16x32_bf16 v[16:19], v[128:131], v[208:211], v[16:19]
	v_mfma_f32_16x16x32_bf16 v[16:19], v[132:135], v[212:215], v[16:19]
	v_mfma_f32_16x16x32_bf16 v[8:11], v[136:139], v[208:211], v[8:11]
	v_mfma_f32_16x16x32_bf16 v[8:11], v[140:143], v[212:215], v[8:11]
	v_mfma_f32_16x16x32_bf16 v[52:55], v[144:147], v[176:179], v[52:55]
	v_mfma_f32_16x16x32_bf16 v[52:55], v[148:151], v[180:183], v[52:55]
	v_mfma_f32_16x16x32_bf16 v[48:51], v[152:155], v[176:179], v[48:51]
	v_mfma_f32_16x16x32_bf16 v[48:51], v[156:159], v[180:183], v[48:51]
	v_mfma_f32_16x16x32_bf16 v[36:39], v[144:147], v[184:187], v[36:39]
	v_mfma_f32_16x16x32_bf16 v[36:39], v[148:151], v[188:191], v[36:39]
	v_mfma_f32_16x16x32_bf16 v[32:35], v[152:155], v[184:187], v[32:35]
	v_mfma_f32_16x16x32_bf16 v[32:35], v[156:159], v[188:191], v[32:35]
	v_mfma_f32_16x16x32_bf16 v[20:23], v[144:147], v[200:203], v[20:23]
	v_mfma_f32_16x16x32_bf16 v[20:23], v[148:151], v[204:207], v[20:23]
	v_mfma_f32_16x16x32_bf16 v[12:15], v[152:155], v[200:203], v[12:15]
	v_mfma_f32_16x16x32_bf16 v[12:15], v[156:159], v[204:207], v[12:15]
	v_mfma_f32_16x16x32_bf16 v[4:7], v[144:147], v[208:211], v[4:7]
	v_mfma_f32_16x16x32_bf16 v[4:7], v[148:151], v[212:215], v[4:7]
	v_mfma_f32_16x16x32_bf16 v[0:3], v[152:155], v[208:211], v[0:3]
	v_mfma_f32_16x16x32_bf16 v[0:3], v[156:159], v[212:215], v[0:3]
	s_setprio 0
	s_barrier
	s_add_i32 s37, 0, 0x18000
	s_add_i32 s63, 0, 0x1c000
	v_add_u32_e32 v140, s37, v194
	v_add_u32_e32 v156, s63, v194
	ds_read_b128 v[128:131], v140
	ds_read_b128 v[132:135], v140 offset:1024
	ds_read_b128 v[136:139], v140 offset:2048
	ds_read_b128 v[140:143], v140 offset:3072
	ds_read_b128 v[144:147], v156
	ds_read_b128 v[148:151], v156 offset:1024
	ds_read_b128 v[152:155], v156 offset:2048
	ds_read_b128 v[156:159], v156 offset:3072
	s_add_u32 s38, s44, 0x80000
	s_addc_u32 s39, s45, 0
	s_mov_b32 m0, s52
	v_lshl_add_u64 v[224:225], s[38:39], 0, v[160:161]
	ds_read_b128 v[176:179], v198 offset:32768
	ds_read_b128 v[180:183], v198 offset:33792
	ds_read_b128 v[184:187], v198 offset:34816
	ds_read_b128 v[188:191], v198 offset:35840
	ds_read_b128 v[200:203], v198 offset:36864
	ds_read_b128 v[204:207], v198 offset:37888
	ds_read_b128 v[208:211], v198 offset:38912
	ds_read_b128 v[212:215], v198 offset:39936
	global_load_lds_dwordx4 v[224:225], off
	v_lshl_add_u64 v[224:225], s[38:39], 0, v[164:165]
	s_mov_b32 m0, s53
	s_nop 0
	global_load_lds_dwordx4 v[224:225], off
	s_waitcnt vmcnt(8)
	s_waitcnt lgkmcnt(0)
	s_barrier
	s_setprio 1
	s_waitcnt lgkmcnt(0)
	v_mfma_f32_16x16x32_bf16 v[124:127], v[128:131], v[176:179], v[124:127]
	v_mfma_f32_16x16x32_bf16 v[124:127], v[132:135], v[180:183], v[124:127]
	v_mfma_f32_16x16x32_bf16 v[120:123], v[136:139], v[176:179], v[120:123]
	v_mfma_f32_16x16x32_bf16 v[120:123], v[140:143], v[180:183], v[120:123]
	v_mfma_f32_16x16x32_bf16 v[108:111], v[128:131], v[184:187], v[108:111]
	v_mfma_f32_16x16x32_bf16 v[108:111], v[132:135], v[188:191], v[108:111]
	v_mfma_f32_16x16x32_bf16 v[104:107], v[136:139], v[184:187], v[104:107]
	v_mfma_f32_16x16x32_bf16 v[104:107], v[140:143], v[188:191], v[104:107]
	v_mfma_f32_16x16x32_bf16 v[92:95], v[128:131], v[200:203], v[92:95]
	v_mfma_f32_16x16x32_bf16 v[92:95], v[132:135], v[204:207], v[92:95]
	v_mfma_f32_16x16x32_bf16 v[88:91], v[136:139], v[200:203], v[88:91]
	v_mfma_f32_16x16x32_bf16 v[88:91], v[140:143], v[204:207], v[88:91]
	v_mfma_f32_16x16x32_bf16 v[76:79], v[128:131], v[208:211], v[76:79]
	v_mfma_f32_16x16x32_bf16 v[76:79], v[132:135], v[212:215], v[76:79]
	v_mfma_f32_16x16x32_bf16 v[72:75], v[136:139], v[208:211], v[72:75]
	v_mfma_f32_16x16x32_bf16 v[72:75], v[140:143], v[212:215], v[72:75]
	v_mfma_f32_16x16x32_bf16 v[116:119], v[144:147], v[176:179], v[116:119]
	v_mfma_f32_16x16x32_bf16 v[116:119], v[148:151], v[180:183], v[116:119]
	v_mfma_f32_16x16x32_bf16 v[112:115], v[152:155], v[176:179], v[112:115]
	v_mfma_f32_16x16x32_bf16 v[112:115], v[156:159], v[180:183], v[112:115]
	v_mfma_f32_16x16x32_bf16 v[100:103], v[144:147], v[184:187], v[100:103]
	v_mfma_f32_16x16x32_bf16 v[100:103], v[148:151], v[188:191], v[100:103]
	v_mfma_f32_16x16x32_bf16 v[96:99], v[152:155], v[184:187], v[96:99]
	v_mfma_f32_16x16x32_bf16 v[96:99], v[156:159], v[188:191], v[96:99]
	v_mfma_f32_16x16x32_bf16 v[84:87], v[144:147], v[200:203], v[84:87]
	v_mfma_f32_16x16x32_bf16 v[84:87], v[148:151], v[204:207], v[84:87]
	v_mfma_f32_16x16x32_bf16 v[80:83], v[152:155], v[200:203], v[80:83]
	v_mfma_f32_16x16x32_bf16 v[80:83], v[156:159], v[204:207], v[80:83]
	v_mfma_f32_16x16x32_bf16 v[68:71], v[144:147], v[208:211], v[68:71]
	v_mfma_f32_16x16x32_bf16 v[68:71], v[148:151], v[212:215], v[68:71]
	v_mfma_f32_16x16x32_bf16 v[64:67], v[152:155], v[208:211], v[64:67]
	v_mfma_f32_16x16x32_bf16 v[64:67], v[156:159], v[212:215], v[64:67]
	s_setprio 0
	s_barrier
; #define PG8_STAGE(bufoff, gbase, voff) do { _Pragma("unroll") for (int _i = 0; _i < 2; ++_i) \
;         __builtin_amdgcn_global_load_lds((const unsigned*)((const char*)(gbase) + (voff)[_i]), (LAS unsigned*)(lds + (bufoff) + ldsw + _i * 8192), 16, 0, 0); } while (0)
; #define PG8_LDA(dst, b, h) do { _Pragma("unroll") for (int m = 0; m < 4; ++m) _Pragma("unroll") for (int k = 0; k < 2; ++k) dst[m][k] = *(const LAS bf16x8*)(lds + PG8_SA(b, h) + aoff + m * 2048 + k * 1024); } while (0)
; #define PG8_MMA(ai, bj, At, Bt) do { __builtin_amdgcn_s_setprio(1); _Pragma("unroll") for (int m = 0; m < 4; ++m) _Pragma("unroll") for (int n = 0; n < 2; ++n) _Pragma("unroll") for (int k = 0; k < 2; ++k) \
;         acc[ai][bj][m][n] = __builtin_amdgcn_mfma_f32_16x16x32_bf16(Bt[n][k], At[m][k], acc[ai][bj][m][n], 0, 0, 0); __builtin_amdgcn_s_setprio(0); } while (0)
; #define PG8_WAIT_V(n) asm volatile("s_waitcnt vmcnt(" #n ")" ::: "memory")
; #define PG8_WAIT_L(n) asm volatile("s_waitcnt lgkmcnt(" #n ")" ::: "memory")
; #define PG8_BAR __builtin_amdgcn_s_barrier()
; #define PG8_SCHED __builtin_amdgcn_sched_barrier(0)
; template <class Epi, bool ALIGN_EPI>
; __device__ __forceinline__ void gemm_phase(LAS unsigned char* lds, const Gemm g, const StaticOrder& S, const Epi& E) {
;     ...
;             PG8_LDA(At, 1, 1); PG8_STAGE(PG8_SB(1, 0), b3, voffB); PG8_STAGE(PG8_SB(1, 1), b3 + hB, voffB); PG8_STAGE(PG8_SA(1, 0), a3, voffA);
;             PG8_WAIT_V(8); PG8_WAIT_L(0); PG8_BAR; PG8_MMA(1, 0, At, B0); PG8_MMA(1, 1, At, B1); PG8_BAR; PG8_SCHED;
;         }
	s_add_i32 s37, s37, s49
	v_lshl_add_u64 v[216:217], v[216:217], 0, s[20:21]
	s_mov_b32 m0, s37
	ds_read_b128 v[176:179], v198 offset:49152
	ds_read_b128 v[180:183], v198 offset:50176
	ds_read_b128 v[184:187], v198 offset:51200
	ds_read_b128 v[188:191], v198 offset:52224
	ds_read_b128 v[200:203], v198 offset:53248
	ds_read_b128 v[204:207], v198 offset:54272
	ds_read_b128 v[208:211], v198 offset:55296
	ds_read_b128 v[212:215], v198 offset:56320
	global_load_lds_dwordx4 v[216:217], off
	s_add_i32 m0, s37, 0x2000
	s_add_u32 s38, s42, 0x80080
	v_lshl_add_u64 v[216:217], v[218:219], 0, s[20:21]
	s_addc_u32 s39, s43, 0
	s_add_i32 s37, s63, s49
	global_load_lds_dwordx4 v[216:217], off
	v_lshl_add_u64 v[216:217], s[38:39], 0, v[162:163]
	s_mov_b32 m0, s37
	s_nop 0
	global_load_lds_dwordx4 v[216:217], off
	v_lshl_add_u64 v[216:217], s[38:39], 0, v[166:167]
	s_add_i32 m0, s37, 0x2000
	s_nop 0
	global_load_lds_dwordx4 v[216:217], off
	v_lshl_add_u64 v[216:217], v[220:221], 0, s[20:21]
	s_mov_b32 m0, s57
	s_nop 0
	global_load_lds_dwordx4 v[216:217], off
	v_lshl_add_u64 v[216:217], v[222:223], 0, s[20:21]
	s_mov_b32 m0, s58
	s_nop 0
	global_load_lds_dwordx4 v[216:217], off
	s_waitcnt vmcnt(8)
	s_waitcnt lgkmcnt(0)
	s_barrier
	s_setprio 1
	s_waitcnt lgkmcnt(0)
	v_mfma_f32_16x16x32_bf16 v[60:63], v[128:131], v[176:179], v[60:63]
	v_mfma_f32_16x16x32_bf16 v[60:63], v[132:135], v[180:183], v[60:63]
	v_mfma_f32_16x16x32_bf16 v[56:59], v[136:139], v[176:179], v[56:59]
	v_mfma_f32_16x16x32_bf16 v[56:59], v[140:143], v[180:183], v[56:59]
	v_mfma_f32_16x16x32_bf16 v[44:47], v[128:131], v[184:187], v[44:47]
	v_mfma_f32_16x16x32_bf16 v[44:47], v[132:135], v[188:191], v[44:47]
	v_mfma_f32_16x16x32_bf16 v[40:43], v[136:139], v[184:187], v[40:43]
	v_mfma_f32_16x16x32_bf16 v[40:43], v[140:143], v[188:191], v[40:43]
	v_mfma_f32_16x16x32_bf16 v[28:31], v[128:131], v[200:203], v[28:31]
	v_mfma_f32_16x16x32_bf16 v[28:31], v[132:135], v[204:207], v[28:31]
	v_mfma_f32_16x16x32_bf16 v[24:27], v[136:139], v[200:203], v[24:27]
	v_mfma_f32_16x16x32_bf16 v[24:27], v[140:143], v[204:207], v[24:27]
	v_mfma_f32_16x16x32_bf16 v[16:19], v[128:131], v[208:211], v[16:19]
	v_mfma_f32_16x16x32_bf16 v[16:19], v[132:135], v[212:215], v[16:19]
	v_mfma_f32_16x16x32_bf16 v[8:11], v[136:139], v[208:211], v[8:11]
	v_mfma_f32_16x16x32_bf16 v[8:11], v[140:143], v[212:215], v[8:11]
	v_mfma_f32_16x16x32_bf16 v[52:55], v[144:147], v[176:179], v[52:55]
	v_mfma_f32_16x16x32_bf16 v[52:55], v[148:151], v[180:183], v[52:55]
	v_mfma_f32_16x16x32_bf16 v[48:51], v[152:155], v[176:179], v[48:51]
	v_mfma_f32_16x16x32_bf16 v[48:51], v[156:159], v[180:183], v[48:51]
	v_mfma_f32_16x16x32_bf16 v[36:39], v[144:147], v[184:187], v[36:39]
	v_mfma_f32_16x16x32_bf16 v[36:39], v[148:151], v[188:191], v[36:39]
	v_mfma_f32_16x16x32_bf16 v[32:35], v[152:155], v[184:187], v[32:35]
	v_mfma_f32_16x16x32_bf16 v[32:35], v[156:159], v[188:191], v[32:35]
	v_mfma_f32_16x16x32_bf16 v[20:23], v[144:147], v[200:203], v[20:23]
	v_mfma_f32_16x16x32_bf16 v[20:23], v[148:151], v[204:207], v[20:23]
	v_mfma_f32_16x16x32_bf16 v[12:15], v[152:155], v[200:203], v[12:15]
	v_mfma_f32_16x16x32_bf16 v[12:15], v[156:159], v[204:207], v[12:15]
	v_mfma_f32_16x16x32_bf16 v[4:7], v[144:147], v[208:211], v[4:7]
	v_mfma_f32_16x16x32_bf16 v[4:7], v[148:151], v[212:215], v[4:7]
	v_mfma_f32_16x16x32_bf16 v[0:3], v[152:155], v[208:211], v[0:3]
	v_mfma_f32_16x16x32_bf16 v[0:3], v[156:159], v[212:215], v[0:3]
	s_setprio 0
	s_barrier
	s_add_i32 s29, s29, 2
	s_add_u32 s40, s40, 0x100
	s_addc_u32 s41, s41, 0
	s_add_u32 s9, s9, 0x100
	s_addc_u32 s27, s27, 0
	s_cmp_gt_u32 s29, 29
	s_cbranch_scc0 .LBB0_775
	s_and_b64 vcc, exec, s[22:23]
	s_cbranch_vccz .LBB0_778
	s_barrier

; #define PG8_STAGE(bufoff, gbase, voff) do { _Pragma("unroll") for (int _i = 0; _i < 2; ++_i) \
;         __builtin_amdgcn_global_load_lds((const unsigned*)((const char*)(gbase) + (voff)[_i]), (LAS unsigned*)(lds + (bufoff) + ldsw + _i * 8192), 16, 0, 0); } while (0)
; #define PG8_LDA(dst, b, h) do { _Pragma("unroll") for (int m = 0; m < 4; ++m) _Pragma("unroll") for (int k = 0; k < 2; ++k) dst[m][k] = *(const LAS bf16x8*)(lds + PG8_SA(b, h) + aoff + m * 2048 + k * 1024); } while (0)
; #define PG8_LDB(dst, b, h) do { _Pragma("unroll") for (int n = 0; n < 2; ++n) _Pragma("unroll") for (int k = 0; k < 2; ++k) dst[n][k] = *(const LAS bf16x8*)(lds + PG8_SB(b, h) + boff + n * 2048 + k * 1024); } while (0)
; #define PG8_MMA(ai, bj, At, Bt) do { __builtin_amdgcn_s_setprio(1); _Pragma("unroll") for (int m = 0; m < 4; ++m) _Pragma("unroll") for (int n = 0; n < 2; ++n) _Pragma("unroll") for (int k = 0; k < 2; ++k) \
;         acc[ai][bj][m][n] = __builtin_amdgcn_mfma_f32_16x16x32_bf16(Bt[n][k], At[m][k], acc[ai][bj][m][n], 0, 0, 0); __builtin_amdgcn_s_setprio(0); } while (0)
; #define PG8_WAIT_V(n) asm volatile("s_waitcnt vmcnt(" #n ")" ::: "memory")
; #define PG8_WAIT_L(n) asm volatile("s_waitcnt lgkmcnt(" #n ")" ::: "memory")
; #define PG8_BAR __builtin_amdgcn_s_barrier()
; #define PG8_SCHED __builtin_amdgcn_sched_barrier(0)
; template <class Epi, bool ALIGN_EPI>
; __device__ __forceinline__ void gemm_phase(LAS unsigned char* lds, const Gemm g, const StaticOrder& S, const Epi& E) {
;     ...
;             const bool last = (t == nt - 2);
;             const char* a1 = cA + (size_t)(t + 1) * kstep;
;             const char* a2 = last ? nA : cA + (size_t)(t + 2) * kstep; const char* b2 = last ? nB : cB + (size_t)(t + 2) * kstep;
;             const char* a3 = a2 + kstep; const char* b3 = b2 + kstep;
;             PG8_LDB(B0, 0, 0); PG8_LDB(B1, 0, 1); PG8_SCHED; PG8_LDA(At, 0, 0); PG8_STAGE(PG8_SA(1, 1), a1 + hA, voffA);
;             PG8_WAIT_V(8); PG8_WAIT_L(0); PG8_BAR; PG8_MMA(0, 0, At, B0); PG8_MMA(0, 1, At, B1); PG8_BAR; PG8_SCHED;
;             PG8_LDA(At, 0, 1); PG8_STAGE(PG8_SB(0, 0), b2, voffB); PG8_STAGE(PG8_SB(0, 1), b2 + hB, voffB); PG8_STAGE(PG8_SA(0, 0), a2, voffA);
;             PG8_WAIT_V(8); PG8_WAIT_L(0); PG8_BAR; PG8_MMA(1, 0, At, B0); PG8_MMA(1, 1, At, B1); PG8_BAR; PG8_SCHED;
.LBB0_926:
	ds_read_b128 v[168:171], v153
	ds_read_b128 v[172:175], v153 offset:1024
	ds_read_b128 v[176:179], v153 offset:2048
	ds_read_b128 v[180:183], v153 offset:3072
	ds_read_b128 v[184:187], v155
	ds_read_b128 v[188:191], v155 offset:1024
	ds_read_b128 v[194:197], v155 offset:2048
	ds_read_b128 v[198:201], v155 offset:3072
	s_add_u32 s8, s6, 0xfff80080
	s_addc_u32 s9, s7, -1
	s_cmp_eq_u32 s71, 28
	s_cselect_b32 s55, s47, s9
	s_cselect_b32 s54, s67, s8
	s_cselect_b32 s9, s45, s70
	s_cselect_b32 s8, s68, s69
	v_lshl_add_u64 v[234:235], s[6:7], 0, v[136:137]
	s_add_i32 m0, s39, 0xc000
	ds_read_b128 v[202:205], v156
	ds_read_b128 v[206:209], v156 offset:1024
	ds_read_b128 v[210:213], v156 offset:2048
	ds_read_b128 v[214:217], v156 offset:3072
	ds_read_b128 v[218:221], v156 offset:4096
	ds_read_b128 v[222:225], v156 offset:5120
	ds_read_b128 v[226:229], v156 offset:6144
	ds_read_b128 v[230:233], v156 offset:7168
	global_load_lds_dwordx4 v[234:235], off
	v_lshl_add_u64 v[234:235], s[6:7], 0, v[138:139]
	s_add_i32 m0, s39, 0xe000
	s_nop 0
	global_load_lds_dwordx4 v[234:235], off
	s_waitcnt vmcnt(8)
	s_waitcnt lgkmcnt(0)
	s_barrier
	s_setprio 1
	s_waitcnt lgkmcnt(0)
	v_mfma_f32_16x16x32_bf16 v[124:127], v[168:171], v[202:205], v[124:127]
	v_mfma_f32_16x16x32_bf16 v[124:127], v[172:175], v[206:209], v[124:127]
	v_mfma_f32_16x16x32_bf16 v[120:123], v[176:179], v[202:205], v[120:123]
	v_mfma_f32_16x16x32_bf16 v[120:123], v[180:183], v[206:209], v[120:123]
	v_mfma_f32_16x16x32_bf16 v[108:111], v[168:171], v[210:213], v[108:111]
	v_mfma_f32_16x16x32_bf16 v[108:111], v[172:175], v[214:217], v[108:111]
	v_mfma_f32_16x16x32_bf16 v[104:107], v[176:179], v[210:213], v[104:107]
	v_mfma_f32_16x16x32_bf16 v[104:107], v[180:183], v[214:217], v[104:107]
	v_mfma_f32_16x16x32_bf16 v[92:95], v[168:171], v[218:221], v[92:95]
	v_mfma_f32_16x16x32_bf16 v[92:95], v[172:175], v[222:225], v[92:95]
	v_mfma_f32_16x16x32_bf16 v[88:91], v[176:179], v[218:221], v[88:91]
	v_mfma_f32_16x16x32_bf16 v[88:91], v[180:183], v[222:225], v[88:91]
	v_mfma_f32_16x16x32_bf16 v[76:79], v[168:171], v[226:229], v[76:79]
	v_mfma_f32_16x16x32_bf16 v[76:79], v[172:175], v[230:233], v[76:79]
	v_mfma_f32_16x16x32_bf16 v[72:75], v[176:179], v[226:229], v[72:75]
	v_mfma_f32_16x16x32_bf16 v[72:75], v[180:183], v[230:233], v[72:75]
	v_mfma_f32_16x16x32_bf16 v[116:119], v[184:187], v[202:205], v[116:119]
	v_mfma_f32_16x16x32_bf16 v[116:119], v[188:191], v[206:209], v[116:119]
	v_mfma_f32_16x16x32_bf16 v[112:115], v[194:197], v[202:205], v[112:115]
	v_mfma_f32_16x16x32_bf16 v[112:115], v[198:201], v[206:209], v[112:115]
	v_mfma_f32_16x16x32_bf16 v[100:103], v[184:187], v[210:213], v[100:103]
	v_mfma_f32_16x16x32_bf16 v[100:103], v[188:191], v[214:217], v[100:103]
	v_mfma_f32_16x16x32_bf16 v[96:99], v[194:197], v[210:213], v[96:99]
	v_mfma_f32_16x16x32_bf16 v[96:99], v[198:201], v[214:217], v[96:99]
	v_mfma_f32_16x16x32_bf16 v[84:87], v[184:187], v[218:221], v[84:87]
	v_mfma_f32_16x16x32_bf16 v[84:87], v[188:191], v[222:225], v[84:87]
	v_mfma_f32_16x16x32_bf16 v[80:83], v[194:197], v[218:221], v[80:83]
	v_mfma_f32_16x16x32_bf16 v[80:83], v[198:201], v[222:225], v[80:83]
	v_mfma_f32_16x16x32_bf16 v[68:71], v[184:187], v[226:229], v[68:71]
	v_mfma_f32_16x16x32_bf16 v[68:71], v[188:191], v[230:233], v[68:71]
	v_mfma_f32_16x16x32_bf16 v[64:67], v[194:197], v[226:229], v[64:67]
	v_mfma_f32_16x16x32_bf16 v[64:67], v[198:201], v[230:233], v[64:67]
	s_setprio 0
	s_barrier
	s_add_i32 s72, s63, s33
	v_lshl_add_u64 v[234:235], s[8:9], 0, v[132:133]
	s_mov_b32 m0, s72
	ds_read_b128 v[202:205], v156 offset:16384
	ds_read_b128 v[206:209], v156 offset:17408
	ds_read_b128 v[210:213], v156 offset:18432
	ds_read_b128 v[214:217], v156 offset:19456
	ds_read_b128 v[218:221], v156 offset:20480
	ds_read_b128 v[222:225], v156 offset:21504
	ds_read_b128 v[226:229], v156 offset:22528
	ds_read_b128 v[230:233], v156 offset:23552
	global_load_lds_dwordx4 v[234:235], off
	s_add_i32 m0, s72, 0x2000
	s_add_u32 s72, s8, 0x80000
	v_lshl_add_u64 v[236:237], s[8:9], 0, v[128:129]
	s_addc_u32 s73, s9, 0
	s_add_i32 s74, s64, s33
	global_load_lds_dwordx4 v[236:237], off
	v_lshl_add_u64 v[238:239], s[72:73], 0, v[132:133]
	s_mov_b32 m0, s74
	v_lshl_add_u64 v[240:241], s[54:55], 0, v[130:131]
	global_load_lds_dwordx4 v[238:239], off
	v_lshl_add_u64 v[238:239], s[72:73], 0, v[128:129]
	s_add_i32 m0, s74, 0x2000
	s_nop 0
	global_load_lds_dwordx4 v[238:239], off
	v_lshl_add_u64 v[238:239], s[54:55], 0, v[134:135]
	s_mov_b32 m0, s39
	s_nop 0
	global_load_lds_dwordx4 v[238:239], off
	s_mov_b32 m0, s53
	s_nop 0
	global_load_lds_dwordx4 v[240:241], off
	s_waitcnt vmcnt(8)
	s_waitcnt lgkmcnt(0)
	s_barrier
; #define PG8_STAGE(bufoff, gbase, voff) do { _Pragma("unroll") for (int _i = 0; _i < 2; ++_i) \
;         __builtin_amdgcn_global_load_lds((const unsigned*)((const char*)(gbase) + (voff)[_i]), (LAS unsigned*)(lds + (bufoff) + ldsw + _i * 8192), 16, 0, 0); } while (0)
; #define PG8_LDA(dst, b, h) do { _Pragma("unroll") for (int m = 0; m < 4; ++m) _Pragma("unroll") for (int k = 0; k < 2; ++k) dst[m][k] = *(const LAS bf16x8*)(lds + PG8_SA(b, h) + aoff + m * 2048 + k * 1024); } while (0)
; #define PG8_LDB(dst, b, h) do { _Pragma("unroll") for (int n = 0; n < 2; ++n) _Pragma("unroll") for (int k = 0; k < 2; ++k) dst[n][k] = *(const LAS bf16x8*)(lds + PG8_SB(b, h) + boff + n * 2048 + k * 1024); } while (0)
; #define PG8_MMA(ai, bj, At, Bt) do { __builtin_amdgcn_s_setprio(1); _Pragma("unroll") for (int m = 0; m < 4; ++m) _Pragma("unroll") for (int n = 0; n < 2; ++n) _Pragma("unroll") for (int k = 0; k < 2; ++k) \
;         acc[ai][bj][m][n] = __builtin_amdgcn_mfma_f32_16x16x32_bf16(Bt[n][k], At[m][k], acc[ai][bj][m][n], 0, 0, 0); __builtin_amdgcn_s_setprio(0); } while (0)
; #define PG8_WAIT_V(n) asm volatile("s_waitcnt vmcnt(" #n ")" ::: "memory")
; #define PG8_WAIT_L(n) asm volatile("s_waitcnt lgkmcnt(" #n ")" ::: "memory")
; #define PG8_BAR __builtin_amdgcn_s_barrier()
; #define PG8_SCHED __builtin_amdgcn_sched_barrier(0)
; template <class Epi, bool ALIGN_EPI>
; __device__ __forceinline__ void gemm_phase(LAS unsigned char* lds, const Gemm g, const StaticOrder& S, const Epi& E) {
;     ...
;             PG8_WAIT_V(8); PG8_WAIT_L(0); PG8_BAR; PG8_MMA(1, 0, At, B0); PG8_MMA(1, 1, At, B1); PG8_BAR; PG8_SCHED;
;             PG8_LDB(B0, 1, 0); PG8_LDB(B1, 1, 1); PG8_SCHED; PG8_LDA(At, 1, 0); PG8_STAGE(PG8_SA(0, 1), a2 + hA, voffA);
;             PG8_WAIT_V(8); PG8_WAIT_L(0); PG8_BAR; PG8_MMA(0, 0, At, B0); PG8_MMA(0, 1, At, B1); PG8_BAR; PG8_SCHED;
	s_setprio 1
	s_waitcnt lgkmcnt(0)
	v_mfma_f32_16x16x32_bf16 v[60:63], v[168:171], v[202:205], v[60:63]
	v_mfma_f32_16x16x32_bf16 v[60:63], v[172:175], v[206:209], v[60:63]
	v_mfma_f32_16x16x32_bf16 v[56:59], v[176:179], v[202:205], v[56:59]
	v_mfma_f32_16x16x32_bf16 v[56:59], v[180:183], v[206:209], v[56:59]
	v_mfma_f32_16x16x32_bf16 v[44:47], v[168:171], v[210:213], v[44:47]
	v_mfma_f32_16x16x32_bf16 v[44:47], v[172:175], v[214:217], v[44:47]
	v_mfma_f32_16x16x32_bf16 v[40:43], v[176:179], v[210:213], v[40:43]
	v_mfma_f32_16x16x32_bf16 v[40:43], v[180:183], v[214:217], v[40:43]
	v_mfma_f32_16x16x32_bf16 v[28:31], v[168:171], v[218:221], v[28:31]
	v_mfma_f32_16x16x32_bf16 v[28:31], v[172:175], v[222:225], v[28:31]
	v_mfma_f32_16x16x32_bf16 v[24:27], v[176:179], v[218:221], v[24:27]
	v_mfma_f32_16x16x32_bf16 v[24:27], v[180:183], v[222:225], v[24:27]
	v_mfma_f32_16x16x32_bf16 v[12:15], v[168:171], v[226:229], v[12:15]
	v_mfma_f32_16x16x32_bf16 v[12:15], v[172:175], v[230:233], v[12:15]
	v_mfma_f32_16x16x32_bf16 v[8:11], v[176:179], v[226:229], v[8:11]
	v_mfma_f32_16x16x32_bf16 v[8:11], v[180:183], v[230:233], v[8:11]
	v_mfma_f32_16x16x32_bf16 v[52:55], v[184:187], v[202:205], v[52:55]
	v_mfma_f32_16x16x32_bf16 v[52:55], v[188:191], v[206:209], v[52:55]
	v_mfma_f32_16x16x32_bf16 v[48:51], v[194:197], v[202:205], v[48:51]
	v_mfma_f32_16x16x32_bf16 v[48:51], v[198:201], v[206:209], v[48:51]
	v_mfma_f32_16x16x32_bf16 v[36:39], v[184:187], v[210:213], v[36:39]
	v_mfma_f32_16x16x32_bf16 v[36:39], v[188:191], v[214:217], v[36:39]
	v_mfma_f32_16x16x32_bf16 v[32:35], v[194:197], v[210:213], v[32:35]
	v_mfma_f32_16x16x32_bf16 v[32:35], v[198:201], v[214:217], v[32:35]
	v_mfma_f32_16x16x32_bf16 v[20:23], v[184:187], v[218:221], v[20:23]
	v_mfma_f32_16x16x32_bf16 v[20:23], v[188:191], v[222:225], v[20:23]
	v_mfma_f32_16x16x32_bf16 v[16:19], v[194:197], v[218:221], v[16:19]
	v_mfma_f32_16x16x32_bf16 v[16:19], v[198:201], v[222:225], v[16:19]
	v_mfma_f32_16x16x32_bf16 v[4:7], v[184:187], v[226:229], v[4:7]
	v_mfma_f32_16x16x32_bf16 v[4:7], v[188:191], v[230:233], v[4:7]
	v_mfma_f32_16x16x32_bf16 v[0:3], v[194:197], v[226:229], v[0:3]
	v_mfma_f32_16x16x32_bf16 v[0:3], v[198:201], v[230:233], v[0:3]
	s_setprio 0
	s_barrier
	s_add_i32 s72, 0, 0x18000
	v_add_u32_e32 v167, s72, v149
	s_add_i32 s73, 0, 0x1c000
	ds_read_b128 v[168:171], v167
	ds_read_b128 v[172:175], v167 offset:1024
	ds_read_b128 v[176:179], v167 offset:2048
	ds_read_b128 v[180:183], v167 offset:3072
	v_add_u32_e32 v167, s73, v149
	ds_read_b128 v[184:187], v167
	ds_read_b128 v[188:191], v167 offset:1024
	ds_read_b128 v[194:197], v167 offset:2048
	ds_read_b128 v[198:201], v167 offset:3072
	s_add_u32 s54, s54, 0x80000
	s_addc_u32 s55, s55, 0
	s_mov_b32 m0, s56
	v_lshl_add_u64 v[242:243], s[54:55], 0, v[134:135]
	ds_read_b128 v[202:205], v156 offset:32768
	ds_read_b128 v[206:209], v156 offset:33792
	ds_read_b128 v[210:213], v156 offset:34816
	ds_read_b128 v[214:217], v156 offset:35840
	ds_read_b128 v[218:221], v156 offset:36864
	ds_read_b128 v[222:225], v156 offset:37888
	ds_read_b128 v[226:229], v156 offset:38912
	ds_read_b128 v[230:233], v156 offset:39936
	global_load_lds_dwordx4 v[242:243], off
	v_lshl_add_u64 v[242:243], s[54:55], 0, v[130:131]
	s_mov_b32 m0, s57
	s_nop 0
	global_load_lds_dwordx4 v[242:243], off
	s_waitcnt vmcnt(8)
	s_waitcnt lgkmcnt(0)
	s_barrier
	s_setprio 1
	s_waitcnt lgkmcnt(0)
	v_mfma_f32_16x16x32_bf16 v[124:127], v[168:171], v[202:205], v[124:127]
	v_mfma_f32_16x16x32_bf16 v[124:127], v[172:175], v[206:209], v[124:127]
	v_mfma_f32_16x16x32_bf16 v[120:123], v[176:179], v[202:205], v[120:123]
	v_mfma_f32_16x16x32_bf16 v[120:123], v[180:183], v[206:209], v[120:123]
	v_mfma_f32_16x16x32_bf16 v[108:111], v[168:171], v[210:213], v[108:111]
	v_mfma_f32_16x16x32_bf16 v[108:111], v[172:175], v[214:217], v[108:111]
	v_mfma_f32_16x16x32_bf16 v[104:107], v[176:179], v[210:213], v[104:107]
	v_mfma_f32_16x16x32_bf16 v[104:107], v[180:183], v[214:217], v[104:107]
	v_mfma_f32_16x16x32_bf16 v[92:95], v[168:171], v[218:221], v[92:95]
	v_mfma_f32_16x16x32_bf16 v[92:95], v[172:175], v[222:225], v[92:95]
	v_mfma_f32_16x16x32_bf16 v[88:91], v[176:179], v[218:221], v[88:91]
	v_mfma_f32_16x16x32_bf16 v[88:91], v[180:183], v[222:225], v[88:91]
	v_mfma_f32_16x16x32_bf16 v[76:79], v[168:171], v[226:229], v[76:79]
	v_mfma_f32_16x16x32_bf16 v[76:79], v[172:175], v[230:233], v[76:79]
	v_mfma_f32_16x16x32_bf16 v[72:75], v[176:179], v[226:229], v[72:75]
	v_mfma_f32_16x16x32_bf16 v[72:75], v[180:183], v[230:233], v[72:75]
	v_mfma_f32_16x16x32_bf16 v[116:119], v[184:187], v[202:205], v[116:119]
	v_mfma_f32_16x16x32_bf16 v[116:119], v[188:191], v[206:209], v[116:119]
	v_mfma_f32_16x16x32_bf16 v[112:115], v[194:197], v[202:205], v[112:115]
	v_mfma_f32_16x16x32_bf16 v[112:115], v[198:201], v[206:209], v[112:115]
	v_mfma_f32_16x16x32_bf16 v[100:103], v[184:187], v[210:213], v[100:103]
	v_mfma_f32_16x16x32_bf16 v[100:103], v[188:191], v[214:217], v[100:103]
	v_mfma_f32_16x16x32_bf16 v[96:99], v[194:197], v[210:213], v[96:99]
	v_mfma_f32_16x16x32_bf16 v[96:99], v[198:201], v[214:217], v[96:99]
	v_mfma_f32_16x16x32_bf16 v[84:87], v[184:187], v[218:221], v[84:87]
	v_mfma_f32_16x16x32_bf16 v[84:87], v[188:191], v[222:225], v[84:87]
	v_mfma_f32_16x16x32_bf16 v[80:83], v[194:197], v[218:221], v[80:83]
	v_mfma_f32_16x16x32_bf16 v[80:83], v[198:201], v[222:225], v[80:83]
	v_mfma_f32_16x16x32_bf16 v[68:71], v[184:187], v[226:229], v[68:71]
	v_mfma_f32_16x16x32_bf16 v[68:71], v[188:191], v[230:233], v[68:71]
	v_mfma_f32_16x16x32_bf16 v[64:67], v[194:197], v[226:229], v[64:67]
	v_mfma_f32_16x16x32_bf16 v[64:67], v[198:201], v[230:233], v[64:67]
	s_setprio 0
	s_barrier
; #define PG8_STAGE(bufoff, gbase, voff) do { _Pragma("unroll") for (int _i = 0; _i < 2; ++_i) \
;         __builtin_amdgcn_global_load_lds((const unsigned*)((const char*)(gbase) + (voff)[_i]), (LAS unsigned*)(lds + (bufoff) + ldsw + _i * 8192), 16, 0, 0); } while (0)
; #define PG8_LDA(dst, b, h) do { _Pragma("unroll") for (int m = 0; m < 4; ++m) _Pragma("unroll") for (int k = 0; k < 2; ++k) dst[m][k] = *(const LAS bf16x8*)(lds + PG8_SA(b, h) + aoff + m * 2048 + k * 1024); } while (0)
; #define PG8_MMA(ai, bj, At, Bt) do { __builtin_amdgcn_s_setprio(1); _Pragma("unroll") for (int m = 0; m < 4; ++m) _Pragma("unroll") for (int n = 0; n < 2; ++n) _Pragma("unroll") for (int k = 0; k < 2; ++k) \
;         acc[ai][bj][m][n] = __builtin_amdgcn_mfma_f32_16x16x32_bf16(Bt[n][k], At[m][k], acc[ai][bj][m][n], 0, 0, 0); __builtin_amdgcn_s_setprio(0); } while (0)
; #define PG8_WAIT_V(n) asm volatile("s_waitcnt vmcnt(" #n ")" ::: "memory")
; #define PG8_WAIT_L(n) asm volatile("s_waitcnt lgkmcnt(" #n ")" ::: "memory")
; #define PG8_BAR __builtin_amdgcn_s_barrier()
; #define PG8_SCHED __builtin_amdgcn_sched_barrier(0)
; template <class Epi, bool ALIGN_EPI>
; __device__ __forceinline__ void gemm_phase(LAS unsigned char* lds, const Gemm g, const StaticOrder& S, const Epi& E) {
;     ...
;             PG8_LDA(At, 1, 1); PG8_STAGE(PG8_SB(1, 0), b3, voffB); PG8_STAGE(PG8_SB(1, 1), b3 + hB, voffB); PG8_STAGE(PG8_SA(1, 0), a3, voffA);
;             PG8_WAIT_V(8); PG8_WAIT_L(0); PG8_BAR; PG8_MMA(1, 0, At, B0); PG8_MMA(1, 1, At, B1); PG8_BAR; PG8_SCHED;
;         }
	s_add_i32 s54, s72, s33
	v_lshl_add_u64 v[234:235], v[234:235], 0, s[18:19]
	s_mov_b32 m0, s54
	ds_read_b128 v[202:205], v156 offset:49152
	ds_read_b128 v[206:209], v156 offset:50176
	ds_read_b128 v[210:213], v156 offset:51200
	ds_read_b128 v[214:217], v156 offset:52224
	ds_read_b128 v[218:221], v156 offset:53248
	ds_read_b128 v[222:225], v156 offset:54272
	ds_read_b128 v[226:229], v156 offset:55296
	ds_read_b128 v[230:233], v156 offset:56320
	global_load_lds_dwordx4 v[234:235], off
	s_add_i32 m0, s54, 0x2000
	s_add_u32 s8, s8, 0x80080
	v_lshl_add_u64 v[234:235], v[236:237], 0, s[18:19]
	s_addc_u32 s9, s9, 0
	s_add_i32 s54, s73, s33
	global_load_lds_dwordx4 v[234:235], off
	v_lshl_add_u64 v[234:235], s[8:9], 0, v[132:133]
	s_mov_b32 m0, s54
	s_nop 0
	global_load_lds_dwordx4 v[234:235], off
	v_lshl_add_u64 v[234:235], s[8:9], 0, v[128:129]
	s_add_i32 m0, s54, 0x2000
	s_nop 0
	global_load_lds_dwordx4 v[234:235], off
	v_lshl_add_u64 v[234:235], v[238:239], 0, s[18:19]
	s_mov_b32 m0, s60
	s_nop 0
	global_load_lds_dwordx4 v[234:235], off
	v_lshl_add_u64 v[234:235], v[240:241], 0, s[18:19]
	s_mov_b32 m0, s61
	s_nop 0
	global_load_lds_dwordx4 v[234:235], off
	s_waitcnt vmcnt(8)
	s_waitcnt lgkmcnt(0)
	s_barrier
	s_setprio 1
	s_waitcnt lgkmcnt(0)
	v_mfma_f32_16x16x32_bf16 v[60:63], v[168:171], v[202:205], v[60:63]
	v_mfma_f32_16x16x32_bf16 v[60:63], v[172:175], v[206:209], v[60:63]
	v_mfma_f32_16x16x32_bf16 v[56:59], v[176:179], v[202:205], v[56:59]
	v_mfma_f32_16x16x32_bf16 v[56:59], v[180:183], v[206:209], v[56:59]
	v_mfma_f32_16x16x32_bf16 v[44:47], v[168:171], v[210:213], v[44:47]
	v_mfma_f32_16x16x32_bf16 v[44:47], v[172:175], v[214:217], v[44:47]
	v_mfma_f32_16x16x32_bf16 v[40:43], v[176:179], v[210:213], v[40:43]
	v_mfma_f32_16x16x32_bf16 v[40:43], v[180:183], v[214:217], v[40:43]
	v_mfma_f32_16x16x32_bf16 v[28:31], v[168:171], v[218:221], v[28:31]
	v_mfma_f32_16x16x32_bf16 v[28:31], v[172:175], v[222:225], v[28:31]
	v_mfma_f32_16x16x32_bf16 v[24:27], v[176:179], v[218:221], v[24:27]
	v_mfma_f32_16x16x32_bf16 v[24:27], v[180:183], v[222:225], v[24:27]
	v_mfma_f32_16x16x32_bf16 v[12:15], v[168:171], v[226:229], v[12:15]
	v_mfma_f32_16x16x32_bf16 v[12:15], v[172:175], v[230:233], v[12:15]
	v_mfma_f32_16x16x32_bf16 v[8:11], v[176:179], v[226:229], v[8:11]
	v_mfma_f32_16x16x32_bf16 v[8:11], v[180:183], v[230:233], v[8:11]
	v_mfma_f32_16x16x32_bf16 v[52:55], v[184:187], v[202:205], v[52:55]
	v_mfma_f32_16x16x32_bf16 v[52:55], v[188:191], v[206:209], v[52:55]
	v_mfma_f32_16x16x32_bf16 v[48:51], v[194:197], v[202:205], v[48:51]
	v_mfma_f32_16x16x32_bf16 v[48:51], v[198:201], v[206:209], v[48:51]
	v_mfma_f32_16x16x32_bf16 v[36:39], v[184:187], v[210:213], v[36:39]
	v_mfma_f32_16x16x32_bf16 v[36:39], v[188:191], v[214:217], v[36:39]
	v_mfma_f32_16x16x32_bf16 v[32:35], v[194:197], v[210:213], v[32:35]
	v_mfma_f32_16x16x32_bf16 v[32:35], v[198:201], v[214:217], v[32:35]
	v_mfma_f32_16x16x32_bf16 v[20:23], v[184:187], v[218:221], v[20:23]
	v_mfma_f32_16x16x32_bf16 v[20:23], v[188:191], v[222:225], v[20:23]
	v_mfma_f32_16x16x32_bf16 v[16:19], v[194:197], v[218:221], v[16:19]
	v_mfma_f32_16x16x32_bf16 v[16:19], v[198:201], v[222:225], v[16:19]
	v_mfma_f32_16x16x32_bf16 v[4:7], v[184:187], v[226:229], v[4:7]
	v_mfma_f32_16x16x32_bf16 v[4:7], v[188:191], v[230:233], v[4:7]
	v_mfma_f32_16x16x32_bf16 v[0:3], v[194:197], v[226:229], v[0:3]
	v_mfma_f32_16x16x32_bf16 v[0:3], v[198:201], v[230:233], v[0:3]
	s_setprio 0
	s_barrier
	s_add_i32 s71, s71, 2
	s_add_u32 s6, s6, 0x100
	s_addc_u32 s7, s7, 0
	s_add_u32 s69, s69, 0x100
	s_addc_u32 s70, s70, 0
	s_cmp_gt_u32 s71, 29
	s_cbranch_scc0 .LBB0_926
	s_and_b64 vcc, exec, s[20:21]
	s_cbranch_vccz .LBB0_929
	s_barrier

; #define PG8_STAGE(bufoff, gbase, voff) do { _Pragma("unroll") for (int _i = 0; _i < 2; ++_i) \
;         __builtin_amdgcn_global_load_lds((const unsigned*)((const char*)(gbase) + (voff)[_i]), (LAS unsigned*)(lds + (bufoff) + ldsw + _i * 8192), 16, 0, 0); } while (0)
; #define PG8_LDA(dst, b, h) do { _Pragma("unroll") for (int m = 0; m < 4; ++m) _Pragma("unroll") for (int k = 0; k < 2; ++k) dst[m][k] = *(const LAS bf16x8*)(lds + PG8_SA(b, h) + aoff + m * 2048 + k * 1024); } while (0)
; #define PG8_LDB(dst, b, h) do { _Pragma("unroll") for (int n = 0; n < 2; ++n) _Pragma("unroll") for (int k = 0; k < 2; ++k) dst[n][k] = *(const LAS bf16x8*)(lds + PG8_SB(b, h) + boff + n * 2048 + k * 1024); } while (0)
; #define PG8_MMA(ai, bj, At, Bt) do { __builtin_amdgcn_s_setprio(1); _Pragma("unroll") for (int m = 0; m < 4; ++m) _Pragma("unroll") for (int n = 0; n < 2; ++n) _Pragma("unroll") for (int k = 0; k < 2; ++k) \
;         acc[ai][bj][m][n] = __builtin_amdgcn_mfma_f32_16x16x32_bf16(Bt[n][k], At[m][k], acc[ai][bj][m][n], 0, 0, 0); __builtin_amdgcn_s_setprio(0); } while (0)
; #define PG8_WAIT_V(n) asm volatile("s_waitcnt vmcnt(" #n ")" ::: "memory")
; #define PG8_WAIT_L(n) asm volatile("s_waitcnt lgkmcnt(" #n ")" ::: "memory")
; #define PG8_BAR __builtin_amdgcn_s_barrier()
; #define PG8_SCHED __builtin_amdgcn_sched_barrier(0)
; template <class Epi, bool ALIGN_EPI>
; __device__ __forceinline__ void gemm_phase(LAS unsigned char* lds, const Gemm g, const StaticOrder& S, const Epi& E) {
;     ...
;             const bool last = (t == nt - 2);
;             const char* a1 = cA + (size_t)(t + 1) * kstep;
;             const char* a2 = last ? nA : cA + (size_t)(t + 2) * kstep; const char* b2 = last ? nB : cB + (size_t)(t + 2) * kstep;
;             const char* a3 = a2 + kstep; const char* b3 = b2 + kstep;
;             PG8_LDB(B0, 0, 0); PG8_LDB(B1, 0, 1); PG8_SCHED; PG8_LDA(At, 0, 0); PG8_STAGE(PG8_SA(1, 1), a1 + hA, voffA);
;             PG8_WAIT_V(8); PG8_WAIT_L(0); PG8_BAR; PG8_MMA(0, 0, At, B0); PG8_MMA(0, 1, At, B1); PG8_BAR; PG8_SCHED;
;             PG8_LDA(At, 0, 1); PG8_STAGE(PG8_SB(0, 0), b2, voffB); PG8_STAGE(PG8_SB(0, 1), b2 + hB, voffB); PG8_STAGE(PG8_SA(0, 0), a2, voffA);
;             PG8_WAIT_V(8); PG8_WAIT_L(0); PG8_BAR; PG8_MMA(1, 0, At, B0); PG8_MMA(1, 1, At, B1); PG8_BAR; PG8_SCHED;
.LBB0_1005:
	ds_read_b128 v[128:131], v175
	ds_read_b128 v[132:135], v175 offset:1024
	ds_read_b128 v[136:139], v175 offset:2048
	ds_read_b128 v[140:143], v175 offset:3072
	ds_read_b128 v[160:163], v176
	ds_read_b128 v[164:167], v176 offset:1024
	ds_read_b128 v[168:171], v176 offset:2048
	ds_read_b128 v[180:183], v176 offset:3072
	s_add_u32 s40, s36, 0xffe00080
	s_addc_u32 s41, s37, -1
	s_cmpk_eq_i32 s57, 0x7c
	s_cselect_b32 s43, s25, s41
	s_cselect_b32 s42, s31, s40
	s_cselect_b32 s41, s23, s56
	s_cselect_b32 s40, s54, s55
	v_lshl_add_u64 v[218:219], s[36:37], 0, v[152:153]
	s_add_i32 m0, s35, 0xc000
	ds_read_b128 v[184:187], v177
	ds_read_b128 v[188:191], v177 offset:1024
	ds_read_b128 v[194:197], v177 offset:2048
	ds_read_b128 v[198:201], v177 offset:3072
	ds_read_b128 v[202:205], v177 offset:4096
	ds_read_b128 v[206:209], v177 offset:5120
	ds_read_b128 v[210:213], v177 offset:6144
	ds_read_b128 v[214:217], v177 offset:7168
	global_load_lds_dwordx4 v[218:219], off
	v_lshl_add_u64 v[218:219], s[36:37], 0, v[154:155]
	s_add_i32 m0, s35, 0xe000
	s_nop 0
	global_load_lds_dwordx4 v[218:219], off
	s_waitcnt vmcnt(8)
	s_waitcnt lgkmcnt(0)
	s_barrier
	s_setprio 1
	s_waitcnt lgkmcnt(0)
	v_mfma_f32_16x16x32_bf16 v[124:127], v[128:131], v[184:187], v[124:127]
	v_mfma_f32_16x16x32_bf16 v[124:127], v[132:135], v[188:191], v[124:127]
	v_mfma_f32_16x16x32_bf16 v[120:123], v[136:139], v[184:187], v[120:123]
	v_mfma_f32_16x16x32_bf16 v[120:123], v[140:143], v[188:191], v[120:123]
	v_mfma_f32_16x16x32_bf16 v[112:115], v[128:131], v[194:197], v[112:115]
	v_mfma_f32_16x16x32_bf16 v[112:115], v[132:135], v[198:201], v[112:115]
	v_mfma_f32_16x16x32_bf16 v[104:107], v[136:139], v[194:197], v[104:107]
	v_mfma_f32_16x16x32_bf16 v[104:107], v[140:143], v[198:201], v[104:107]
	v_mfma_f32_16x16x32_bf16 v[92:95], v[128:131], v[202:205], v[92:95]
	v_mfma_f32_16x16x32_bf16 v[92:95], v[132:135], v[206:209], v[92:95]
	v_mfma_f32_16x16x32_bf16 v[88:91], v[136:139], v[202:205], v[88:91]
	v_mfma_f32_16x16x32_bf16 v[88:91], v[140:143], v[206:209], v[88:91]
	v_mfma_f32_16x16x32_bf16 v[76:79], v[128:131], v[210:213], v[76:79]
	v_mfma_f32_16x16x32_bf16 v[76:79], v[132:135], v[214:217], v[76:79]
	v_mfma_f32_16x16x32_bf16 v[72:75], v[136:139], v[210:213], v[72:75]
	v_mfma_f32_16x16x32_bf16 v[72:75], v[140:143], v[214:217], v[72:75]
	v_mfma_f32_16x16x32_bf16 v[116:119], v[160:163], v[184:187], v[116:119]
	v_mfma_f32_16x16x32_bf16 v[116:119], v[164:167], v[188:191], v[116:119]
	v_mfma_f32_16x16x32_bf16 v[108:111], v[168:171], v[184:187], v[108:111]
	v_mfma_f32_16x16x32_bf16 v[108:111], v[180:183], v[188:191], v[108:111]
	v_mfma_f32_16x16x32_bf16 v[100:103], v[160:163], v[194:197], v[100:103]
	v_mfma_f32_16x16x32_bf16 v[100:103], v[164:167], v[198:201], v[100:103]
	v_mfma_f32_16x16x32_bf16 v[96:99], v[168:171], v[194:197], v[96:99]
	v_mfma_f32_16x16x32_bf16 v[96:99], v[180:183], v[198:201], v[96:99]
	v_mfma_f32_16x16x32_bf16 v[84:87], v[160:163], v[202:205], v[84:87]
	v_mfma_f32_16x16x32_bf16 v[84:87], v[164:167], v[206:209], v[84:87]
	v_mfma_f32_16x16x32_bf16 v[80:83], v[168:171], v[202:205], v[80:83]
	v_mfma_f32_16x16x32_bf16 v[80:83], v[180:183], v[206:209], v[80:83]
	v_mfma_f32_16x16x32_bf16 v[68:71], v[160:163], v[210:213], v[68:71]
	v_mfma_f32_16x16x32_bf16 v[68:71], v[164:167], v[214:217], v[68:71]
	v_mfma_f32_16x16x32_bf16 v[64:67], v[168:171], v[210:213], v[64:67]
	v_mfma_f32_16x16x32_bf16 v[64:67], v[180:183], v[214:217], v[64:67]
	s_setprio 0
	s_barrier
	s_add_i32 s58, s51, s33
	v_lshl_add_u64 v[218:219], s[40:41], 0, v[146:147]
	s_mov_b32 m0, s58
	ds_read_b128 v[184:187], v177 offset:16384
	ds_read_b128 v[188:191], v177 offset:17408
	ds_read_b128 v[194:197], v177 offset:18432
	ds_read_b128 v[198:201], v177 offset:19456
	ds_read_b128 v[202:205], v177 offset:20480
	ds_read_b128 v[206:209], v177 offset:21504
	ds_read_b128 v[210:213], v177 offset:22528
	ds_read_b128 v[214:217], v177 offset:23552
	global_load_lds_dwordx4 v[218:219], off
	s_add_i32 m0, s58, 0x2000
	s_add_u32 s58, s40, 0x200000
	v_lshl_add_u64 v[220:221], s[40:41], 0, v[150:151]
	s_addc_u32 s59, s41, 0
	s_add_i32 s60, s52, s33
	global_load_lds_dwordx4 v[220:221], off
	v_lshl_add_u64 v[222:223], s[58:59], 0, v[146:147]
	s_mov_b32 m0, s60
	v_lshl_add_u64 v[224:225], s[42:43], 0, v[148:149]
	global_load_lds_dwordx4 v[222:223], off
	v_lshl_add_u64 v[222:223], s[58:59], 0, v[150:151]
	s_add_i32 m0, s60, 0x2000
	s_nop 0
	global_load_lds_dwordx4 v[222:223], off
	v_lshl_add_u64 v[222:223], s[42:43], 0, v[144:145]
	s_mov_b32 m0, s35
	s_nop 0
	global_load_lds_dwordx4 v[222:223], off
	s_mov_b32 m0, s38
	s_nop 0
	global_load_lds_dwordx4 v[224:225], off
	s_waitcnt vmcnt(8)
	s_waitcnt lgkmcnt(0)
	s_barrier
; #define PG8_STAGE(bufoff, gbase, voff) do { _Pragma("unroll") for (int _i = 0; _i < 2; ++_i) \
;         __builtin_amdgcn_global_load_lds((const unsigned*)((const char*)(gbase) + (voff)[_i]), (LAS unsigned*)(lds + (bufoff) + ldsw + _i * 8192), 16, 0, 0); } while (0)
; #define PG8_LDA(dst, b, h) do { _Pragma("unroll") for (int m = 0; m < 4; ++m) _Pragma("unroll") for (int k = 0; k < 2; ++k) dst[m][k] = *(const LAS bf16x8*)(lds + PG8_SA(b, h) + aoff + m * 2048 + k * 1024); } while (0)
; #define PG8_LDB(dst, b, h) do { _Pragma("unroll") for (int n = 0; n < 2; ++n) _Pragma("unroll") for (int k = 0; k < 2; ++k) dst[n][k] = *(const LAS bf16x8*)(lds + PG8_SB(b, h) + boff + n * 2048 + k * 1024); } while (0)
; #define PG8_MMA(ai, bj, At, Bt) do { __builtin_amdgcn_s_setprio(1); _Pragma("unroll") for (int m = 0; m < 4; ++m) _Pragma("unroll") for (int n = 0; n < 2; ++n) _Pragma("unroll") for (int k = 0; k < 2; ++k) \
;         acc[ai][bj][m][n] = __builtin_amdgcn_mfma_f32_16x16x32_bf16(Bt[n][k], At[m][k], acc[ai][bj][m][n], 0, 0, 0); __builtin_amdgcn_s_setprio(0); } while (0)
; #define PG8_WAIT_V(n) asm volatile("s_waitcnt vmcnt(" #n ")" ::: "memory")
; #define PG8_WAIT_L(n) asm volatile("s_waitcnt lgkmcnt(" #n ")" ::: "memory")
; #define PG8_BAR __builtin_amdgcn_s_barrier()
; #define PG8_SCHED __builtin_amdgcn_sched_barrier(0)
; template <class Epi, bool ALIGN_EPI>
; __device__ __forceinline__ void gemm_phase(LAS unsigned char* lds, const Gemm g, const StaticOrder& S, const Epi& E) {
;     ...
;             PG8_WAIT_V(8); PG8_WAIT_L(0); PG8_BAR; PG8_MMA(1, 0, At, B0); PG8_MMA(1, 1, At, B1); PG8_BAR; PG8_SCHED;
;             PG8_LDB(B0, 1, 0); PG8_LDB(B1, 1, 1); PG8_SCHED; PG8_LDA(At, 1, 0); PG8_STAGE(PG8_SA(0, 1), a2 + hA, voffA);
;             PG8_WAIT_V(8); PG8_WAIT_L(0); PG8_BAR; PG8_MMA(0, 0, At, B0); PG8_MMA(0, 1, At, B1); PG8_BAR; PG8_SCHED;
	s_setprio 1
	s_waitcnt lgkmcnt(0)
	v_mfma_f32_16x16x32_bf16 v[60:63], v[128:131], v[184:187], v[60:63]
	v_mfma_f32_16x16x32_bf16 v[60:63], v[132:135], v[188:191], v[60:63]
	v_mfma_f32_16x16x32_bf16 v[56:59], v[136:139], v[184:187], v[56:59]
	v_mfma_f32_16x16x32_bf16 v[56:59], v[140:143], v[188:191], v[56:59]
	v_mfma_f32_16x16x32_bf16 v[44:47], v[128:131], v[194:197], v[44:47]
	v_mfma_f32_16x16x32_bf16 v[44:47], v[132:135], v[198:201], v[44:47]
	v_mfma_f32_16x16x32_bf16 v[40:43], v[136:139], v[194:197], v[40:43]
	v_mfma_f32_16x16x32_bf16 v[40:43], v[140:143], v[198:201], v[40:43]
	v_mfma_f32_16x16x32_bf16 v[28:31], v[128:131], v[202:205], v[28:31]
	v_mfma_f32_16x16x32_bf16 v[28:31], v[132:135], v[206:209], v[28:31]
	v_mfma_f32_16x16x32_bf16 v[24:27], v[136:139], v[202:205], v[24:27]
	v_mfma_f32_16x16x32_bf16 v[24:27], v[140:143], v[206:209], v[24:27]
	v_mfma_f32_16x16x32_bf16 v[12:15], v[128:131], v[210:213], v[12:15]
	v_mfma_f32_16x16x32_bf16 v[12:15], v[132:135], v[214:217], v[12:15]
	v_mfma_f32_16x16x32_bf16 v[8:11], v[136:139], v[210:213], v[8:11]
	v_mfma_f32_16x16x32_bf16 v[8:11], v[140:143], v[214:217], v[8:11]
	v_mfma_f32_16x16x32_bf16 v[52:55], v[160:163], v[184:187], v[52:55]
	v_mfma_f32_16x16x32_bf16 v[52:55], v[164:167], v[188:191], v[52:55]
	v_mfma_f32_16x16x32_bf16 v[48:51], v[168:171], v[184:187], v[48:51]
	v_mfma_f32_16x16x32_bf16 v[48:51], v[180:183], v[188:191], v[48:51]
	v_mfma_f32_16x16x32_bf16 v[36:39], v[160:163], v[194:197], v[36:39]
	v_mfma_f32_16x16x32_bf16 v[36:39], v[164:167], v[198:201], v[36:39]
	v_mfma_f32_16x16x32_bf16 v[32:35], v[168:171], v[194:197], v[32:35]
	v_mfma_f32_16x16x32_bf16 v[32:35], v[180:183], v[198:201], v[32:35]
	v_mfma_f32_16x16x32_bf16 v[20:23], v[160:163], v[202:205], v[20:23]
	v_mfma_f32_16x16x32_bf16 v[20:23], v[164:167], v[206:209], v[20:23]
	v_mfma_f32_16x16x32_bf16 v[16:19], v[168:171], v[202:205], v[16:19]
	v_mfma_f32_16x16x32_bf16 v[16:19], v[180:183], v[206:209], v[16:19]
	v_mfma_f32_16x16x32_bf16 v[4:7], v[160:163], v[210:213], v[4:7]
	v_mfma_f32_16x16x32_bf16 v[4:7], v[164:167], v[214:217], v[4:7]
	v_mfma_f32_16x16x32_bf16 v[0:3], v[168:171], v[210:213], v[0:3]
	v_mfma_f32_16x16x32_bf16 v[0:3], v[180:183], v[214:217], v[0:3]
	s_setprio 0
	s_barrier
	s_add_i32 s58, 0, 0x18000
	s_add_i32 s59, 0, 0x1c000
	v_add_u32_e32 v140, s58, v173
	v_add_u32_e32 v179, s59, v173
	ds_read_b128 v[128:131], v140
	ds_read_b128 v[132:135], v140 offset:1024
	ds_read_b128 v[136:139], v140 offset:2048
	ds_read_b128 v[140:143], v140 offset:3072
	ds_read_b128 v[160:163], v179
	ds_read_b128 v[164:167], v179 offset:1024
	ds_read_b128 v[168:171], v179 offset:2048
	ds_read_b128 v[180:183], v179 offset:3072
	s_add_u32 s42, s42, 0x200000
	s_addc_u32 s43, s43, 0
	s_mov_b32 m0, s39
	v_lshl_add_u64 v[226:227], s[42:43], 0, v[144:145]
	ds_read_b128 v[184:187], v177 offset:32768
	ds_read_b128 v[188:191], v177 offset:33792
	ds_read_b128 v[194:197], v177 offset:34816
	ds_read_b128 v[198:201], v177 offset:35840
	ds_read_b128 v[202:205], v177 offset:36864
	ds_read_b128 v[206:209], v177 offset:37888
	ds_read_b128 v[210:213], v177 offset:38912
	ds_read_b128 v[214:217], v177 offset:39936
	global_load_lds_dwordx4 v[226:227], off
	v_lshl_add_u64 v[226:227], s[42:43], 0, v[148:149]
	s_mov_b32 m0, s44
	s_nop 0
	global_load_lds_dwordx4 v[226:227], off
	s_waitcnt vmcnt(8)
	s_waitcnt lgkmcnt(0)
	s_barrier
	s_setprio 1
	s_waitcnt lgkmcnt(0)
	v_mfma_f32_16x16x32_bf16 v[124:127], v[128:131], v[184:187], v[124:127]
	v_mfma_f32_16x16x32_bf16 v[124:127], v[132:135], v[188:191], v[124:127]
	v_mfma_f32_16x16x32_bf16 v[120:123], v[136:139], v[184:187], v[120:123]
	v_mfma_f32_16x16x32_bf16 v[120:123], v[140:143], v[188:191], v[120:123]
	v_mfma_f32_16x16x32_bf16 v[112:115], v[128:131], v[194:197], v[112:115]
	v_mfma_f32_16x16x32_bf16 v[112:115], v[132:135], v[198:201], v[112:115]
	v_mfma_f32_16x16x32_bf16 v[104:107], v[136:139], v[194:197], v[104:107]
	v_mfma_f32_16x16x32_bf16 v[104:107], v[140:143], v[198:201], v[104:107]
	v_mfma_f32_16x16x32_bf16 v[92:95], v[128:131], v[202:205], v[92:95]
	v_mfma_f32_16x16x32_bf16 v[92:95], v[132:135], v[206:209], v[92:95]
	v_mfma_f32_16x16x32_bf16 v[88:91], v[136:139], v[202:205], v[88:91]
	v_mfma_f32_16x16x32_bf16 v[88:91], v[140:143], v[206:209], v[88:91]
	v_mfma_f32_16x16x32_bf16 v[76:79], v[128:131], v[210:213], v[76:79]
	v_mfma_f32_16x16x32_bf16 v[76:79], v[132:135], v[214:217], v[76:79]
	v_mfma_f32_16x16x32_bf16 v[72:75], v[136:139], v[210:213], v[72:75]
	v_mfma_f32_16x16x32_bf16 v[72:75], v[140:143], v[214:217], v[72:75]
	v_mfma_f32_16x16x32_bf16 v[116:119], v[160:163], v[184:187], v[116:119]
	v_mfma_f32_16x16x32_bf16 v[116:119], v[164:167], v[188:191], v[116:119]
	v_mfma_f32_16x16x32_bf16 v[108:111], v[168:171], v[184:187], v[108:111]
	v_mfma_f32_16x16x32_bf16 v[108:111], v[180:183], v[188:191], v[108:111]
	v_mfma_f32_16x16x32_bf16 v[100:103], v[160:163], v[194:197], v[100:103]
	v_mfma_f32_16x16x32_bf16 v[100:103], v[164:167], v[198:201], v[100:103]
	v_mfma_f32_16x16x32_bf16 v[96:99], v[168:171], v[194:197], v[96:99]
	v_mfma_f32_16x16x32_bf16 v[96:99], v[180:183], v[198:201], v[96:99]
	v_mfma_f32_16x16x32_bf16 v[84:87], v[160:163], v[202:205], v[84:87]
	v_mfma_f32_16x16x32_bf16 v[84:87], v[164:167], v[206:209], v[84:87]
	v_mfma_f32_16x16x32_bf16 v[80:83], v[168:171], v[202:205], v[80:83]
	v_mfma_f32_16x16x32_bf16 v[80:83], v[180:183], v[206:209], v[80:83]
	v_mfma_f32_16x16x32_bf16 v[68:71], v[160:163], v[210:213], v[68:71]
	v_mfma_f32_16x16x32_bf16 v[68:71], v[164:167], v[214:217], v[68:71]
	v_mfma_f32_16x16x32_bf16 v[64:67], v[168:171], v[210:213], v[64:67]
	v_mfma_f32_16x16x32_bf16 v[64:67], v[180:183], v[214:217], v[64:67]
	s_setprio 0
	s_barrier
; #define PG8_STAGE(bufoff, gbase, voff) do { _Pragma("unroll") for (int _i = 0; _i < 2; ++_i) \
;         __builtin_amdgcn_global_load_lds((const unsigned*)((const char*)(gbase) + (voff)[_i]), (LAS unsigned*)(lds + (bufoff) + ldsw + _i * 8192), 16, 0, 0); } while (0)
; #define PG8_LDA(dst, b, h) do { _Pragma("unroll") for (int m = 0; m < 4; ++m) _Pragma("unroll") for (int k = 0; k < 2; ++k) dst[m][k] = *(const LAS bf16x8*)(lds + PG8_SA(b, h) + aoff + m * 2048 + k * 1024); } while (0)
; #define PG8_MMA(ai, bj, At, Bt) do { __builtin_amdgcn_s_setprio(1); _Pragma("unroll") for (int m = 0; m < 4; ++m) _Pragma("unroll") for (int n = 0; n < 2; ++n) _Pragma("unroll") for (int k = 0; k < 2; ++k) \
;         acc[ai][bj][m][n] = __builtin_amdgcn_mfma_f32_16x16x32_bf16(Bt[n][k], At[m][k], acc[ai][bj][m][n], 0, 0, 0); __builtin_amdgcn_s_setprio(0); } while (0)
; #define PG8_WAIT_V(n) asm volatile("s_waitcnt vmcnt(" #n ")" ::: "memory")
; #define PG8_WAIT_L(n) asm volatile("s_waitcnt lgkmcnt(" #n ")" ::: "memory")
; #define PG8_BAR __builtin_amdgcn_s_barrier()
; #define PG8_SCHED __builtin_amdgcn_sched_barrier(0)
; template <class Epi, bool ALIGN_EPI>
; __device__ __forceinline__ void gemm_phase(LAS unsigned char* lds, const Gemm g, const StaticOrder& S, const Epi& E) {
;     ...
;             PG8_LDA(At, 1, 1); PG8_STAGE(PG8_SB(1, 0), b3, voffB); PG8_STAGE(PG8_SB(1, 1), b3 + hB, voffB); PG8_STAGE(PG8_SA(1, 0), a3, voffA);
;             PG8_WAIT_V(8); PG8_WAIT_L(0); PG8_BAR; PG8_MMA(1, 0, At, B0); PG8_MMA(1, 1, At, B1); PG8_BAR; PG8_SCHED;
;         }
	s_add_i32 s42, s58, s33
	v_lshl_add_u64 v[218:219], v[218:219], 0, s[16:17]
	s_mov_b32 m0, s42
	ds_read_b128 v[184:187], v177 offset:49152
	ds_read_b128 v[188:191], v177 offset:50176
	ds_read_b128 v[194:197], v177 offset:51200
	ds_read_b128 v[198:201], v177 offset:52224
	ds_read_b128 v[202:205], v177 offset:53248
	ds_read_b128 v[206:209], v177 offset:54272
	ds_read_b128 v[210:213], v177 offset:55296
	ds_read_b128 v[214:217], v177 offset:56320
	global_load_lds_dwordx4 v[218:219], off
	s_add_i32 m0, s42, 0x2000
	s_add_u32 s40, s40, 0x200080
	v_lshl_add_u64 v[218:219], v[220:221], 0, s[16:17]
	s_addc_u32 s41, s41, 0
	s_add_i32 s42, s59, s33
	global_load_lds_dwordx4 v[218:219], off
	v_lshl_add_u64 v[218:219], s[40:41], 0, v[146:147]
	s_mov_b32 m0, s42
	s_nop 0
	global_load_lds_dwordx4 v[218:219], off
	v_lshl_add_u64 v[218:219], s[40:41], 0, v[150:151]
	s_add_i32 m0, s42, 0x2000
	s_nop 0
	global_load_lds_dwordx4 v[218:219], off
	v_lshl_add_u64 v[218:219], v[222:223], 0, s[16:17]
	s_mov_b32 m0, s48
	s_nop 0
	global_load_lds_dwordx4 v[218:219], off
	v_lshl_add_u64 v[218:219], v[224:225], 0, s[16:17]
	s_mov_b32 m0, s49
	s_nop 0
	global_load_lds_dwordx4 v[218:219], off
	s_waitcnt vmcnt(8)
	s_waitcnt lgkmcnt(0)
	s_barrier
	s_setprio 1
	s_waitcnt lgkmcnt(0)
	v_mfma_f32_16x16x32_bf16 v[60:63], v[128:131], v[184:187], v[60:63]
	v_mfma_f32_16x16x32_bf16 v[60:63], v[132:135], v[188:191], v[60:63]
	v_mfma_f32_16x16x32_bf16 v[56:59], v[136:139], v[184:187], v[56:59]
	v_mfma_f32_16x16x32_bf16 v[56:59], v[140:143], v[188:191], v[56:59]
	v_mfma_f32_16x16x32_bf16 v[44:47], v[128:131], v[194:197], v[44:47]
	v_mfma_f32_16x16x32_bf16 v[44:47], v[132:135], v[198:201], v[44:47]
	v_mfma_f32_16x16x32_bf16 v[40:43], v[136:139], v[194:197], v[40:43]
	v_mfma_f32_16x16x32_bf16 v[40:43], v[140:143], v[198:201], v[40:43]
	v_mfma_f32_16x16x32_bf16 v[28:31], v[128:131], v[202:205], v[28:31]
	v_mfma_f32_16x16x32_bf16 v[28:31], v[132:135], v[206:209], v[28:31]
	v_mfma_f32_16x16x32_bf16 v[24:27], v[136:139], v[202:205], v[24:27]
	v_mfma_f32_16x16x32_bf16 v[24:27], v[140:143], v[206:209], v[24:27]
	v_mfma_f32_16x16x32_bf16 v[12:15], v[128:131], v[210:213], v[12:15]
	v_mfma_f32_16x16x32_bf16 v[12:15], v[132:135], v[214:217], v[12:15]
	v_mfma_f32_16x16x32_bf16 v[8:11], v[136:139], v[210:213], v[8:11]
	v_mfma_f32_16x16x32_bf16 v[8:11], v[140:143], v[214:217], v[8:11]
	v_mfma_f32_16x16x32_bf16 v[52:55], v[160:163], v[184:187], v[52:55]
	v_mfma_f32_16x16x32_bf16 v[52:55], v[164:167], v[188:191], v[52:55]
	v_mfma_f32_16x16x32_bf16 v[48:51], v[168:171], v[184:187], v[48:51]
	v_mfma_f32_16x16x32_bf16 v[48:51], v[180:183], v[188:191], v[48:51]
	v_mfma_f32_16x16x32_bf16 v[36:39], v[160:163], v[194:197], v[36:39]
	v_mfma_f32_16x16x32_bf16 v[36:39], v[164:167], v[198:201], v[36:39]
	v_mfma_f32_16x16x32_bf16 v[32:35], v[168:171], v[194:197], v[32:35]
	v_mfma_f32_16x16x32_bf16 v[32:35], v[180:183], v[198:201], v[32:35]
	v_mfma_f32_16x16x32_bf16 v[20:23], v[160:163], v[202:205], v[20:23]
	v_mfma_f32_16x16x32_bf16 v[20:23], v[164:167], v[206:209], v[20:23]
	v_mfma_f32_16x16x32_bf16 v[16:19], v[168:171], v[202:205], v[16:19]
	v_mfma_f32_16x16x32_bf16 v[16:19], v[180:183], v[206:209], v[16:19]
	v_mfma_f32_16x16x32_bf16 v[4:7], v[160:163], v[210:213], v[4:7]
	v_mfma_f32_16x16x32_bf16 v[4:7], v[164:167], v[214:217], v[4:7]
	v_mfma_f32_16x16x32_bf16 v[0:3], v[168:171], v[210:213], v[0:3]
	v_mfma_f32_16x16x32_bf16 v[0:3], v[180:183], v[214:217], v[0:3]
	s_setprio 0
	s_barrier
	s_add_i32 s57, s57, 2
	s_add_u32 s36, s36, 0x100
	s_addc_u32 s37, s37, 0
	s_add_u32 s55, s55, 0x100
	s_addc_u32 s56, s56, 0
	s_cmpk_gt_u32 s57, 0x7d
	s_cbranch_scc0 .LBB0_1005
	s_and_b64 vcc, exec, s[18:19]
	s_cbranch_vccz .LBB0_1008
	s_barrier

; #define PG8_STAGE(bufoff, gbase, voff) do { _Pragma("unroll") for (int _i = 0; _i < 2; ++_i) \
;         __builtin_amdgcn_global_load_lds((const unsigned*)((const char*)(gbase) + (voff)[_i]), (LAS unsigned*)(lds + (bufoff) + ldsw + _i * 8192), 16, 0, 0); } while (0)
; #define PG8_LDA(dst, b, h) do { _Pragma("unroll") for (int m = 0; m < 4; ++m) _Pragma("unroll") for (int k = 0; k < 2; ++k) dst[m][k] = *(const LAS bf16x8*)(lds + PG8_SA(b, h) + aoff + m * 2048 + k * 1024); } while (0)
; #define PG8_LDB(dst, b, h) do { _Pragma("unroll") for (int n = 0; n < 2; ++n) _Pragma("unroll") for (int k = 0; k < 2; ++k) dst[n][k] = *(const LAS bf16x8*)(lds + PG8_SB(b, h) + boff + n * 2048 + k * 1024); } while (0)
; #define PG8_MMA(ai, bj, At, Bt) do { __builtin_amdgcn_s_setprio(1); _Pragma("unroll") for (int m = 0; m < 4; ++m) _Pragma("unroll") for (int n = 0; n < 2; ++n) _Pragma("unroll") for (int k = 0; k < 2; ++k) \
;         acc[ai][bj][m][n] = __builtin_amdgcn_mfma_f32_16x16x32_bf16(Bt[n][k], At[m][k], acc[ai][bj][m][n], 0, 0, 0); __builtin_amdgcn_s_setprio(0); } while (0)
; #define PG8_WAIT_V(n) asm volatile("s_waitcnt vmcnt(" #n ")" ::: "memory")
; #define PG8_WAIT_L(n) asm volatile("s_waitcnt lgkmcnt(" #n ")" ::: "memory")
; #define PG8_BAR __builtin_amdgcn_s_barrier()
; #define PG8_SCHED __builtin_amdgcn_sched_barrier(0)
; template <class Epi, bool ALIGN_EPI>
; __device__ __forceinline__ void gemm_phase(LAS unsigned char* lds, const Gemm g, const StaticOrder& S, const Epi& E) {
;     ...
;             const bool last = (t == nt - 2);
;             const char* a1 = cA + (size_t)(t + 1) * kstep;
;             const char* a2 = last ? nA : cA + (size_t)(t + 2) * kstep; const char* b2 = last ? nB : cB + (size_t)(t + 2) * kstep;
;             const char* a3 = a2 + kstep; const char* b3 = b2 + kstep;
;             PG8_LDB(B0, 0, 0); PG8_LDB(B1, 0, 1); PG8_SCHED; PG8_LDA(At, 0, 0); PG8_STAGE(PG8_SA(1, 1), a1 + hA, voffA);
;             PG8_WAIT_V(8); PG8_WAIT_L(0); PG8_BAR; PG8_MMA(0, 0, At, B0); PG8_MMA(0, 1, At, B1); PG8_BAR; PG8_SCHED;
;             PG8_LDA(At, 0, 1); PG8_STAGE(PG8_SB(0, 0), b2, voffB); PG8_STAGE(PG8_SB(0, 1), b2 + hB, voffB); PG8_STAGE(PG8_SA(0, 0), a2, voffA);
;             PG8_WAIT_V(8); PG8_WAIT_L(0); PG8_BAR; PG8_MMA(1, 0, At, B0); PG8_MMA(1, 1, At, B1); PG8_BAR; PG8_SCHED;
.LBB0_1094:
	ds_read_b128 v[146:149], v153
	ds_read_b128 v[174:177], v153 offset:1024
	ds_read_b128 v[178:181], v153 offset:2048
	ds_read_b128 v[182:185], v153 offset:3072
	ds_read_b128 v[186:189], v154
	ds_read_b128 v[194:197], v154 offset:1024
	ds_read_b128 v[198:201], v154 offset:2048
	ds_read_b128 v[202:205], v154 offset:3072
	s_add_u32 s36, s4, 0xfff80080
	s_addc_u32 s37, s5, -1
	s_cmp_eq_u32 s38, 28
	s_cselect_b32 s45, s0, s37
	s_cselect_b32 s44, s1, s36
	s_cselect_b32 s37, s2, s29
	s_cselect_b32 s36, s3, s27
	v_lshl_add_u64 v[190:191], s[4:5], 0, v[136:137]
	s_add_i32 m0, s41, 0xc000
	ds_read_b128 v[206:209], v155
	ds_read_b128 v[210:213], v155 offset:1024
	ds_read_b128 v[214:217], v155 offset:2048
	ds_read_b128 v[218:221], v155 offset:3072
	ds_read_b128 v[222:225], v155 offset:4096
	ds_read_b128 v[226:229], v155 offset:5120
	ds_read_b128 v[230:233], v155 offset:6144
	ds_read_b128 v[234:237], v155 offset:7168
	global_load_lds_dwordx4 v[190:191], off
	v_lshl_add_u64 v[190:191], s[4:5], 0, v[138:139]
	s_add_i32 m0, s41, 0xe000
	s_nop 0
	global_load_lds_dwordx4 v[190:191], off
	s_waitcnt vmcnt(8)
	s_waitcnt lgkmcnt(0)
	s_barrier
	s_setprio 1
	s_waitcnt lgkmcnt(0)
	v_mfma_f32_16x16x32_bf16 v[124:127], v[146:149], v[206:209], v[124:127]
	v_mfma_f32_16x16x32_bf16 v[124:127], v[174:177], v[210:213], v[124:127]
	v_mfma_f32_16x16x32_bf16 v[120:123], v[178:181], v[206:209], v[120:123]
	v_mfma_f32_16x16x32_bf16 v[120:123], v[182:185], v[210:213], v[120:123]
	v_mfma_f32_16x16x32_bf16 v[108:111], v[146:149], v[214:217], v[108:111]
	v_mfma_f32_16x16x32_bf16 v[108:111], v[174:177], v[218:221], v[108:111]
	v_mfma_f32_16x16x32_bf16 v[104:107], v[178:181], v[214:217], v[104:107]
	v_mfma_f32_16x16x32_bf16 v[104:107], v[182:185], v[218:221], v[104:107]
	v_mfma_f32_16x16x32_bf16 v[92:95], v[146:149], v[222:225], v[92:95]
	v_mfma_f32_16x16x32_bf16 v[92:95], v[174:177], v[226:229], v[92:95]
	v_mfma_f32_16x16x32_bf16 v[88:91], v[178:181], v[222:225], v[88:91]
	v_mfma_f32_16x16x32_bf16 v[88:91], v[182:185], v[226:229], v[88:91]
	v_mfma_f32_16x16x32_bf16 v[76:79], v[146:149], v[230:233], v[76:79]
	v_mfma_f32_16x16x32_bf16 v[76:79], v[174:177], v[234:237], v[76:79]
	v_mfma_f32_16x16x32_bf16 v[72:75], v[178:181], v[230:233], v[72:75]
	v_mfma_f32_16x16x32_bf16 v[72:75], v[182:185], v[234:237], v[72:75]
	v_mfma_f32_16x16x32_bf16 v[116:119], v[186:189], v[206:209], v[116:119]
	v_mfma_f32_16x16x32_bf16 v[116:119], v[194:197], v[210:213], v[116:119]
	v_mfma_f32_16x16x32_bf16 v[112:115], v[198:201], v[206:209], v[112:115]
	v_mfma_f32_16x16x32_bf16 v[112:115], v[202:205], v[210:213], v[112:115]
	v_mfma_f32_16x16x32_bf16 v[100:103], v[186:189], v[214:217], v[100:103]
	v_mfma_f32_16x16x32_bf16 v[100:103], v[194:197], v[218:221], v[100:103]
	v_mfma_f32_16x16x32_bf16 v[96:99], v[198:201], v[214:217], v[96:99]
	v_mfma_f32_16x16x32_bf16 v[96:99], v[202:205], v[218:221], v[96:99]
	v_mfma_f32_16x16x32_bf16 v[84:87], v[186:189], v[222:225], v[84:87]
	v_mfma_f32_16x16x32_bf16 v[84:87], v[194:197], v[226:229], v[84:87]
	v_mfma_f32_16x16x32_bf16 v[80:83], v[198:201], v[222:225], v[80:83]
	v_mfma_f32_16x16x32_bf16 v[80:83], v[202:205], v[226:229], v[80:83]
	v_mfma_f32_16x16x32_bf16 v[68:71], v[186:189], v[230:233], v[68:71]
	v_mfma_f32_16x16x32_bf16 v[68:71], v[194:197], v[234:237], v[68:71]
	v_mfma_f32_16x16x32_bf16 v[64:67], v[198:201], v[230:233], v[64:67]
	v_mfma_f32_16x16x32_bf16 v[64:67], v[202:205], v[234:237], v[64:67]
	s_setprio 0
	s_barrier
	s_add_i32 s39, s61, s51
	v_lshl_add_u64 v[190:191], s[36:37], 0, v[130:131]
	s_mov_b32 m0, s39
	ds_read_b128 v[206:209], v155 offset:16384
	ds_read_b128 v[210:213], v155 offset:17408
	ds_read_b128 v[214:217], v155 offset:18432
	ds_read_b128 v[218:221], v155 offset:19456
	ds_read_b128 v[222:225], v155 offset:20480
	ds_read_b128 v[226:229], v155 offset:21504
	ds_read_b128 v[230:233], v155 offset:22528
	ds_read_b128 v[234:237], v155 offset:23552
	global_load_lds_dwordx4 v[190:191], off
	s_add_i32 m0, s39, 0x2000
	s_add_u32 s46, s36, 0x80000
	v_lshl_add_u64 v[238:239], s[36:37], 0, v[134:135]
	s_addc_u32 s47, s37, 0
	s_add_i32 s39, s62, s51
	global_load_lds_dwordx4 v[238:239], off
	v_lshl_add_u64 v[240:241], s[46:47], 0, v[130:131]
	s_mov_b32 m0, s39
	v_lshl_add_u64 v[242:243], s[44:45], 0, v[132:133]
	global_load_lds_dwordx4 v[240:241], off
	v_lshl_add_u64 v[240:241], s[46:47], 0, v[134:135]
	s_add_i32 m0, s39, 0x2000
	s_nop 0
	global_load_lds_dwordx4 v[240:241], off
	v_lshl_add_u64 v[240:241], s[44:45], 0, v[128:129]
	s_mov_b32 m0, s41
	s_nop 0
	global_load_lds_dwordx4 v[240:241], off
	s_mov_b32 m0, s43
	s_nop 0
	global_load_lds_dwordx4 v[242:243], off
	s_waitcnt vmcnt(8)
	s_waitcnt lgkmcnt(0)
	s_barrier
; #define PG8_STAGE(bufoff, gbase, voff) do { _Pragma("unroll") for (int _i = 0; _i < 2; ++_i) \
;         __builtin_amdgcn_global_load_lds((const unsigned*)((const char*)(gbase) + (voff)[_i]), (LAS unsigned*)(lds + (bufoff) + ldsw + _i * 8192), 16, 0, 0); } while (0)
; #define PG8_LDA(dst, b, h) do { _Pragma("unroll") for (int m = 0; m < 4; ++m) _Pragma("unroll") for (int k = 0; k < 2; ++k) dst[m][k] = *(const LAS bf16x8*)(lds + PG8_SA(b, h) + aoff + m * 2048 + k * 1024); } while (0)
; #define PG8_LDB(dst, b, h) do { _Pragma("unroll") for (int n = 0; n < 2; ++n) _Pragma("unroll") for (int k = 0; k < 2; ++k) dst[n][k] = *(const LAS bf16x8*)(lds + PG8_SB(b, h) + boff + n * 2048 + k * 1024); } while (0)
; #define PG8_MMA(ai, bj, At, Bt) do { __builtin_amdgcn_s_setprio(1); _Pragma("unroll") for (int m = 0; m < 4; ++m) _Pragma("unroll") for (int n = 0; n < 2; ++n) _Pragma("unroll") for (int k = 0; k < 2; ++k) \
;         acc[ai][bj][m][n] = __builtin_amdgcn_mfma_f32_16x16x32_bf16(Bt[n][k], At[m][k], acc[ai][bj][m][n], 0, 0, 0); __builtin_amdgcn_s_setprio(0); } while (0)
; #define PG8_WAIT_V(n) asm volatile("s_waitcnt vmcnt(" #n ")" ::: "memory")
; #define PG8_WAIT_L(n) asm volatile("s_waitcnt lgkmcnt(" #n ")" ::: "memory")
; #define PG8_BAR __builtin_amdgcn_s_barrier()
; #define PG8_SCHED __builtin_amdgcn_sched_barrier(0)
; template <class Epi, bool ALIGN_EPI>
; __device__ __forceinline__ void gemm_phase(LAS unsigned char* lds, const Gemm g, const StaticOrder& S, const Epi& E) {
;     ...
;             PG8_WAIT_V(8); PG8_WAIT_L(0); PG8_BAR; PG8_MMA(1, 0, At, B0); PG8_MMA(1, 1, At, B1); PG8_BAR; PG8_SCHED;
;             PG8_LDB(B0, 1, 0); PG8_LDB(B1, 1, 1); PG8_SCHED; PG8_LDA(At, 1, 0); PG8_STAGE(PG8_SA(0, 1), a2 + hA, voffA);
;             PG8_WAIT_V(8); PG8_WAIT_L(0); PG8_BAR; PG8_MMA(0, 0, At, B0); PG8_MMA(0, 1, At, B1); PG8_BAR; PG8_SCHED;
	s_setprio 1
	s_waitcnt lgkmcnt(0)
	v_mfma_f32_16x16x32_bf16 v[60:63], v[146:149], v[206:209], v[60:63]
	v_mfma_f32_16x16x32_bf16 v[60:63], v[174:177], v[210:213], v[60:63]
	v_mfma_f32_16x16x32_bf16 v[56:59], v[178:181], v[206:209], v[56:59]
	v_mfma_f32_16x16x32_bf16 v[56:59], v[182:185], v[210:213], v[56:59]
	v_mfma_f32_16x16x32_bf16 v[44:47], v[146:149], v[214:217], v[44:47]
	v_mfma_f32_16x16x32_bf16 v[44:47], v[174:177], v[218:221], v[44:47]
	v_mfma_f32_16x16x32_bf16 v[40:43], v[178:181], v[214:217], v[40:43]
	v_mfma_f32_16x16x32_bf16 v[40:43], v[182:185], v[218:221], v[40:43]
	v_mfma_f32_16x16x32_bf16 v[28:31], v[146:149], v[222:225], v[28:31]
	v_mfma_f32_16x16x32_bf16 v[28:31], v[174:177], v[226:229], v[28:31]
	v_mfma_f32_16x16x32_bf16 v[24:27], v[178:181], v[222:225], v[24:27]
	v_mfma_f32_16x16x32_bf16 v[24:27], v[182:185], v[226:229], v[24:27]
	v_mfma_f32_16x16x32_bf16 v[12:15], v[146:149], v[230:233], v[12:15]
	v_mfma_f32_16x16x32_bf16 v[12:15], v[174:177], v[234:237], v[12:15]
	v_mfma_f32_16x16x32_bf16 v[8:11], v[178:181], v[230:233], v[8:11]
	v_mfma_f32_16x16x32_bf16 v[8:11], v[182:185], v[234:237], v[8:11]
	v_mfma_f32_16x16x32_bf16 v[52:55], v[186:189], v[206:209], v[52:55]
	v_mfma_f32_16x16x32_bf16 v[52:55], v[194:197], v[210:213], v[52:55]
	v_mfma_f32_16x16x32_bf16 v[48:51], v[198:201], v[206:209], v[48:51]
	v_mfma_f32_16x16x32_bf16 v[48:51], v[202:205], v[210:213], v[48:51]
	v_mfma_f32_16x16x32_bf16 v[36:39], v[186:189], v[214:217], v[36:39]
	v_mfma_f32_16x16x32_bf16 v[36:39], v[194:197], v[218:221], v[36:39]
	v_mfma_f32_16x16x32_bf16 v[32:35], v[198:201], v[214:217], v[32:35]
	v_mfma_f32_16x16x32_bf16 v[32:35], v[202:205], v[218:221], v[32:35]
	v_mfma_f32_16x16x32_bf16 v[20:23], v[186:189], v[222:225], v[20:23]
	v_mfma_f32_16x16x32_bf16 v[20:23], v[194:197], v[226:229], v[20:23]
	v_mfma_f32_16x16x32_bf16 v[16:19], v[198:201], v[222:225], v[16:19]
	v_mfma_f32_16x16x32_bf16 v[16:19], v[202:205], v[226:229], v[16:19]
	v_mfma_f32_16x16x32_bf16 v[4:7], v[186:189], v[230:233], v[4:7]
	v_mfma_f32_16x16x32_bf16 v[4:7], v[194:197], v[234:237], v[4:7]
	v_mfma_f32_16x16x32_bf16 v[0:3], v[198:201], v[230:233], v[0:3]
	v_mfma_f32_16x16x32_bf16 v[0:3], v[202:205], v[234:237], v[0:3]
	s_setprio 0
	s_barrier
	s_add_i32 s39, 0, 0x18000
	v_add_u32_e32 v145, s39, v151
	s_add_i32 s46, 0, 0x1c000
	ds_read_b128 v[146:149], v145
	ds_read_b128 v[174:177], v145 offset:1024
	ds_read_b128 v[178:181], v145 offset:2048
	ds_read_b128 v[182:185], v145 offset:3072
	v_add_u32_e32 v145, s46, v151
	ds_read_b128 v[186:189], v145
	ds_read_b128 v[194:197], v145 offset:1024
	ds_read_b128 v[198:201], v145 offset:2048
	ds_read_b128 v[202:205], v145 offset:3072
	s_add_u32 s44, s44, 0x80000
	s_addc_u32 s45, s45, 0
	s_mov_b32 m0, s52
	v_lshl_add_u64 v[244:245], s[44:45], 0, v[128:129]
	ds_read_b128 v[206:209], v155 offset:32768
	ds_read_b128 v[210:213], v155 offset:33792
	ds_read_b128 v[214:217], v155 offset:34816
	ds_read_b128 v[218:221], v155 offset:35840
	ds_read_b128 v[222:225], v155 offset:36864
	ds_read_b128 v[226:229], v155 offset:37888
	ds_read_b128 v[230:233], v155 offset:38912
	ds_read_b128 v[234:237], v155 offset:39936
	global_load_lds_dwordx4 v[244:245], off
	v_lshl_add_u64 v[244:245], s[44:45], 0, v[132:133]
	s_mov_b32 m0, s53
	s_nop 0
	global_load_lds_dwordx4 v[244:245], off
	s_waitcnt vmcnt(8)
	s_waitcnt lgkmcnt(0)
	s_barrier
	s_setprio 1
	s_waitcnt lgkmcnt(0)
	v_mfma_f32_16x16x32_bf16 v[124:127], v[146:149], v[206:209], v[124:127]
	v_mfma_f32_16x16x32_bf16 v[124:127], v[174:177], v[210:213], v[124:127]
	v_mfma_f32_16x16x32_bf16 v[120:123], v[178:181], v[206:209], v[120:123]
	v_mfma_f32_16x16x32_bf16 v[120:123], v[182:185], v[210:213], v[120:123]
	v_mfma_f32_16x16x32_bf16 v[108:111], v[146:149], v[214:217], v[108:111]
	v_mfma_f32_16x16x32_bf16 v[108:111], v[174:177], v[218:221], v[108:111]
	v_mfma_f32_16x16x32_bf16 v[104:107], v[178:181], v[214:217], v[104:107]
	v_mfma_f32_16x16x32_bf16 v[104:107], v[182:185], v[218:221], v[104:107]
	v_mfma_f32_16x16x32_bf16 v[92:95], v[146:149], v[222:225], v[92:95]
	v_mfma_f32_16x16x32_bf16 v[92:95], v[174:177], v[226:229], v[92:95]
	v_mfma_f32_16x16x32_bf16 v[88:91], v[178:181], v[222:225], v[88:91]
	v_mfma_f32_16x16x32_bf16 v[88:91], v[182:185], v[226:229], v[88:91]
	v_mfma_f32_16x16x32_bf16 v[76:79], v[146:149], v[230:233], v[76:79]
	v_mfma_f32_16x16x32_bf16 v[76:79], v[174:177], v[234:237], v[76:79]
	v_mfma_f32_16x16x32_bf16 v[72:75], v[178:181], v[230:233], v[72:75]
	v_mfma_f32_16x16x32_bf16 v[72:75], v[182:185], v[234:237], v[72:75]
	v_mfma_f32_16x16x32_bf16 v[116:119], v[186:189], v[206:209], v[116:119]
	v_mfma_f32_16x16x32_bf16 v[116:119], v[194:197], v[210:213], v[116:119]
	v_mfma_f32_16x16x32_bf16 v[112:115], v[198:201], v[206:209], v[112:115]
	v_mfma_f32_16x16x32_bf16 v[112:115], v[202:205], v[210:213], v[112:115]
	v_mfma_f32_16x16x32_bf16 v[100:103], v[186:189], v[214:217], v[100:103]
	v_mfma_f32_16x16x32_bf16 v[100:103], v[194:197], v[218:221], v[100:103]
	v_mfma_f32_16x16x32_bf16 v[96:99], v[198:201], v[214:217], v[96:99]
	v_mfma_f32_16x16x32_bf16 v[96:99], v[202:205], v[218:221], v[96:99]
	v_mfma_f32_16x16x32_bf16 v[84:87], v[186:189], v[222:225], v[84:87]
	v_mfma_f32_16x16x32_bf16 v[84:87], v[194:197], v[226:229], v[84:87]
	v_mfma_f32_16x16x32_bf16 v[80:83], v[198:201], v[222:225], v[80:83]
	v_mfma_f32_16x16x32_bf16 v[80:83], v[202:205], v[226:229], v[80:83]
	v_mfma_f32_16x16x32_bf16 v[68:71], v[186:189], v[230:233], v[68:71]
	v_mfma_f32_16x16x32_bf16 v[68:71], v[194:197], v[234:237], v[68:71]
	v_mfma_f32_16x16x32_bf16 v[64:67], v[198:201], v[230:233], v[64:67]
	v_mfma_f32_16x16x32_bf16 v[64:67], v[202:205], v[234:237], v[64:67]
	s_setprio 0
	s_barrier
; #define PG8_STAGE(bufoff, gbase, voff) do { _Pragma("unroll") for (int _i = 0; _i < 2; ++_i) \
;         __builtin_amdgcn_global_load_lds((const unsigned*)((const char*)(gbase) + (voff)[_i]), (LAS unsigned*)(lds + (bufoff) + ldsw + _i * 8192), 16, 0, 0); } while (0)
; #define PG8_LDA(dst, b, h) do { _Pragma("unroll") for (int m = 0; m < 4; ++m) _Pragma("unroll") for (int k = 0; k < 2; ++k) dst[m][k] = *(const LAS bf16x8*)(lds + PG8_SA(b, h) + aoff + m * 2048 + k * 1024); } while (0)
; #define PG8_MMA(ai, bj, At, Bt) do { __builtin_amdgcn_s_setprio(1); _Pragma("unroll") for (int m = 0; m < 4; ++m) _Pragma("unroll") for (int n = 0; n < 2; ++n) _Pragma("unroll") for (int k = 0; k < 2; ++k) \
;         acc[ai][bj][m][n] = __builtin_amdgcn_mfma_f32_16x16x32_bf16(Bt[n][k], At[m][k], acc[ai][bj][m][n], 0, 0, 0); __builtin_amdgcn_s_setprio(0); } while (0)
; #define PG8_WAIT_V(n) asm volatile("s_waitcnt vmcnt(" #n ")" ::: "memory")
; #define PG8_WAIT_L(n) asm volatile("s_waitcnt lgkmcnt(" #n ")" ::: "memory")
; #define PG8_BAR __builtin_amdgcn_s_barrier()
; #define PG8_SCHED __builtin_amdgcn_sched_barrier(0)
; template <class Epi, bool ALIGN_EPI>
; __device__ __forceinline__ void gemm_phase(LAS unsigned char* lds, const Gemm g, const StaticOrder& S, const Epi& E) {
;     ...
;             PG8_LDA(At, 1, 1); PG8_STAGE(PG8_SB(1, 0), b3, voffB); PG8_STAGE(PG8_SB(1, 1), b3 + hB, voffB); PG8_STAGE(PG8_SA(1, 0), a3, voffA);
;             PG8_WAIT_V(8); PG8_WAIT_L(0); PG8_BAR; PG8_MMA(1, 0, At, B0); PG8_MMA(1, 1, At, B1); PG8_BAR; PG8_SCHED;
;         }
	s_add_i32 s39, s39, s51
	v_lshl_add_u64 v[190:191], v[190:191], 0, s[20:21]
	s_mov_b32 m0, s39
	ds_read_b128 v[206:209], v155 offset:49152
	ds_read_b128 v[210:213], v155 offset:50176
	ds_read_b128 v[214:217], v155 offset:51200
	ds_read_b128 v[218:221], v155 offset:52224
	ds_read_b128 v[222:225], v155 offset:53248
	ds_read_b128 v[226:229], v155 offset:54272
	ds_read_b128 v[230:233], v155 offset:55296
	ds_read_b128 v[234:237], v155 offset:56320
	global_load_lds_dwordx4 v[190:191], off
	s_add_i32 m0, s39, 0x2000
	s_add_u32 s36, s36, 0x80080
	v_lshl_add_u64 v[190:191], v[238:239], 0, s[20:21]
	s_addc_u32 s37, s37, 0
	s_add_i32 s39, s46, s51
	global_load_lds_dwordx4 v[190:191], off
	v_lshl_add_u64 v[190:191], s[36:37], 0, v[130:131]
	s_mov_b32 m0, s39
	s_nop 0
	global_load_lds_dwordx4 v[190:191], off
	v_lshl_add_u64 v[190:191], s[36:37], 0, v[134:135]
	s_add_i32 m0, s39, 0x2000
	s_nop 0
	global_load_lds_dwordx4 v[190:191], off
	v_lshl_add_u64 v[190:191], v[240:241], 0, s[20:21]
	s_mov_b32 m0, s57
	s_nop 0
	global_load_lds_dwordx4 v[190:191], off
	v_lshl_add_u64 v[190:191], v[242:243], 0, s[20:21]
	s_mov_b32 m0, s58
	s_nop 0
	global_load_lds_dwordx4 v[190:191], off
	s_waitcnt vmcnt(8)
	s_waitcnt lgkmcnt(0)
	s_barrier
	s_setprio 1
	s_waitcnt lgkmcnt(0)
	v_mfma_f32_16x16x32_bf16 v[60:63], v[146:149], v[206:209], v[60:63]
	v_mfma_f32_16x16x32_bf16 v[60:63], v[174:177], v[210:213], v[60:63]
	v_mfma_f32_16x16x32_bf16 v[56:59], v[178:181], v[206:209], v[56:59]
	v_mfma_f32_16x16x32_bf16 v[56:59], v[182:185], v[210:213], v[56:59]
	v_mfma_f32_16x16x32_bf16 v[44:47], v[146:149], v[214:217], v[44:47]
	v_mfma_f32_16x16x32_bf16 v[44:47], v[174:177], v[218:221], v[44:47]
	v_mfma_f32_16x16x32_bf16 v[40:43], v[178:181], v[214:217], v[40:43]
	v_mfma_f32_16x16x32_bf16 v[40:43], v[182:185], v[218:221], v[40:43]
	v_mfma_f32_16x16x32_bf16 v[28:31], v[146:149], v[222:225], v[28:31]
	v_mfma_f32_16x16x32_bf16 v[28:31], v[174:177], v[226:229], v[28:31]
	v_mfma_f32_16x16x32_bf16 v[24:27], v[178:181], v[222:225], v[24:27]
	v_mfma_f32_16x16x32_bf16 v[24:27], v[182:185], v[226:229], v[24:27]
	v_mfma_f32_16x16x32_bf16 v[12:15], v[146:149], v[230:233], v[12:15]
	v_mfma_f32_16x16x32_bf16 v[12:15], v[174:177], v[234:237], v[12:15]
	v_mfma_f32_16x16x32_bf16 v[8:11], v[178:181], v[230:233], v[8:11]
	v_mfma_f32_16x16x32_bf16 v[8:11], v[182:185], v[234:237], v[8:11]
	v_mfma_f32_16x16x32_bf16 v[52:55], v[186:189], v[206:209], v[52:55]
	v_mfma_f32_16x16x32_bf16 v[52:55], v[194:197], v[210:213], v[52:55]
	v_mfma_f32_16x16x32_bf16 v[48:51], v[198:201], v[206:209], v[48:51]
	v_mfma_f32_16x16x32_bf16 v[48:51], v[202:205], v[210:213], v[48:51]
	v_mfma_f32_16x16x32_bf16 v[36:39], v[186:189], v[214:217], v[36:39]
	v_mfma_f32_16x16x32_bf16 v[36:39], v[194:197], v[218:221], v[36:39]
	v_mfma_f32_16x16x32_bf16 v[32:35], v[198:201], v[214:217], v[32:35]
	v_mfma_f32_16x16x32_bf16 v[32:35], v[202:205], v[218:221], v[32:35]
	v_mfma_f32_16x16x32_bf16 v[20:23], v[186:189], v[222:225], v[20:23]
	v_mfma_f32_16x16x32_bf16 v[20:23], v[194:197], v[226:229], v[20:23]
	v_mfma_f32_16x16x32_bf16 v[16:19], v[198:201], v[222:225], v[16:19]
	v_mfma_f32_16x16x32_bf16 v[16:19], v[202:205], v[226:229], v[16:19]
	v_mfma_f32_16x16x32_bf16 v[4:7], v[186:189], v[230:233], v[4:7]
	v_mfma_f32_16x16x32_bf16 v[4:7], v[194:197], v[234:237], v[4:7]
	v_mfma_f32_16x16x32_bf16 v[0:3], v[198:201], v[230:233], v[0:3]
	v_mfma_f32_16x16x32_bf16 v[0:3], v[202:205], v[234:237], v[0:3]
	s_setprio 0
	s_barrier
	s_add_i32 s38, s38, 2
	s_add_u32 s4, s4, 0x100
	s_addc_u32 s5, s5, 0
	s_add_u32 s27, s27, 0x100
	s_addc_u32 s29, s29, 0
	s_cmp_gt_u32 s38, 29
	s_cbranch_scc0 .LBB0_1094
	s_and_b64 vcc, exec, s[22:23]
	s_cbranch_vccz .LBB0_1097
	s_barrier

; #define PG8_STAGE(bufoff, gbase, voff) do { _Pragma("unroll") for (int _i = 0; _i < 2; ++_i) \
;         __builtin_amdgcn_global_load_lds((const unsigned*)((const char*)(gbase) + (voff)[_i]), (LAS unsigned*)(lds + (bufoff) + ldsw + _i * 8192), 16, 0, 0); } while (0)
; #define PG8_LDA(dst, b, h) do { _Pragma("unroll") for (int m = 0; m < 4; ++m) _Pragma("unroll") for (int k = 0; k < 2; ++k) dst[m][k] = *(const LAS bf16x8*)(lds + PG8_SA(b, h) + aoff + m * 2048 + k * 1024); } while (0)
; #define PG8_LDB(dst, b, h) do { _Pragma("unroll") for (int n = 0; n < 2; ++n) _Pragma("unroll") for (int k = 0; k < 2; ++k) dst[n][k] = *(const LAS bf16x8*)(lds + PG8_SB(b, h) + boff + n * 2048 + k * 1024); } while (0)
; #define PG8_MMA(ai, bj, At, Bt) do { __builtin_amdgcn_s_setprio(1); _Pragma("unroll") for (int m = 0; m < 4; ++m) _Pragma("unroll") for (int n = 0; n < 2; ++n) _Pragma("unroll") for (int k = 0; k < 2; ++k) \
;         acc[ai][bj][m][n] = __builtin_amdgcn_mfma_f32_16x16x32_bf16(Bt[n][k], At[m][k], acc[ai][bj][m][n], 0, 0, 0); __builtin_amdgcn_s_setprio(0); } while (0)
; #define PG8_WAIT_V(n) asm volatile("s_waitcnt vmcnt(" #n ")" ::: "memory")
; #define PG8_WAIT_L(n) asm volatile("s_waitcnt lgkmcnt(" #n ")" ::: "memory")
; #define PG8_BAR __builtin_amdgcn_s_barrier()
; #define PG8_SCHED __builtin_amdgcn_sched_barrier(0)
; template <class Epi, bool ALIGN_EPI>
; __device__ __forceinline__ void gemm_phase(LAS unsigned char* lds, const Gemm g, const StaticOrder& S, const Epi& E) {
;     ...
;             const bool last = (t == nt - 2);
;             const char* a1 = cA + (size_t)(t + 1) * kstep;
;             const char* a2 = last ? nA : cA + (size_t)(t + 2) * kstep; const char* b2 = last ? nB : cB + (size_t)(t + 2) * kstep;
;             const char* a3 = a2 + kstep; const char* b3 = b2 + kstep;
;             PG8_LDB(B0, 0, 0); PG8_LDB(B1, 0, 1); PG8_SCHED; PG8_LDA(At, 0, 0); PG8_STAGE(PG8_SA(1, 1), a1 + hA, voffA);
;             PG8_WAIT_V(8); PG8_WAIT_L(0); PG8_BAR; PG8_MMA(0, 0, At, B0); PG8_MMA(0, 1, At, B1); PG8_BAR; PG8_SCHED;
;             PG8_LDA(At, 0, 1); PG8_STAGE(PG8_SB(0, 0), b2, voffB); PG8_STAGE(PG8_SB(0, 1), b2 + hB, voffB); PG8_STAGE(PG8_SA(0, 0), a2, voffA);
;             PG8_WAIT_V(8); PG8_WAIT_L(0); PG8_BAR; PG8_MMA(1, 0, At, B0); PG8_MMA(1, 1, At, B1); PG8_BAR; PG8_SCHED;
.LBB0_1585:
	ds_read_b128 v[128:131], v175
	ds_read_b128 v[132:135], v175 offset:1024
	ds_read_b128 v[136:139], v175 offset:2048
	ds_read_b128 v[140:143], v175 offset:3072
	ds_read_b128 v[160:163], v176
	ds_read_b128 v[164:167], v176 offset:1024
	ds_read_b128 v[168:171], v176 offset:2048
	ds_read_b128 v[180:183], v176 offset:3072
	s_add_u32 s40, s36, 0xfff80080
	s_addc_u32 s41, s37, -1
	s_cmp_eq_u32 s57, 28
	s_cselect_b32 s43, s25, s41
	s_cselect_b32 s42, s31, s40
	s_cselect_b32 s41, s23, s56
	s_cselect_b32 s40, s54, s55
	v_lshl_add_u64 v[218:219], s[36:37], 0, v[152:153]
	s_add_i32 m0, s35, 0xc000
	ds_read_b128 v[184:187], v177
	ds_read_b128 v[188:191], v177 offset:1024
	ds_read_b128 v[194:197], v177 offset:2048
	ds_read_b128 v[198:201], v177 offset:3072
	ds_read_b128 v[202:205], v177 offset:4096
	ds_read_b128 v[206:209], v177 offset:5120
	ds_read_b128 v[210:213], v177 offset:6144
	ds_read_b128 v[214:217], v177 offset:7168
	global_load_lds_dwordx4 v[218:219], off
	v_lshl_add_u64 v[218:219], s[36:37], 0, v[154:155]
	s_add_i32 m0, s35, 0xe000
	s_nop 0
	global_load_lds_dwordx4 v[218:219], off
	s_waitcnt vmcnt(8)
	s_waitcnt lgkmcnt(0)
	s_barrier
	s_setprio 1
	s_waitcnt lgkmcnt(0)
	v_mfma_f32_16x16x32_bf16 v[124:127], v[128:131], v[184:187], v[124:127]
	v_mfma_f32_16x16x32_bf16 v[124:127], v[132:135], v[188:191], v[124:127]
	v_mfma_f32_16x16x32_bf16 v[120:123], v[136:139], v[184:187], v[120:123]
	v_mfma_f32_16x16x32_bf16 v[120:123], v[140:143], v[188:191], v[120:123]
	v_mfma_f32_16x16x32_bf16 v[112:115], v[128:131], v[194:197], v[112:115]
	v_mfma_f32_16x16x32_bf16 v[112:115], v[132:135], v[198:201], v[112:115]
	v_mfma_f32_16x16x32_bf16 v[104:107], v[136:139], v[194:197], v[104:107]
	v_mfma_f32_16x16x32_bf16 v[104:107], v[140:143], v[198:201], v[104:107]
	v_mfma_f32_16x16x32_bf16 v[92:95], v[128:131], v[202:205], v[92:95]
	v_mfma_f32_16x16x32_bf16 v[92:95], v[132:135], v[206:209], v[92:95]
	v_mfma_f32_16x16x32_bf16 v[88:91], v[136:139], v[202:205], v[88:91]
	v_mfma_f32_16x16x32_bf16 v[88:91], v[140:143], v[206:209], v[88:91]
	v_mfma_f32_16x16x32_bf16 v[76:79], v[128:131], v[210:213], v[76:79]
	v_mfma_f32_16x16x32_bf16 v[76:79], v[132:135], v[214:217], v[76:79]
	v_mfma_f32_16x16x32_bf16 v[72:75], v[136:139], v[210:213], v[72:75]
	v_mfma_f32_16x16x32_bf16 v[72:75], v[140:143], v[214:217], v[72:75]
	v_mfma_f32_16x16x32_bf16 v[116:119], v[160:163], v[184:187], v[116:119]
	v_mfma_f32_16x16x32_bf16 v[116:119], v[164:167], v[188:191], v[116:119]
	v_mfma_f32_16x16x32_bf16 v[108:111], v[168:171], v[184:187], v[108:111]
	v_mfma_f32_16x16x32_bf16 v[108:111], v[180:183], v[188:191], v[108:111]
	v_mfma_f32_16x16x32_bf16 v[100:103], v[160:163], v[194:197], v[100:103]
	v_mfma_f32_16x16x32_bf16 v[100:103], v[164:167], v[198:201], v[100:103]
	v_mfma_f32_16x16x32_bf16 v[96:99], v[168:171], v[194:197], v[96:99]
	v_mfma_f32_16x16x32_bf16 v[96:99], v[180:183], v[198:201], v[96:99]
	v_mfma_f32_16x16x32_bf16 v[84:87], v[160:163], v[202:205], v[84:87]
	v_mfma_f32_16x16x32_bf16 v[84:87], v[164:167], v[206:209], v[84:87]
	v_mfma_f32_16x16x32_bf16 v[80:83], v[168:171], v[202:205], v[80:83]
	v_mfma_f32_16x16x32_bf16 v[80:83], v[180:183], v[206:209], v[80:83]
	v_mfma_f32_16x16x32_bf16 v[68:71], v[160:163], v[210:213], v[68:71]
	v_mfma_f32_16x16x32_bf16 v[68:71], v[164:167], v[214:217], v[68:71]
	v_mfma_f32_16x16x32_bf16 v[64:67], v[168:171], v[210:213], v[64:67]
	v_mfma_f32_16x16x32_bf16 v[64:67], v[180:183], v[214:217], v[64:67]
	s_setprio 0
	s_barrier
	s_add_i32 s58, s51, s33
	v_lshl_add_u64 v[218:219], s[40:41], 0, v[146:147]
	s_mov_b32 m0, s58
	ds_read_b128 v[184:187], v177 offset:16384
	ds_read_b128 v[188:191], v177 offset:17408
	ds_read_b128 v[194:197], v177 offset:18432
	ds_read_b128 v[198:201], v177 offset:19456
	ds_read_b128 v[202:205], v177 offset:20480
	ds_read_b128 v[206:209], v177 offset:21504
	ds_read_b128 v[210:213], v177 offset:22528
	ds_read_b128 v[214:217], v177 offset:23552
	global_load_lds_dwordx4 v[218:219], off
	s_add_i32 m0, s58, 0x2000
	s_add_u32 s58, s40, 0x80000
	v_lshl_add_u64 v[220:221], s[40:41], 0, v[150:151]
	s_addc_u32 s59, s41, 0
	s_add_i32 s60, s52, s33
	global_load_lds_dwordx4 v[220:221], off
	v_lshl_add_u64 v[222:223], s[58:59], 0, v[146:147]
	s_mov_b32 m0, s60
	v_lshl_add_u64 v[224:225], s[42:43], 0, v[148:149]
	global_load_lds_dwordx4 v[222:223], off
	v_lshl_add_u64 v[222:223], s[58:59], 0, v[150:151]
	s_add_i32 m0, s60, 0x2000
	s_nop 0
	global_load_lds_dwordx4 v[222:223], off
	v_lshl_add_u64 v[222:223], s[42:43], 0, v[144:145]
	s_mov_b32 m0, s35
	s_nop 0
	global_load_lds_dwordx4 v[222:223], off
	s_mov_b32 m0, s38
	s_nop 0
	global_load_lds_dwordx4 v[224:225], off
	s_waitcnt vmcnt(8)
	s_waitcnt lgkmcnt(0)
	s_barrier
; #define PG8_STAGE(bufoff, gbase, voff) do { _Pragma("unroll") for (int _i = 0; _i < 2; ++_i) \
;         __builtin_amdgcn_global_load_lds((const unsigned*)((const char*)(gbase) + (voff)[_i]), (LAS unsigned*)(lds + (bufoff) + ldsw + _i * 8192), 16, 0, 0); } while (0)
; #define PG8_LDA(dst, b, h) do { _Pragma("unroll") for (int m = 0; m < 4; ++m) _Pragma("unroll") for (int k = 0; k < 2; ++k) dst[m][k] = *(const LAS bf16x8*)(lds + PG8_SA(b, h) + aoff + m * 2048 + k * 1024); } while (0)
; #define PG8_LDB(dst, b, h) do { _Pragma("unroll") for (int n = 0; n < 2; ++n) _Pragma("unroll") for (int k = 0; k < 2; ++k) dst[n][k] = *(const LAS bf16x8*)(lds + PG8_SB(b, h) + boff + n * 2048 + k * 1024); } while (0)
; #define PG8_MMA(ai, bj, At, Bt) do { __builtin_amdgcn_s_setprio(1); _Pragma("unroll") for (int m = 0; m < 4; ++m) _Pragma("unroll") for (int n = 0; n < 2; ++n) _Pragma("unroll") for (int k = 0; k < 2; ++k) \
;         acc[ai][bj][m][n] = __builtin_amdgcn_mfma_f32_16x16x32_bf16(Bt[n][k], At[m][k], acc[ai][bj][m][n], 0, 0, 0); __builtin_amdgcn_s_setprio(0); } while (0)
; #define PG8_WAIT_V(n) asm volatile("s_waitcnt vmcnt(" #n ")" ::: "memory")
; #define PG8_WAIT_L(n) asm volatile("s_waitcnt lgkmcnt(" #n ")" ::: "memory")
; #define PG8_BAR __builtin_amdgcn_s_barrier()
; #define PG8_SCHED __builtin_amdgcn_sched_barrier(0)
; template <class Epi, bool ALIGN_EPI>
; __device__ __forceinline__ void gemm_phase(LAS unsigned char* lds, const Gemm g, const StaticOrder& S, const Epi& E) {
;     ...
;             PG8_WAIT_V(8); PG8_WAIT_L(0); PG8_BAR; PG8_MMA(1, 0, At, B0); PG8_MMA(1, 1, At, B1); PG8_BAR; PG8_SCHED;
;             PG8_LDB(B0, 1, 0); PG8_LDB(B1, 1, 1); PG8_SCHED; PG8_LDA(At, 1, 0); PG8_STAGE(PG8_SA(0, 1), a2 + hA, voffA);
;             PG8_WAIT_V(8); PG8_WAIT_L(0); PG8_BAR; PG8_MMA(0, 0, At, B0); PG8_MMA(0, 1, At, B1); PG8_BAR; PG8_SCHED;
	s_setprio 1
	s_waitcnt lgkmcnt(0)
	v_mfma_f32_16x16x32_bf16 v[60:63], v[128:131], v[184:187], v[60:63]
	v_mfma_f32_16x16x32_bf16 v[60:63], v[132:135], v[188:191], v[60:63]
	v_mfma_f32_16x16x32_bf16 v[56:59], v[136:139], v[184:187], v[56:59]
	v_mfma_f32_16x16x32_bf16 v[56:59], v[140:143], v[188:191], v[56:59]
	v_mfma_f32_16x16x32_bf16 v[44:47], v[128:131], v[194:197], v[44:47]
	v_mfma_f32_16x16x32_bf16 v[44:47], v[132:135], v[198:201], v[44:47]
	v_mfma_f32_16x16x32_bf16 v[40:43], v[136:139], v[194:197], v[40:43]
	v_mfma_f32_16x16x32_bf16 v[40:43], v[140:143], v[198:201], v[40:43]
	v_mfma_f32_16x16x32_bf16 v[28:31], v[128:131], v[202:205], v[28:31]
	v_mfma_f32_16x16x32_bf16 v[28:31], v[132:135], v[206:209], v[28:31]
	v_mfma_f32_16x16x32_bf16 v[24:27], v[136:139], v[202:205], v[24:27]
	v_mfma_f32_16x16x32_bf16 v[24:27], v[140:143], v[206:209], v[24:27]
	v_mfma_f32_16x16x32_bf16 v[12:15], v[128:131], v[210:213], v[12:15]
	v_mfma_f32_16x16x32_bf16 v[12:15], v[132:135], v[214:217], v[12:15]
	v_mfma_f32_16x16x32_bf16 v[8:11], v[136:139], v[210:213], v[8:11]
	v_mfma_f32_16x16x32_bf16 v[8:11], v[140:143], v[214:217], v[8:11]
	v_mfma_f32_16x16x32_bf16 v[52:55], v[160:163], v[184:187], v[52:55]
	v_mfma_f32_16x16x32_bf16 v[52:55], v[164:167], v[188:191], v[52:55]
	v_mfma_f32_16x16x32_bf16 v[48:51], v[168:171], v[184:187], v[48:51]
	v_mfma_f32_16x16x32_bf16 v[48:51], v[180:183], v[188:191], v[48:51]
	v_mfma_f32_16x16x32_bf16 v[36:39], v[160:163], v[194:197], v[36:39]
	v_mfma_f32_16x16x32_bf16 v[36:39], v[164:167], v[198:201], v[36:39]
	v_mfma_f32_16x16x32_bf16 v[32:35], v[168:171], v[194:197], v[32:35]
	v_mfma_f32_16x16x32_bf16 v[32:35], v[180:183], v[198:201], v[32:35]
	v_mfma_f32_16x16x32_bf16 v[20:23], v[160:163], v[202:205], v[20:23]
	v_mfma_f32_16x16x32_bf16 v[20:23], v[164:167], v[206:209], v[20:23]
	v_mfma_f32_16x16x32_bf16 v[16:19], v[168:171], v[202:205], v[16:19]
	v_mfma_f32_16x16x32_bf16 v[16:19], v[180:183], v[206:209], v[16:19]
	v_mfma_f32_16x16x32_bf16 v[4:7], v[160:163], v[210:213], v[4:7]
	v_mfma_f32_16x16x32_bf16 v[4:7], v[164:167], v[214:217], v[4:7]
	v_mfma_f32_16x16x32_bf16 v[0:3], v[168:171], v[210:213], v[0:3]
	v_mfma_f32_16x16x32_bf16 v[0:3], v[180:183], v[214:217], v[0:3]
	s_setprio 0
	s_barrier
	s_add_i32 s58, 0, 0x18000
	s_add_i32 s59, 0, 0x1c000
	v_add_u32_e32 v140, s58, v173
	v_add_u32_e32 v179, s59, v173
	ds_read_b128 v[128:131], v140
	ds_read_b128 v[132:135], v140 offset:1024
	ds_read_b128 v[136:139], v140 offset:2048
	ds_read_b128 v[140:143], v140 offset:3072
	ds_read_b128 v[160:163], v179
	ds_read_b128 v[164:167], v179 offset:1024
	ds_read_b128 v[168:171], v179 offset:2048
	ds_read_b128 v[180:183], v179 offset:3072
	s_add_u32 s42, s42, 0x80000
	s_addc_u32 s43, s43, 0
	s_mov_b32 m0, s39
	v_lshl_add_u64 v[226:227], s[42:43], 0, v[144:145]
	ds_read_b128 v[184:187], v177 offset:32768
	ds_read_b128 v[188:191], v177 offset:33792
	ds_read_b128 v[194:197], v177 offset:34816
	ds_read_b128 v[198:201], v177 offset:35840
	ds_read_b128 v[202:205], v177 offset:36864
	ds_read_b128 v[206:209], v177 offset:37888
	ds_read_b128 v[210:213], v177 offset:38912
	ds_read_b128 v[214:217], v177 offset:39936
	global_load_lds_dwordx4 v[226:227], off
	v_lshl_add_u64 v[226:227], s[42:43], 0, v[148:149]
	s_mov_b32 m0, s44
	s_nop 0
	global_load_lds_dwordx4 v[226:227], off
	s_waitcnt vmcnt(8)
	s_waitcnt lgkmcnt(0)
	s_barrier
	s_setprio 1
	s_waitcnt lgkmcnt(0)
	v_mfma_f32_16x16x32_bf16 v[124:127], v[128:131], v[184:187], v[124:127]
	v_mfma_f32_16x16x32_bf16 v[124:127], v[132:135], v[188:191], v[124:127]
	v_mfma_f32_16x16x32_bf16 v[120:123], v[136:139], v[184:187], v[120:123]
	v_mfma_f32_16x16x32_bf16 v[120:123], v[140:143], v[188:191], v[120:123]
	v_mfma_f32_16x16x32_bf16 v[112:115], v[128:131], v[194:197], v[112:115]
	v_mfma_f32_16x16x32_bf16 v[112:115], v[132:135], v[198:201], v[112:115]
	v_mfma_f32_16x16x32_bf16 v[104:107], v[136:139], v[194:197], v[104:107]
	v_mfma_f32_16x16x32_bf16 v[104:107], v[140:143], v[198:201], v[104:107]
	v_mfma_f32_16x16x32_bf16 v[92:95], v[128:131], v[202:205], v[92:95]
	v_mfma_f32_16x16x32_bf16 v[92:95], v[132:135], v[206:209], v[92:95]
	v_mfma_f32_16x16x32_bf16 v[88:91], v[136:139], v[202:205], v[88:91]
	v_mfma_f32_16x16x32_bf16 v[88:91], v[140:143], v[206:209], v[88:91]
	v_mfma_f32_16x16x32_bf16 v[76:79], v[128:131], v[210:213], v[76:79]
	v_mfma_f32_16x16x32_bf16 v[76:79], v[132:135], v[214:217], v[76:79]
	v_mfma_f32_16x16x32_bf16 v[72:75], v[136:139], v[210:213], v[72:75]
	v_mfma_f32_16x16x32_bf16 v[72:75], v[140:143], v[214:217], v[72:75]
	v_mfma_f32_16x16x32_bf16 v[116:119], v[160:163], v[184:187], v[116:119]
	v_mfma_f32_16x16x32_bf16 v[116:119], v[164:167], v[188:191], v[116:119]
	v_mfma_f32_16x16x32_bf16 v[108:111], v[168:171], v[184:187], v[108:111]
	v_mfma_f32_16x16x32_bf16 v[108:111], v[180:183], v[188:191], v[108:111]
	v_mfma_f32_16x16x32_bf16 v[100:103], v[160:163], v[194:197], v[100:103]
	v_mfma_f32_16x16x32_bf16 v[100:103], v[164:167], v[198:201], v[100:103]
	v_mfma_f32_16x16x32_bf16 v[96:99], v[168:171], v[194:197], v[96:99]
	v_mfma_f32_16x16x32_bf16 v[96:99], v[180:183], v[198:201], v[96:99]
	v_mfma_f32_16x16x32_bf16 v[84:87], v[160:163], v[202:205], v[84:87]
	v_mfma_f32_16x16x32_bf16 v[84:87], v[164:167], v[206:209], v[84:87]
	v_mfma_f32_16x16x32_bf16 v[80:83], v[168:171], v[202:205], v[80:83]
	v_mfma_f32_16x16x32_bf16 v[80:83], v[180:183], v[206:209], v[80:83]
	v_mfma_f32_16x16x32_bf16 v[68:71], v[160:163], v[210:213], v[68:71]
	v_mfma_f32_16x16x32_bf16 v[68:71], v[164:167], v[214:217], v[68:71]
	v_mfma_f32_16x16x32_bf16 v[64:67], v[168:171], v[210:213], v[64:67]
	v_mfma_f32_16x16x32_bf16 v[64:67], v[180:183], v[214:217], v[64:67]
	s_setprio 0
	s_barrier
; #define PG8_STAGE(bufoff, gbase, voff) do { _Pragma("unroll") for (int _i = 0; _i < 2; ++_i) \
;         __builtin_amdgcn_global_load_lds((const unsigned*)((const char*)(gbase) + (voff)[_i]), (LAS unsigned*)(lds + (bufoff) + ldsw + _i * 8192), 16, 0, 0); } while (0)
; #define PG8_LDA(dst, b, h) do { _Pragma("unroll") for (int m = 0; m < 4; ++m) _Pragma("unroll") for (int k = 0; k < 2; ++k) dst[m][k] = *(const LAS bf16x8*)(lds + PG8_SA(b, h) + aoff + m * 2048 + k * 1024); } while (0)
; #define PG8_MMA(ai, bj, At, Bt) do { __builtin_amdgcn_s_setprio(1); _Pragma("unroll") for (int m = 0; m < 4; ++m) _Pragma("unroll") for (int n = 0; n < 2; ++n) _Pragma("unroll") for (int k = 0; k < 2; ++k) \
;         acc[ai][bj][m][n] = __builtin_amdgcn_mfma_f32_16x16x32_bf16(Bt[n][k], At[m][k], acc[ai][bj][m][n], 0, 0, 0); __builtin_amdgcn_s_setprio(0); } while (0)
; #define PG8_WAIT_V(n) asm volatile("s_waitcnt vmcnt(" #n ")" ::: "memory")
; #define PG8_WAIT_L(n) asm volatile("s_waitcnt lgkmcnt(" #n ")" ::: "memory")
; #define PG8_BAR __builtin_amdgcn_s_barrier()
; #define PG8_SCHED __builtin_amdgcn_sched_barrier(0)
; template <class Epi, bool ALIGN_EPI>
; __device__ __forceinline__ void gemm_phase(LAS unsigned char* lds, const Gemm g, const StaticOrder& S, const Epi& E) {
;     ...
;             PG8_LDA(At, 1, 1); PG8_STAGE(PG8_SB(1, 0), b3, voffB); PG8_STAGE(PG8_SB(1, 1), b3 + hB, voffB); PG8_STAGE(PG8_SA(1, 0), a3, voffA);
;             PG8_WAIT_V(8); PG8_WAIT_L(0); PG8_BAR; PG8_MMA(1, 0, At, B0); PG8_MMA(1, 1, At, B1); PG8_BAR; PG8_SCHED;
;         }
	s_add_i32 s42, s58, s33
	v_lshl_add_u64 v[218:219], v[218:219], 0, s[18:19]
	s_mov_b32 m0, s42
	ds_read_b128 v[184:187], v177 offset:49152
	ds_read_b128 v[188:191], v177 offset:50176
	ds_read_b128 v[194:197], v177 offset:51200
	ds_read_b128 v[198:201], v177 offset:52224
	ds_read_b128 v[202:205], v177 offset:53248
	ds_read_b128 v[206:209], v177 offset:54272
	ds_read_b128 v[210:213], v177 offset:55296
	ds_read_b128 v[214:217], v177 offset:56320
	global_load_lds_dwordx4 v[218:219], off
	s_add_i32 m0, s42, 0x2000
	s_add_u32 s40, s40, 0x80080
	v_lshl_add_u64 v[218:219], v[220:221], 0, s[18:19]
	s_addc_u32 s41, s41, 0
	s_add_i32 s42, s59, s33
	global_load_lds_dwordx4 v[218:219], off
	v_lshl_add_u64 v[218:219], s[40:41], 0, v[146:147]
	s_mov_b32 m0, s42
	s_nop 0
	global_load_lds_dwordx4 v[218:219], off
	v_lshl_add_u64 v[218:219], s[40:41], 0, v[150:151]
	s_add_i32 m0, s42, 0x2000
	s_nop 0
	global_load_lds_dwordx4 v[218:219], off
	v_lshl_add_u64 v[218:219], v[222:223], 0, s[18:19]
	s_mov_b32 m0, s48
	s_nop 0
	global_load_lds_dwordx4 v[218:219], off
	v_lshl_add_u64 v[218:219], v[224:225], 0, s[18:19]
	s_mov_b32 m0, s49
	s_nop 0
	global_load_lds_dwordx4 v[218:219], off
	s_waitcnt vmcnt(8)
	s_waitcnt lgkmcnt(0)
	s_barrier
	s_setprio 1
	s_waitcnt lgkmcnt(0)
	v_mfma_f32_16x16x32_bf16 v[60:63], v[128:131], v[184:187], v[60:63]
	v_mfma_f32_16x16x32_bf16 v[60:63], v[132:135], v[188:191], v[60:63]
	v_mfma_f32_16x16x32_bf16 v[56:59], v[136:139], v[184:187], v[56:59]
	v_mfma_f32_16x16x32_bf16 v[56:59], v[140:143], v[188:191], v[56:59]
	v_mfma_f32_16x16x32_bf16 v[44:47], v[128:131], v[194:197], v[44:47]
	v_mfma_f32_16x16x32_bf16 v[44:47], v[132:135], v[198:201], v[44:47]
	v_mfma_f32_16x16x32_bf16 v[40:43], v[136:139], v[194:197], v[40:43]
	v_mfma_f32_16x16x32_bf16 v[40:43], v[140:143], v[198:201], v[40:43]
	v_mfma_f32_16x16x32_bf16 v[28:31], v[128:131], v[202:205], v[28:31]
	v_mfma_f32_16x16x32_bf16 v[28:31], v[132:135], v[206:209], v[28:31]
	v_mfma_f32_16x16x32_bf16 v[24:27], v[136:139], v[202:205], v[24:27]
	v_mfma_f32_16x16x32_bf16 v[24:27], v[140:143], v[206:209], v[24:27]
	v_mfma_f32_16x16x32_bf16 v[12:15], v[128:131], v[210:213], v[12:15]
	v_mfma_f32_16x16x32_bf16 v[12:15], v[132:135], v[214:217], v[12:15]
	v_mfma_f32_16x16x32_bf16 v[8:11], v[136:139], v[210:213], v[8:11]
	v_mfma_f32_16x16x32_bf16 v[8:11], v[140:143], v[214:217], v[8:11]
	v_mfma_f32_16x16x32_bf16 v[52:55], v[160:163], v[184:187], v[52:55]
	v_mfma_f32_16x16x32_bf16 v[52:55], v[164:167], v[188:191], v[52:55]
	v_mfma_f32_16x16x32_bf16 v[48:51], v[168:171], v[184:187], v[48:51]
	v_mfma_f32_16x16x32_bf16 v[48:51], v[180:183], v[188:191], v[48:51]
	v_mfma_f32_16x16x32_bf16 v[36:39], v[160:163], v[194:197], v[36:39]
	v_mfma_f32_16x16x32_bf16 v[36:39], v[164:167], v[198:201], v[36:39]
	v_mfma_f32_16x16x32_bf16 v[32:35], v[168:171], v[194:197], v[32:35]
	v_mfma_f32_16x16x32_bf16 v[32:35], v[180:183], v[198:201], v[32:35]
	v_mfma_f32_16x16x32_bf16 v[20:23], v[160:163], v[202:205], v[20:23]
	v_mfma_f32_16x16x32_bf16 v[20:23], v[164:167], v[206:209], v[20:23]
	v_mfma_f32_16x16x32_bf16 v[16:19], v[168:171], v[202:205], v[16:19]
	v_mfma_f32_16x16x32_bf16 v[16:19], v[180:183], v[206:209], v[16:19]
	v_mfma_f32_16x16x32_bf16 v[4:7], v[160:163], v[210:213], v[4:7]
	v_mfma_f32_16x16x32_bf16 v[4:7], v[164:167], v[214:217], v[4:7]
	v_mfma_f32_16x16x32_bf16 v[0:3], v[168:171], v[210:213], v[0:3]
	v_mfma_f32_16x16x32_bf16 v[0:3], v[180:183], v[214:217], v[0:3]
	s_setprio 0
	s_barrier
	s_add_i32 s57, s57, 2
	s_add_u32 s36, s36, 0x100
	s_addc_u32 s37, s37, 0
	s_add_u32 s55, s55, 0x100
	s_addc_u32 s56, s56, 0
	s_cmp_gt_u32 s57, 29
	s_cbranch_scc0 .LBB0_1585
	s_and_b64 vcc, exec, s[20:21]
	s_cbranch_vccz .LBB0_1588
	s_barrier

; #define PG8_STAGE(bufoff, gbase, voff) do { _Pragma("unroll") for (int _i = 0; _i < 2; ++_i) \
;         __builtin_amdgcn_global_load_lds((const unsigned*)((const char*)(gbase) + (voff)[_i]), (LAS unsigned*)(lds + (bufoff) + ldsw + _i * 8192), 16, 0, 0); } while (0)
; #define PG8_LDA(dst, b, h) do { _Pragma("unroll") for (int m = 0; m < 4; ++m) _Pragma("unroll") for (int k = 0; k < 2; ++k) dst[m][k] = *(const LAS bf16x8*)(lds + PG8_SA(b, h) + aoff + m * 2048 + k * 1024); } while (0)
; #define PG8_LDB(dst, b, h) do { _Pragma("unroll") for (int n = 0; n < 2; ++n) _Pragma("unroll") for (int k = 0; k < 2; ++k) dst[n][k] = *(const LAS bf16x8*)(lds + PG8_SB(b, h) + boff + n * 2048 + k * 1024); } while (0)
; #define PG8_MMA(ai, bj, At, Bt) do { __builtin_amdgcn_s_setprio(1); _Pragma("unroll") for (int m = 0; m < 4; ++m) _Pragma("unroll") for (int n = 0; n < 2; ++n) _Pragma("unroll") for (int k = 0; k < 2; ++k) \
;         acc[ai][bj][m][n] = __builtin_amdgcn_mfma_f32_16x16x32_bf16(Bt[n][k], At[m][k], acc[ai][bj][m][n], 0, 0, 0); __builtin_amdgcn_s_setprio(0); } while (0)
; #define PG8_WAIT_V(n) asm volatile("s_waitcnt vmcnt(" #n ")" ::: "memory")
; #define PG8_WAIT_L(n) asm volatile("s_waitcnt lgkmcnt(" #n ")" ::: "memory")
; #define PG8_BAR __builtin_amdgcn_s_barrier()
; #define PG8_SCHED __builtin_amdgcn_sched_barrier(0)
; template <class Epi, bool ALIGN_EPI>
; __device__ __forceinline__ void gemm_phase(LAS unsigned char* lds, const Gemm g, const StaticOrder& S, const Epi& E) {
;     ...
;             const bool last = (t == nt - 2);
;             const char* a1 = cA + (size_t)(t + 1) * kstep;
;             const char* a2 = last ? nA : cA + (size_t)(t + 2) * kstep; const char* b2 = last ? nB : cB + (size_t)(t + 2) * kstep;
;             const char* a3 = a2 + kstep; const char* b3 = b2 + kstep;
;             PG8_LDB(B0, 0, 0); PG8_LDB(B1, 0, 1); PG8_SCHED; PG8_LDA(At, 0, 0); PG8_STAGE(PG8_SA(1, 1), a1 + hA, voffA);
;             PG8_WAIT_V(8); PG8_WAIT_L(0); PG8_BAR; PG8_MMA(0, 0, At, B0); PG8_MMA(0, 1, At, B1); PG8_BAR; PG8_SCHED;
;             PG8_LDA(At, 0, 1); PG8_STAGE(PG8_SB(0, 0), b2, voffB); PG8_STAGE(PG8_SB(0, 1), b2 + hB, voffB); PG8_STAGE(PG8_SA(0, 0), a2, voffA);
;             PG8_WAIT_V(8); PG8_WAIT_L(0); PG8_BAR; PG8_MMA(1, 0, At, B0); PG8_MMA(1, 1, At, B1); PG8_BAR; PG8_SCHED;
.LBB0_1755:
	ds_read_b128 v[128:131], v183
	ds_read_b128 v[132:135], v183 offset:1024
	ds_read_b128 v[152:155], v183 offset:2048
	ds_read_b128 v[156:159], v183 offset:3072
	ds_read_b128 v[160:163], v184
	ds_read_b128 v[164:167], v184 offset:1024
	ds_read_b128 v[168:171], v184 offset:2048
	ds_read_b128 v[172:175], v184 offset:3072
	s_add_u32 s30, s28, 0xffe00080
	s_addc_u32 s31, s29, -1
	s_cmpk_eq_i32 s51, 0x7c
	s_cselect_b32 s35, s5, s31
	s_cselect_b32 s34, s21, s30
	s_cselect_b32 s31, s19, s50
	s_cselect_b32 s30, s48, s49
	v_lshl_add_u64 v[214:215], s[28:29], 0, v[144:145]
	s_add_i32 m0, s27, 0xc000
	ds_read_b128 v[176:179], v185
	ds_read_b128 v[186:189], v185 offset:1024
	ds_read_b128 v[190:193], v185 offset:2048
	ds_read_b128 v[194:197], v185 offset:3072
	ds_read_b128 v[198:201], v185 offset:4096
	ds_read_b128 v[202:205], v185 offset:5120
	ds_read_b128 v[206:209], v185 offset:6144
	ds_read_b128 v[210:213], v185 offset:7168
	global_load_lds_dwordx4 v[214:215], off
	v_lshl_add_u64 v[214:215], s[28:29], 0, v[146:147]
	s_add_i32 m0, s27, 0xe000
	s_nop 0
	global_load_lds_dwordx4 v[214:215], off
	s_waitcnt vmcnt(8)
	s_waitcnt lgkmcnt(0)
	s_barrier
	s_setprio 1
	s_waitcnt lgkmcnt(0)
	v_mfma_f32_16x16x32_bf16 v[120:123], v[128:131], v[176:179], v[120:123]
	v_mfma_f32_16x16x32_bf16 v[120:123], v[132:135], v[186:189], v[120:123]
	v_mfma_f32_16x16x32_bf16 v[124:127], v[152:155], v[176:179], v[124:127]
	v_mfma_f32_16x16x32_bf16 v[124:127], v[156:159], v[186:189], v[124:127]
	v_mfma_f32_16x16x32_bf16 v[104:107], v[128:131], v[190:193], v[104:107]
	v_mfma_f32_16x16x32_bf16 v[104:107], v[132:135], v[194:197], v[104:107]
	v_mfma_f32_16x16x32_bf16 v[108:111], v[152:155], v[190:193], v[108:111]
	v_mfma_f32_16x16x32_bf16 v[108:111], v[156:159], v[194:197], v[108:111]
	v_mfma_f32_16x16x32_bf16 v[88:91], v[128:131], v[198:201], v[88:91]
	v_mfma_f32_16x16x32_bf16 v[88:91], v[132:135], v[202:205], v[88:91]
	v_mfma_f32_16x16x32_bf16 v[92:95], v[152:155], v[198:201], v[92:95]
	v_mfma_f32_16x16x32_bf16 v[92:95], v[156:159], v[202:205], v[92:95]
	v_mfma_f32_16x16x32_bf16 v[72:75], v[128:131], v[206:209], v[72:75]
	v_mfma_f32_16x16x32_bf16 v[72:75], v[132:135], v[210:213], v[72:75]
	v_mfma_f32_16x16x32_bf16 v[76:79], v[152:155], v[206:209], v[76:79]
	v_mfma_f32_16x16x32_bf16 v[76:79], v[156:159], v[210:213], v[76:79]
	v_mfma_f32_16x16x32_bf16 v[112:115], v[160:163], v[176:179], v[112:115]
	v_mfma_f32_16x16x32_bf16 v[112:115], v[164:167], v[186:189], v[112:115]
	v_mfma_f32_16x16x32_bf16 v[116:119], v[168:171], v[176:179], v[116:119]
	v_mfma_f32_16x16x32_bf16 v[116:119], v[172:175], v[186:189], v[116:119]
	v_mfma_f32_16x16x32_bf16 v[96:99], v[160:163], v[190:193], v[96:99]
	v_mfma_f32_16x16x32_bf16 v[96:99], v[164:167], v[194:197], v[96:99]
	v_mfma_f32_16x16x32_bf16 v[100:103], v[168:171], v[190:193], v[100:103]
	v_mfma_f32_16x16x32_bf16 v[100:103], v[172:175], v[194:197], v[100:103]
	v_mfma_f32_16x16x32_bf16 v[80:83], v[160:163], v[198:201], v[80:83]
	v_mfma_f32_16x16x32_bf16 v[80:83], v[164:167], v[202:205], v[80:83]
	v_mfma_f32_16x16x32_bf16 v[84:87], v[168:171], v[198:201], v[84:87]
	v_mfma_f32_16x16x32_bf16 v[84:87], v[172:175], v[202:205], v[84:87]
	v_mfma_f32_16x16x32_bf16 v[64:67], v[160:163], v[206:209], v[64:67]
	v_mfma_f32_16x16x32_bf16 v[64:67], v[164:167], v[210:213], v[64:67]
	v_mfma_f32_16x16x32_bf16 v[68:71], v[168:171], v[206:209], v[68:71]
	v_mfma_f32_16x16x32_bf16 v[68:71], v[172:175], v[210:213], v[68:71]
	s_setprio 0
	s_barrier
	s_add_i32 s52, s46, s37
	v_lshl_add_u64 v[214:215], s[30:31], 0, v[138:139]
	s_mov_b32 m0, s52
	ds_read_b128 v[176:179], v185 offset:16384
	ds_read_b128 v[186:189], v185 offset:17408
	ds_read_b128 v[190:193], v185 offset:18432
	ds_read_b128 v[194:197], v185 offset:19456
	ds_read_b128 v[198:201], v185 offset:20480
	ds_read_b128 v[202:205], v185 offset:21504
	ds_read_b128 v[206:209], v185 offset:22528
	ds_read_b128 v[210:213], v185 offset:23552
	global_load_lds_dwordx4 v[214:215], off
	s_add_i32 m0, s52, 0x2000
	s_add_u32 s52, s30, 0x200000
	v_lshl_add_u64 v[216:217], s[30:31], 0, v[142:143]
	s_addc_u32 s53, s31, 0
	s_add_i32 s54, s47, s37
	global_load_lds_dwordx4 v[216:217], off
	v_lshl_add_u64 v[218:219], s[52:53], 0, v[138:139]
	s_mov_b32 m0, s54
	v_lshl_add_u64 v[220:221], s[34:35], 0, v[140:141]
	global_load_lds_dwordx4 v[218:219], off
	v_lshl_add_u64 v[218:219], s[52:53], 0, v[142:143]
	s_add_i32 m0, s54, 0x2000
	s_nop 0
	global_load_lds_dwordx4 v[218:219], off
	v_lshl_add_u64 v[218:219], s[34:35], 0, v[136:137]
	s_mov_b32 m0, s27
	s_nop 0
	global_load_lds_dwordx4 v[218:219], off
	s_mov_b32 m0, s38
	s_nop 0
	global_load_lds_dwordx4 v[220:221], off
	s_waitcnt vmcnt(8)
	s_waitcnt lgkmcnt(0)
	s_barrier
; #define PG8_STAGE(bufoff, gbase, voff) do { _Pragma("unroll") for (int _i = 0; _i < 2; ++_i) \
;         __builtin_amdgcn_global_load_lds((const unsigned*)((const char*)(gbase) + (voff)[_i]), (LAS unsigned*)(lds + (bufoff) + ldsw + _i * 8192), 16, 0, 0); } while (0)
; #define PG8_LDA(dst, b, h) do { _Pragma("unroll") for (int m = 0; m < 4; ++m) _Pragma("unroll") for (int k = 0; k < 2; ++k) dst[m][k] = *(const LAS bf16x8*)(lds + PG8_SA(b, h) + aoff + m * 2048 + k * 1024); } while (0)
; #define PG8_LDB(dst, b, h) do { _Pragma("unroll") for (int n = 0; n < 2; ++n) _Pragma("unroll") for (int k = 0; k < 2; ++k) dst[n][k] = *(const LAS bf16x8*)(lds + PG8_SB(b, h) + boff + n * 2048 + k * 1024); } while (0)
; #define PG8_MMA(ai, bj, At, Bt) do { __builtin_amdgcn_s_setprio(1); _Pragma("unroll") for (int m = 0; m < 4; ++m) _Pragma("unroll") for (int n = 0; n < 2; ++n) _Pragma("unroll") for (int k = 0; k < 2; ++k) \
;         acc[ai][bj][m][n] = __builtin_amdgcn_mfma_f32_16x16x32_bf16(Bt[n][k], At[m][k], acc[ai][bj][m][n], 0, 0, 0); __builtin_amdgcn_s_setprio(0); } while (0)
; #define PG8_WAIT_V(n) asm volatile("s_waitcnt vmcnt(" #n ")" ::: "memory")
; #define PG8_WAIT_L(n) asm volatile("s_waitcnt lgkmcnt(" #n ")" ::: "memory")
; #define PG8_BAR __builtin_amdgcn_s_barrier()
; #define PG8_SCHED __builtin_amdgcn_sched_barrier(0)
; template <class Epi, bool ALIGN_EPI>
; __device__ __forceinline__ void gemm_phase(LAS unsigned char* lds, const Gemm g, const StaticOrder& S, const Epi& E) {
;     ...
;             PG8_WAIT_V(8); PG8_WAIT_L(0); PG8_BAR; PG8_MMA(1, 0, At, B0); PG8_MMA(1, 1, At, B1); PG8_BAR; PG8_SCHED;
;             PG8_LDB(B0, 1, 0); PG8_LDB(B1, 1, 1); PG8_SCHED; PG8_LDA(At, 1, 0); PG8_STAGE(PG8_SA(0, 1), a2 + hA, voffA);
;             PG8_WAIT_V(8); PG8_WAIT_L(0); PG8_BAR; PG8_MMA(0, 0, At, B0); PG8_MMA(0, 1, At, B1); PG8_BAR; PG8_SCHED;
	s_setprio 1
	s_waitcnt lgkmcnt(0)
	v_mfma_f32_16x16x32_bf16 v[56:59], v[128:131], v[176:179], v[56:59]
	v_mfma_f32_16x16x32_bf16 v[56:59], v[132:135], v[186:189], v[56:59]
	v_mfma_f32_16x16x32_bf16 v[60:63], v[152:155], v[176:179], v[60:63]
	v_mfma_f32_16x16x32_bf16 v[60:63], v[156:159], v[186:189], v[60:63]
	v_mfma_f32_16x16x32_bf16 v[40:43], v[128:131], v[190:193], v[40:43]
	v_mfma_f32_16x16x32_bf16 v[40:43], v[132:135], v[194:197], v[40:43]
	v_mfma_f32_16x16x32_bf16 v[44:47], v[152:155], v[190:193], v[44:47]
	v_mfma_f32_16x16x32_bf16 v[44:47], v[156:159], v[194:197], v[44:47]
	v_mfma_f32_16x16x32_bf16 v[24:27], v[128:131], v[198:201], v[24:27]
	v_mfma_f32_16x16x32_bf16 v[24:27], v[132:135], v[202:205], v[24:27]
	v_mfma_f32_16x16x32_bf16 v[28:31], v[152:155], v[198:201], v[28:31]
	v_mfma_f32_16x16x32_bf16 v[28:31], v[156:159], v[202:205], v[28:31]
	v_mfma_f32_16x16x32_bf16 v[8:11], v[128:131], v[206:209], v[8:11]
	v_mfma_f32_16x16x32_bf16 v[8:11], v[132:135], v[210:213], v[8:11]
	v_mfma_f32_16x16x32_bf16 v[12:15], v[152:155], v[206:209], v[12:15]
	v_mfma_f32_16x16x32_bf16 v[12:15], v[156:159], v[210:213], v[12:15]
	v_mfma_f32_16x16x32_bf16 v[48:51], v[160:163], v[176:179], v[48:51]
	v_mfma_f32_16x16x32_bf16 v[48:51], v[164:167], v[186:189], v[48:51]
	v_mfma_f32_16x16x32_bf16 v[52:55], v[168:171], v[176:179], v[52:55]
	v_mfma_f32_16x16x32_bf16 v[52:55], v[172:175], v[186:189], v[52:55]
	v_mfma_f32_16x16x32_bf16 v[32:35], v[160:163], v[190:193], v[32:35]
	v_mfma_f32_16x16x32_bf16 v[32:35], v[164:167], v[194:197], v[32:35]
	v_mfma_f32_16x16x32_bf16 v[36:39], v[168:171], v[190:193], v[36:39]
	v_mfma_f32_16x16x32_bf16 v[36:39], v[172:175], v[194:197], v[36:39]
	v_mfma_f32_16x16x32_bf16 v[16:19], v[160:163], v[198:201], v[16:19]
	v_mfma_f32_16x16x32_bf16 v[16:19], v[164:167], v[202:205], v[16:19]
	v_mfma_f32_16x16x32_bf16 v[20:23], v[168:171], v[198:201], v[20:23]
	v_mfma_f32_16x16x32_bf16 v[20:23], v[172:175], v[202:205], v[20:23]
	v_mfma_f32_16x16x32_bf16 v[4:7], v[160:163], v[206:209], v[4:7]
	v_mfma_f32_16x16x32_bf16 v[4:7], v[164:167], v[210:213], v[4:7]
	v_mfma_f32_16x16x32_bf16 v[0:3], v[168:171], v[206:209], v[0:3]
	v_mfma_f32_16x16x32_bf16 v[0:3], v[172:175], v[210:213], v[0:3]
	s_setprio 0
	s_barrier
	s_add_i32 s52, 0, 0x18000
	s_add_i32 s53, 0, 0x1c000
	v_add_u32_e32 v156, s52, v181
	v_add_u32_e32 v172, s53, v181
	ds_read_b128 v[128:131], v156
	ds_read_b128 v[132:135], v156 offset:1024
	ds_read_b128 v[152:155], v156 offset:2048
	ds_read_b128 v[156:159], v156 offset:3072
	ds_read_b128 v[160:163], v172
	ds_read_b128 v[164:167], v172 offset:1024
	ds_read_b128 v[168:171], v172 offset:2048
	ds_read_b128 v[172:175], v172 offset:3072
	s_add_u32 s34, s34, 0x200000
	s_addc_u32 s35, s35, 0
	s_mov_b32 m0, s39
	v_lshl_add_u64 v[222:223], s[34:35], 0, v[136:137]
	ds_read_b128 v[176:179], v185 offset:32768
	ds_read_b128 v[186:189], v185 offset:33792
	ds_read_b128 v[190:193], v185 offset:34816
	ds_read_b128 v[194:197], v185 offset:35840
	ds_read_b128 v[198:201], v185 offset:36864
	ds_read_b128 v[202:205], v185 offset:37888
	ds_read_b128 v[206:209], v185 offset:38912
	ds_read_b128 v[210:213], v185 offset:39936
	global_load_lds_dwordx4 v[222:223], off
	v_lshl_add_u64 v[222:223], s[34:35], 0, v[140:141]
	s_mov_b32 m0, s40
	s_nop 0
	global_load_lds_dwordx4 v[222:223], off
	s_waitcnt vmcnt(8)
	s_waitcnt lgkmcnt(0)
	s_barrier
	s_setprio 1
	s_waitcnt lgkmcnt(0)
	v_mfma_f32_16x16x32_bf16 v[120:123], v[128:131], v[176:179], v[120:123]
	v_mfma_f32_16x16x32_bf16 v[120:123], v[132:135], v[186:189], v[120:123]
	v_mfma_f32_16x16x32_bf16 v[124:127], v[152:155], v[176:179], v[124:127]
	v_mfma_f32_16x16x32_bf16 v[124:127], v[156:159], v[186:189], v[124:127]
	v_mfma_f32_16x16x32_bf16 v[104:107], v[128:131], v[190:193], v[104:107]
	v_mfma_f32_16x16x32_bf16 v[104:107], v[132:135], v[194:197], v[104:107]
	v_mfma_f32_16x16x32_bf16 v[108:111], v[152:155], v[190:193], v[108:111]
	v_mfma_f32_16x16x32_bf16 v[108:111], v[156:159], v[194:197], v[108:111]
	v_mfma_f32_16x16x32_bf16 v[88:91], v[128:131], v[198:201], v[88:91]
	v_mfma_f32_16x16x32_bf16 v[88:91], v[132:135], v[202:205], v[88:91]
	v_mfma_f32_16x16x32_bf16 v[92:95], v[152:155], v[198:201], v[92:95]
	v_mfma_f32_16x16x32_bf16 v[92:95], v[156:159], v[202:205], v[92:95]
	v_mfma_f32_16x16x32_bf16 v[72:75], v[128:131], v[206:209], v[72:75]
	v_mfma_f32_16x16x32_bf16 v[72:75], v[132:135], v[210:213], v[72:75]
	v_mfma_f32_16x16x32_bf16 v[76:79], v[152:155], v[206:209], v[76:79]
	v_mfma_f32_16x16x32_bf16 v[76:79], v[156:159], v[210:213], v[76:79]
	v_mfma_f32_16x16x32_bf16 v[112:115], v[160:163], v[176:179], v[112:115]
	v_mfma_f32_16x16x32_bf16 v[112:115], v[164:167], v[186:189], v[112:115]
	v_mfma_f32_16x16x32_bf16 v[116:119], v[168:171], v[176:179], v[116:119]
	v_mfma_f32_16x16x32_bf16 v[116:119], v[172:175], v[186:189], v[116:119]
	v_mfma_f32_16x16x32_bf16 v[96:99], v[160:163], v[190:193], v[96:99]
	v_mfma_f32_16x16x32_bf16 v[96:99], v[164:167], v[194:197], v[96:99]
	v_mfma_f32_16x16x32_bf16 v[100:103], v[168:171], v[190:193], v[100:103]
	v_mfma_f32_16x16x32_bf16 v[100:103], v[172:175], v[194:197], v[100:103]
	v_mfma_f32_16x16x32_bf16 v[80:83], v[160:163], v[198:201], v[80:83]
	v_mfma_f32_16x16x32_bf16 v[80:83], v[164:167], v[202:205], v[80:83]
	v_mfma_f32_16x16x32_bf16 v[84:87], v[168:171], v[198:201], v[84:87]
	v_mfma_f32_16x16x32_bf16 v[84:87], v[172:175], v[202:205], v[84:87]
	v_mfma_f32_16x16x32_bf16 v[64:67], v[160:163], v[206:209], v[64:67]
	v_mfma_f32_16x16x32_bf16 v[64:67], v[164:167], v[210:213], v[64:67]
	v_mfma_f32_16x16x32_bf16 v[68:71], v[168:171], v[206:209], v[68:71]
	v_mfma_f32_16x16x32_bf16 v[68:71], v[172:175], v[210:213], v[68:71]
	s_setprio 0
	s_barrier
; #define PG8_STAGE(bufoff, gbase, voff) do { _Pragma("unroll") for (int _i = 0; _i < 2; ++_i) \
;         __builtin_amdgcn_global_load_lds((const unsigned*)((const char*)(gbase) + (voff)[_i]), (LAS unsigned*)(lds + (bufoff) + ldsw + _i * 8192), 16, 0, 0); } while (0)
; #define PG8_LDA(dst, b, h) do { _Pragma("unroll") for (int m = 0; m < 4; ++m) _Pragma("unroll") for (int k = 0; k < 2; ++k) dst[m][k] = *(const LAS bf16x8*)(lds + PG8_SA(b, h) + aoff + m * 2048 + k * 1024); } while (0)
; #define PG8_MMA(ai, bj, At, Bt) do { __builtin_amdgcn_s_setprio(1); _Pragma("unroll") for (int m = 0; m < 4; ++m) _Pragma("unroll") for (int n = 0; n < 2; ++n) _Pragma("unroll") for (int k = 0; k < 2; ++k) \
;         acc[ai][bj][m][n] = __builtin_amdgcn_mfma_f32_16x16x32_bf16(Bt[n][k], At[m][k], acc[ai][bj][m][n], 0, 0, 0); __builtin_amdgcn_s_setprio(0); } while (0)
; #define PG8_WAIT_V(n) asm volatile("s_waitcnt vmcnt(" #n ")" ::: "memory")
; #define PG8_WAIT_L(n) asm volatile("s_waitcnt lgkmcnt(" #n ")" ::: "memory")
; #define PG8_BAR __builtin_amdgcn_s_barrier()
; #define PG8_SCHED __builtin_amdgcn_sched_barrier(0)
; template <class Epi, bool ALIGN_EPI>
; __device__ __forceinline__ void gemm_phase(LAS unsigned char* lds, const Gemm g, const StaticOrder& S, const Epi& E) {
;     ...
;             PG8_LDA(At, 1, 1); PG8_STAGE(PG8_SB(1, 0), b3, voffB); PG8_STAGE(PG8_SB(1, 1), b3 + hB, voffB); PG8_STAGE(PG8_SA(1, 0), a3, voffA);
;             PG8_WAIT_V(8); PG8_WAIT_L(0); PG8_BAR; PG8_MMA(1, 0, At, B0); PG8_MMA(1, 1, At, B1); PG8_BAR; PG8_SCHED;
;         }
;         if constexpr (ALIGN_EPI) { if (wr == 0) PG8_BAR; }
	s_add_i32 s34, s52, s37
	v_lshl_add_u64 v[214:215], v[214:215], 0, s[12:13]
	s_mov_b32 m0, s34
	ds_read_b128 v[176:179], v185 offset:49152
	ds_read_b128 v[186:189], v185 offset:50176
	ds_read_b128 v[190:193], v185 offset:51200
	ds_read_b128 v[194:197], v185 offset:52224
	ds_read_b128 v[198:201], v185 offset:53248
	ds_read_b128 v[202:205], v185 offset:54272
	ds_read_b128 v[206:209], v185 offset:55296
	ds_read_b128 v[210:213], v185 offset:56320
	global_load_lds_dwordx4 v[214:215], off
	s_add_i32 m0, s34, 0x2000
	s_add_u32 s30, s30, 0x200080
	v_lshl_add_u64 v[214:215], v[216:217], 0, s[12:13]
	s_addc_u32 s31, s31, 0
	s_add_i32 s34, s53, s37
	global_load_lds_dwordx4 v[214:215], off
	v_lshl_add_u64 v[214:215], s[30:31], 0, v[138:139]
	s_mov_b32 m0, s34
	s_nop 0
	global_load_lds_dwordx4 v[214:215], off
	v_lshl_add_u64 v[214:215], s[30:31], 0, v[142:143]
	s_add_i32 m0, s34, 0x2000
	s_nop 0
	global_load_lds_dwordx4 v[214:215], off
	v_lshl_add_u64 v[214:215], v[218:219], 0, s[12:13]
	s_mov_b32 m0, s44
	s_nop 0
	global_load_lds_dwordx4 v[214:215], off
	v_lshl_add_u64 v[214:215], v[220:221], 0, s[12:13]
	s_mov_b32 m0, s45
	s_nop 0
	global_load_lds_dwordx4 v[214:215], off
	s_waitcnt vmcnt(8)
	s_waitcnt lgkmcnt(0)
	s_barrier
	s_setprio 1
	s_waitcnt lgkmcnt(0)
	v_mfma_f32_16x16x32_bf16 v[56:59], v[128:131], v[176:179], v[56:59]
	v_mfma_f32_16x16x32_bf16 v[56:59], v[132:135], v[186:189], v[56:59]
	v_mfma_f32_16x16x32_bf16 v[60:63], v[152:155], v[176:179], v[60:63]
	v_mfma_f32_16x16x32_bf16 v[60:63], v[156:159], v[186:189], v[60:63]
	v_mfma_f32_16x16x32_bf16 v[40:43], v[128:131], v[190:193], v[40:43]
	v_mfma_f32_16x16x32_bf16 v[40:43], v[132:135], v[194:197], v[40:43]
	v_mfma_f32_16x16x32_bf16 v[44:47], v[152:155], v[190:193], v[44:47]
	v_mfma_f32_16x16x32_bf16 v[44:47], v[156:159], v[194:197], v[44:47]
	v_mfma_f32_16x16x32_bf16 v[24:27], v[128:131], v[198:201], v[24:27]
	v_mfma_f32_16x16x32_bf16 v[24:27], v[132:135], v[202:205], v[24:27]
	v_mfma_f32_16x16x32_bf16 v[28:31], v[152:155], v[198:201], v[28:31]
	v_mfma_f32_16x16x32_bf16 v[28:31], v[156:159], v[202:205], v[28:31]
	v_mfma_f32_16x16x32_bf16 v[8:11], v[128:131], v[206:209], v[8:11]
	v_mfma_f32_16x16x32_bf16 v[8:11], v[132:135], v[210:213], v[8:11]
	v_mfma_f32_16x16x32_bf16 v[12:15], v[152:155], v[206:209], v[12:15]
	v_mfma_f32_16x16x32_bf16 v[12:15], v[156:159], v[210:213], v[12:15]
	v_mfma_f32_16x16x32_bf16 v[48:51], v[160:163], v[176:179], v[48:51]
	v_mfma_f32_16x16x32_bf16 v[48:51], v[164:167], v[186:189], v[48:51]
	v_mfma_f32_16x16x32_bf16 v[52:55], v[168:171], v[176:179], v[52:55]
	v_mfma_f32_16x16x32_bf16 v[52:55], v[172:175], v[186:189], v[52:55]
	v_mfma_f32_16x16x32_bf16 v[32:35], v[160:163], v[190:193], v[32:35]
	v_mfma_f32_16x16x32_bf16 v[32:35], v[164:167], v[194:197], v[32:35]
	v_mfma_f32_16x16x32_bf16 v[36:39], v[168:171], v[190:193], v[36:39]
	v_mfma_f32_16x16x32_bf16 v[36:39], v[172:175], v[194:197], v[36:39]
	v_mfma_f32_16x16x32_bf16 v[16:19], v[160:163], v[198:201], v[16:19]
	v_mfma_f32_16x16x32_bf16 v[16:19], v[164:167], v[202:205], v[16:19]
	v_mfma_f32_16x16x32_bf16 v[20:23], v[168:171], v[198:201], v[20:23]
	v_mfma_f32_16x16x32_bf16 v[20:23], v[172:175], v[202:205], v[20:23]
	v_mfma_f32_16x16x32_bf16 v[4:7], v[160:163], v[206:209], v[4:7]
	v_mfma_f32_16x16x32_bf16 v[4:7], v[164:167], v[210:213], v[4:7]
	v_mfma_f32_16x16x32_bf16 v[0:3], v[168:171], v[206:209], v[0:3]
	v_mfma_f32_16x16x32_bf16 v[0:3], v[172:175], v[210:213], v[0:3]
	s_setprio 0
	s_barrier
	s_add_i32 s51, s51, 2
	s_add_u32 s28, s28, 0x100
	s_addc_u32 s29, s29, 0
	s_add_u32 s49, s49, 0x100
	s_addc_u32 s50, s50, 0
	s_cmpk_gt_u32 s51, 0x7d
	s_cbranch_scc0 .LBB0_1755
	s_and_b64 vcc, exec, s[14:15]
	s_cbranch_vccz .LBB0_1758
	s_barrier
